# prep_rwkv elementwise step: the item's 48 PRE loads (8 token iterations x current+previous row) issued in one burst instead of load/wait per iteration behind the previous iteration's stores
# baseline (speedup 1.0000x reference)
; __device__ __forceinline__ unsigned pack2(float a, float b) { return (unsigned)f2bf(a) | ((unsigned)f2bf(b) << 16); }
; __device__ __forceinline__ float sigmoidf_(float x) { return frcp_(1.f + __expf(-x)); }
; __device__ __forceinline__ float softplusf_(float x) { return fmaxf(x, 0.f) + __logf(1.f + __expf(-fabsf(x))); }
; __device__ __forceinline__ void prep_rwkv(const Params& p, int l, int item, char* smem) {
;     ...
;     u32x4 o;
;     o.x = pack2(u[0], u[1]); o.y = pack2(u[2], u[3]); o.z = pack2(u[4], u[5]); o.w = pack2(u[6], u[7]);
;     *(u32x4*)(sA + tok * 136 + c8) = o;
;   }
;   __syncthreads();
;   {
;     const int fr = lane & 15, fq = (lane >> 4) * 8;
;     bf16x8 atw[2], aad[2];
; #pragma unroll
;     for (int ks = 0; ks < 2; ++ks) {
;       atw[ks] = *(const bf16x8*)(sA + fr * 136 + ks * 32 + fq);
;       aad[ks] = *(const bf16x8*)(sA + fr * 136 + 64 + ks * 32 + fq);
;     }
;     const float* w0 = p.in[12] + (size_t)l * 512;
;     const float* a0 = p.in[14] + (size_t)l * 512;
; #pragma unroll
;     for (int jt = 0; jt < 8; ++jt) {
;       const int n = wave * 128 + jt * 16 + fr;
;       f32x4 cw = (f32x4){0.f, 0.f, 0.f, 0.f}, ca = (f32x4){0.f, 0.f, 0.f, 0.f};
; #pragma unroll
;       for (int ks = 0; ks < 2; ++ks) {
;         const bf16x8 bw = *(const bf16x8*)(W2T + (size_t)n * 64 + ks * 32 + fq);
;         const bf16x8 ba = *(const bf16x8*)(A2T + (size_t)n * 64 + ks * 32 + fq);
;         cw = __builtin_amdgcn_mfma_f32_16x16x32_bf16(atw[ks], bw, cw, 0, 0, 0);
;         ca = __builtin_amdgcn_mfma_f32_16x16x32_bf16(aad[ks], ba, ca, 0, 0, 0);
;       }
;       const float w0v = w0[n], a0v = a0[n];
; #pragma unroll
;       for (int r = 0; r < 4; ++r) {
;         const int tok = (lane >> 4) * 4 + r;
;         const float wl = w0v + cw[r];
;         const float wv = -softplusf_(-wl) - 0.5f;
;         sW[tok * 516 + n] = __expf(-__expf(wv));
;         sAs[tok * 516 + n] = sigmoidf_(a0v + ca[r]);
;       }
;     }
;   }
.LBB0_460:
	s_or_b64 exec, exec, s[16:17]
	v_bfe_u32 v9, v7, 16, 1
	v_bfe_u32 v10, v6, 16, 1
	v_bfe_u32 v11, v5, 16, 1
	v_bfe_u32 v14, v4, 16, 1
	v_add3_u32 v4, v4, v14, s37
	v_add3_u32 v5, v5, v11, s37
	v_add3_u32 v6, v6, v10, s37
	v_add3_u32 v7, v7, v9, s37
	v_bfe_u32 v9, v2, 16, 1
	v_bfe_u32 v10, v12, 16, 1
	v_bfe_u32 v11, v13, 16, 1
	v_bfe_u32 v14, v8, 16, 1
	v_add3_u32 v8, v8, v14, s37
	v_add3_u32 v11, v13, v11, s37
	v_add3_u32 v10, v12, v10, s37
	v_add3_u32 v2, v2, v9, s37
	v_lshrrev_b32_e32 v2, 16, v2
	v_lshrrev_b32_e32 v9, 16, v10
	v_lshrrev_b32_e32 v10, 16, v11
	v_lshrrev_b32_e32 v8, 16, v8
	s_mov_b32 s0, 0xffff0000
	v_and_or_b32 v7, v7, s0, v8
	v_and_or_b32 v6, v6, s0, v10
	v_and_or_b32 v5, v5, s0, v9
	v_and_or_b32 v4, v4, s0, v2
	s_movk_i32 s0, 0x110
	v_mul_lo_u32 v0, v0, s0
	v_bfe_u32 v44, v58, 4, 2
	v_lshl_add_u32 v0, v1, 1, v0
	v_and_b32_e32 v59, 15, v58
	v_lshlrev_b32_e32 v2, 4, v44
	ds_write_b128 v0, v[4:7]
	v_mad_u32_u24 v0, v59, s0, v2
	s_waitcnt lgkmcnt(0)
	s_barrier
	ds_read_b128 v[12:15], v0
	ds_read_b128 v[16:19], v0 offset:128
	ds_read_b128 v[4:7], v0 offset:64
	ds_read_b128 v[8:11], v0 offset:192
	v_lshlrev_b32_e32 v0, 1, v58
	s_movk_i32 s14, 0xff80
	v_readlane_b32 s0, v243, 40
	v_and_or_b32 v30, v0, s14, v59
	v_readlane_b32 s1, v243, 41
	v_ashrrev_i32_e32 v31, 31, v30
	v_lshlrev_b64 v[0:1], 7, v[30:31]
	v_lshl_add_u64 v[32:33], s[0:1], 0, v[2:3]
	v_readlane_b32 s0, v243, 42
	v_readlane_b32 s1, v243, 43
	v_lshl_add_u64 v[28:29], v[32:33], 0, v[0:1]
	v_ashrrev_i32_e32 v60, 7, v58
	v_lshl_add_u64 v[34:35], s[0:1], 0, v[2:3]
	v_lshl_add_u64 v[0:1], v[34:35], 0, v[0:1]
	global_load_dwordx4 v[20:23], v[28:29], off
	global_load_dwordx4 v[24:27], v[0:1], off
	global_load_dwordx4 v[36:39], v[28:29], off offset:64
	global_load_dwordx4 v[40:43], v[0:1], off offset:64
	v_readlane_b32 s0, v240, 9
	v_lshlrev_b64 v[0:1], 2, v[30:31]
	v_readlane_b32 s1, v240, 10
	v_add_u32_e32 v50, s23, v60
	s_mov_b32 s73, 0xffff0000
	v_lshl_add_u64 v[28:29], s[0:1], 0, v[0:1]
	v_readlane_b32 s0, v240, 11
	v_readlane_b32 s1, v240, 12
	s_waitcnt vmcnt(3) lgkmcnt(3)
	v_mfma_f32_16x16x32_bf16 v[20:23], v[12:15], v[20:23], 0
	v_lshl_add_u64 v[0:1], s[0:1], 0, v[0:1]
	v_readlane_b32 s0, v240, 13
	v_readlane_b32 s1, v240, 14
	s_waitcnt vmcnt(2) lgkmcnt(2)
	v_mfma_f32_16x16x32_bf16 v[24:27], v[16:19], v[24:27], 0
	s_waitcnt vmcnt(1) lgkmcnt(1)
	v_mfma_f32_16x16x32_bf16 v[36:39], v[4:7], v[36:39], v[20:23]
	s_waitcnt vmcnt(0) lgkmcnt(0)
	v_mfma_f32_16x16x32_bf16 v[22:25], v[8:11], v[40:43], v[24:27]
	s_nop 3
	global_load_dword v26, v[28:29], off
	global_load_dword v27, v[0:1], off
	s_waitcnt vmcnt(1)
	v_add_f32_e32 v2, v36, v26
	v_max_f32_e64 v20, -v2, 0
	v_mul_f32_e64 v2, |v2|, s36
	v_exp_f32_e32 v2, v2
	s_nop 0
	v_add_f32_e32 v2, 1.0, v2
	v_cmp_gt_f32_e32 vcc, s72, v2
	s_nop 1
	v_cndmask_b32_e64 v21, 0, 32, vcc
	v_ldexp_f32 v2, v2, v21
	v_log_f32_e32 v2, v2
	s_nop 0
	v_mul_f32_e32 v21, 0x3f317217, v2
	v_fma_f32 v21, v2, s33, -v21
	v_fmac_f32_e32 v21, 0x3377d1cf, v2
	v_fmac_f32_e32 v21, 0x3f317217, v2
	v_cmp_lt_f32_e64 s[40:41], |v2|, s34
	s_nop 1
	v_cndmask_b32_e64 v2, v2, v21, s[40:41]
	v_cndmask_b32_e32 v21, 0, v184, vcc
	v_sub_f32_e32 v2, v2, v21
	s_waitcnt vmcnt(0)
	v_add_f32_e32 v21, v22, v27
	v_add_f32_e32 v22, v37, v26
	v_max_f32_e64 v36, -v22, 0
	v_mul_f32_e64 v22, |v22|, s36
	v_exp_f32_e32 v22, v22
	v_add_f32_e32 v2, v20, v2
	v_sub_f32_e32 v2, -0.5, v2
	v_mul_f32_e32 v2, 0x3fb8aa3b, v2
	v_add_f32_e32 v22, 1.0, v22
	v_cmp_gt_f32_e32 vcc, s72, v22
	v_exp_f32_e32 v2, v2
	v_mul_f32_e32 v21, 0xbfb8aa3b, v21
	v_cndmask_b32_e64 v37, 0, 32, vcc
	v_ldexp_f32 v22, v22, v37
	v_log_f32_e32 v22, v22
	v_mul_f32_e32 v2, 0xbfb8aa3b, v2
	v_exp_f32_e32 v20, v2
	v_mul_u32_u24_e32 v2, 0x810, v44
	v_mul_f32_e32 v37, 0x3f317217, v22
	v_fma_f32 v37, v22, s33, -v37
	v_fmac_f32_e32 v37, 0x3377d1cf, v22
	v_fmac_f32_e32 v37, 0x3f317217, v22
	v_cmp_lt_f32_e64 s[40:41], |v22|, s34
	v_add_lshl_u32 v31, v2, v30, 2
	v_exp_f32_e32 v21, v21
	v_cndmask_b32_e64 v22, v22, v37, s[40:41]
	v_cndmask_b32_e32 v37, 0, v184, vcc
	v_sub_f32_e32 v22, v22, v37
	v_add_f32_e32 v22, v36, v22
	v_sub_f32_e32 v22, -0.5, v22
	v_mul_f32_e32 v22, 0x3fb8aa3b, v22
	v_exp_f32_e32 v22, v22
	v_add_f32_e32 v21, 1.0, v21
	v_rcp_f32_e32 v21, v21
	v_mul_f32_e32 v22, 0xbfb8aa3b, v22
	v_exp_f32_e32 v22, v22
	ds_write_b32 v31, v22 offset:6416
	v_add_f32_e32 v22, v23, v27
	v_mul_f32_e32 v22, 0xbfb8aa3b, v22
	v_exp_f32_e32 v22, v22
	s_nop 0
	v_add_f32_e32 v22, 1.0, v22
	v_rcp_f32_e32 v22, v22
	ds_write_b32 v31, v22 offset:39440
	v_add_f32_e32 v22, v38, v26
	v_max_f32_e64 v23, -v22, 0
	v_mul_f32_e64 v22, |v22|, s36
	v_exp_f32_e32 v22, v22
	s_nop 0
	v_add_f32_e32 v22, 1.0, v22
	v_cmp_gt_f32_e32 vcc, s72, v22
	s_nop 1
	v_cndmask_b32_e64 v36, 0, 32, vcc
	v_ldexp_f32 v22, v22, v36
	v_log_f32_e32 v22, v22
	s_nop 0
	v_mul_f32_e32 v36, 0x3f317217, v22
	v_fma_f32 v36, v22, s33, -v36
	v_fmac_f32_e32 v36, 0x3377d1cf, v22
	v_fmac_f32_e32 v36, 0x3f317217, v22
	v_cmp_lt_f32_e64 s[40:41], |v22|, s34
	s_nop 1
	v_cndmask_b32_e64 v22, v22, v36, s[40:41]
	v_cndmask_b32_e32 v36, 0, v184, vcc
	v_sub_f32_e32 v22, v22, v36
	v_add_f32_e32 v22, v23, v22
	v_sub_f32_e32 v22, -0.5, v22
	v_mul_f32_e32 v22, 0x3fb8aa3b, v22
	v_exp_f32_e32 v22, v22
	s_nop 0
	v_mul_f32_e32 v22, 0xbfb8aa3b, v22
	v_exp_f32_e32 v22, v22
	ds_write_b32 v31, v22 offset:8480
	v_add_f32_e32 v22, v24, v27
	v_mul_f32_e32 v22, 0xbfb8aa3b, v22
	v_exp_f32_e32 v22, v22
	s_nop 0
	v_add_f32_e32 v22, 1.0, v22
	v_rcp_f32_e32 v22, v22
	ds_write_b32 v31, v22 offset:41504
	v_add_f32_e32 v22, v39, v26
	v_max_f32_e64 v23, -v22, 0
	v_mul_f32_e64 v22, |v22|, s36
	v_exp_f32_e32 v22, v22
	v_or_b32_e32 v26, 16, v30
	v_add_f32_e32 v22, 1.0, v22
	v_cmp_gt_f32_e32 vcc, s72, v22
	s_nop 1
	v_cndmask_b32_e64 v24, 0, 32, vcc
	v_ldexp_f32 v22, v22, v24
	v_log_f32_e32 v22, v22
	s_nop 0
	v_mul_f32_e32 v24, 0x3f317217, v22
	v_fma_f32 v24, v22, s33, -v24
	v_fmac_f32_e32 v24, 0x3377d1cf, v22
	v_fmac_f32_e32 v24, 0x3f317217, v22
	v_cmp_lt_f32_e64 s[40:41], |v22|, s34
	s_nop 1
	v_cndmask_b32_e64 v22, v22, v24, s[40:41]
	v_cndmask_b32_e32 v24, 0, v184, vcc
	v_sub_f32_e32 v22, v22, v24
	v_add_f32_e32 v22, v23, v22
	v_sub_f32_e32 v22, -0.5, v22
	v_mul_f32_e32 v22, 0x3fb8aa3b, v22
	v_exp_f32_e32 v22, v22
	s_nop 0
	v_mul_f32_e32 v22, 0xbfb8aa3b, v22
	v_exp_f32_e32 v22, v22
	ds_write_b32 v31, v22 offset:10544
	v_add_f32_e32 v22, v25, v27
	v_mul_f32_e32 v22, 0xbfb8aa3b, v22
	v_exp_f32_e32 v22, v22
	v_ashrrev_i32_e32 v27, 31, v26
	v_add_f32_e32 v22, 1.0, v22
	v_rcp_f32_e32 v22, v22
	ds_write_b32 v31, v22 offset:43568
	v_lshlrev_b64 v[22:23], 7, v[26:27]
	v_lshl_add_u64 v[40:41], v[32:33], 0, v[22:23]
	v_lshl_add_u64 v[44:45], v[34:35], 0, v[22:23]
	global_load_dwordx4 v[22:25], v[40:41], off
	global_load_dwordx4 v[36:39], v[44:45], off
	s_nop 0
	global_load_dwordx4 v[40:43], v[40:41], off offset:64
	s_nop 0
	global_load_dwordx4 v[44:47], v[44:45], off offset:64
	s_waitcnt vmcnt(3)
; __device__ __forceinline__ float sigmoidf_(float x) { return frcp_(1.f + __expf(-x)); }
; __device__ __forceinline__ float softplusf_(float x) { return fmaxf(x, 0.f) + __logf(1.f + __expf(-fabsf(x))); }
; __device__ __forceinline__ void prep_rwkv(const Params& p, int l, int item, char* smem) {
;     ...
; #pragma unroll
;     for (int jt = 0; jt < 8; ++jt) {
;       const int n = wave * 128 + jt * 16 + fr;
;       f32x4 cw = (f32x4){0.f, 0.f, 0.f, 0.f}, ca = (f32x4){0.f, 0.f, 0.f, 0.f};
; #pragma unroll
;       for (int ks = 0; ks < 2; ++ks) {
;         const bf16x8 bw = *(const bf16x8*)(W2T + (size_t)n * 64 + ks * 32 + fq);
;         const bf16x8 ba = *(const bf16x8*)(A2T + (size_t)n * 64 + ks * 32 + fq);
;         cw = __builtin_amdgcn_mfma_f32_16x16x32_bf16(atw[ks], bw, cw, 0, 0, 0);
;         ca = __builtin_amdgcn_mfma_f32_16x16x32_bf16(aad[ks], ba, ca, 0, 0, 0);
;       }
;       const float w0v = w0[n], a0v = a0[n];
; #pragma unroll
;       for (int r = 0; r < 4; ++r) {
;         const int tok = (lane >> 4) * 4 + r;
;         const float wl = w0v + cw[r];
;         const float wv = -softplusf_(-wl) - 0.5f;
;         sW[tok * 516 + n] = __expf(-__expf(wv));
;         sAs[tok * 516 + n] = sigmoidf_(a0v + ca[r]);
;       }
;     }
	v_mfma_f32_16x16x32_bf16 v[22:25], v[12:15], v[22:25], 0
	s_waitcnt vmcnt(1)
	v_mfma_f32_16x16x32_bf16 v[22:25], v[4:7], v[40:43], v[22:25]
	global_load_dword v27, v[28:29], off offset:64
	global_load_dword v40, v[0:1], off offset:64
	v_mfma_f32_16x16x32_bf16 v[36:39], v[16:19], v[36:39], 0
	s_waitcnt vmcnt(1)
	s_nop 3
	v_add_f32_e32 v22, v22, v27
	v_max_f32_e64 v41, -v22, 0
	v_mul_f32_e64 v22, |v22|, s36
	v_exp_f32_e32 v22, v22
	v_mfma_f32_16x16x32_bf16 v[36:39], v[8:11], v[44:47], v[36:39]
	v_add_f32_e32 v22, 1.0, v22
	v_cmp_gt_f32_e32 vcc, s72, v22
	s_nop 1
	v_cndmask_b32_e64 v42, 0, 32, vcc
	v_ldexp_f32 v22, v22, v42
	v_log_f32_e32 v22, v22
	s_nop 0
	v_mul_f32_e32 v42, 0x3f317217, v22
	v_fma_f32 v42, v22, s33, -v42
	v_fmac_f32_e32 v42, 0x3377d1cf, v22
	v_fmac_f32_e32 v42, 0x3f317217, v22
	v_cmp_lt_f32_e64 s[40:41], |v22|, s34
	s_nop 1
	v_cndmask_b32_e64 v22, v22, v42, s[40:41]
	v_cndmask_b32_e32 v42, 0, v184, vcc
	v_sub_f32_e32 v22, v22, v42
	v_add_f32_e32 v22, v41, v22
	v_sub_f32_e32 v22, -0.5, v22
	v_mul_f32_e32 v22, 0x3fb8aa3b, v22
	v_exp_f32_e32 v22, v22
	v_add_u32_e32 v41, 0x1000, v31
	v_mul_f32_e32 v22, 0xbfb8aa3b, v22
	v_exp_f32_e32 v22, v22
	ds_write2_b32 v41, v20, v22 offset0:64 offset1:80
	s_waitcnt vmcnt(0)
	v_add_f32_e32 v20, v36, v40
	v_mul_f32_e32 v20, 0xbfb8aa3b, v20
	v_exp_f32_e32 v20, v20
	v_add_u32_e32 v22, 0x9000, v31
	v_or_b32_e32 v36, 32, v30
	v_add_f32_e32 v20, 1.0, v20
	v_rcp_f32_e32 v20, v20
	ds_write2_b32 v22, v21, v20 offset0:128 offset1:144
	v_add_f32_e32 v20, v23, v27
	v_max_f32_e64 v21, -v20, 0
	v_mul_f32_e64 v20, |v20|, s36
	v_exp_f32_e32 v20, v20
	s_nop 0
	v_add_f32_e32 v20, 1.0, v20
	v_cmp_gt_f32_e32 vcc, s72, v20
	s_nop 1
	v_cndmask_b32_e64 v22, 0, 32, vcc
	v_ldexp_f32 v20, v20, v22
	v_log_f32_e32 v20, v20
	s_nop 0
	v_mul_f32_e32 v22, 0x3f317217, v20
	v_fma_f32 v22, v20, s33, -v22
	v_fmac_f32_e32 v22, 0x3377d1cf, v20
	v_fmac_f32_e32 v22, 0x3f317217, v20
	v_cmp_lt_f32_e64 s[40:41], |v20|, s34
	s_nop 1
	v_cndmask_b32_e64 v20, v20, v22, s[40:41]
	v_cndmask_b32_e32 v22, 0, v184, vcc
	v_sub_f32_e32 v20, v20, v22
	v_add_f32_e32 v20, v21, v20
	v_sub_f32_e32 v20, -0.5, v20
	v_mul_f32_e32 v20, 0x3fb8aa3b, v20
	v_exp_f32_e32 v20, v20
	v_add_lshl_u32 v21, v2, v26, 2
	v_mul_f32_e32 v20, 0xbfb8aa3b, v20
	v_exp_f32_e32 v20, v20
	ds_write_b32 v21, v20 offset:6416
	v_add_f32_e32 v20, v37, v40
	v_mul_f32_e32 v20, 0xbfb8aa3b, v20
	v_exp_f32_e32 v20, v20
	v_ashrrev_i32_e32 v37, 31, v36
	v_add_f32_e32 v20, 1.0, v20
	v_rcp_f32_e32 v20, v20
	ds_write_b32 v21, v20 offset:39440
	v_add_f32_e32 v20, v24, v27
	v_max_f32_e64 v22, -v20, 0
	v_mul_f32_e64 v20, |v20|, s36
	v_exp_f32_e32 v20, v20
	s_nop 0
	v_add_f32_e32 v20, 1.0, v20
	v_cmp_gt_f32_e32 vcc, s72, v20
	s_nop 1
	v_cndmask_b32_e64 v23, 0, 32, vcc
	v_ldexp_f32 v20, v20, v23
	v_log_f32_e32 v20, v20
	s_nop 0
	v_mul_f32_e32 v23, 0x3f317217, v20
	v_fma_f32 v23, v20, s33, -v23
	v_fmac_f32_e32 v23, 0x3377d1cf, v20
	v_fmac_f32_e32 v23, 0x3f317217, v20
	v_cmp_lt_f32_e64 s[40:41], |v20|, s34
	s_nop 1
	v_cndmask_b32_e64 v20, v20, v23, s[40:41]
	v_cndmask_b32_e32 v23, 0, v184, vcc
	v_sub_f32_e32 v20, v20, v23
	v_add_f32_e32 v20, v22, v20
	v_sub_f32_e32 v20, -0.5, v20
	v_mul_f32_e32 v20, 0x3fb8aa3b, v20
	v_exp_f32_e32 v20, v20
	s_nop 0
	v_mul_f32_e32 v20, 0xbfb8aa3b, v20
	v_exp_f32_e32 v20, v20
	ds_write_b32 v21, v20 offset:8480
	v_add_f32_e32 v20, v38, v40
	v_mul_f32_e32 v20, 0xbfb8aa3b, v20
	v_exp_f32_e32 v20, v20
	s_nop 0
	v_add_f32_e32 v20, 1.0, v20
	v_rcp_f32_e32 v20, v20
	ds_write_b32 v21, v20 offset:41504
	v_add_f32_e32 v20, v25, v27
	v_max_f32_e64 v22, -v20, 0
	v_mul_f32_e64 v20, |v20|, s36
	v_exp_f32_e32 v20, v20
	s_nop 0
	v_add_f32_e32 v20, 1.0, v20
	v_cmp_gt_f32_e32 vcc, s72, v20
	s_nop 1
	v_cndmask_b32_e64 v23, 0, 32, vcc
	v_ldexp_f32 v20, v20, v23
	v_log_f32_e32 v20, v20
	s_nop 0
	v_mul_f32_e32 v23, 0x3f317217, v20
	v_fma_f32 v23, v20, s33, -v23
	v_fmac_f32_e32 v23, 0x3377d1cf, v20
	v_fmac_f32_e32 v23, 0x3f317217, v20
	v_cmp_lt_f32_e64 s[40:41], |v20|, s34
	s_nop 1
	v_cndmask_b32_e64 v20, v20, v23, s[40:41]
	v_cndmask_b32_e32 v23, 0, v184, vcc
	v_sub_f32_e32 v20, v20, v23
	v_add_f32_e32 v20, v22, v20
	v_sub_f32_e32 v20, -0.5, v20
	v_mul_f32_e32 v20, 0x3fb8aa3b, v20
	v_exp_f32_e32 v20, v20
	s_nop 0
	v_mul_f32_e32 v20, 0xbfb8aa3b, v20
	v_exp_f32_e32 v20, v20
	ds_write_b32 v21, v20 offset:10544
	v_add_f32_e32 v20, v39, v40
	v_mul_f32_e32 v20, 0xbfb8aa3b, v20
	v_exp_f32_e32 v20, v20
	s_nop 0
	v_add_f32_e32 v20, 1.0, v20
	v_rcp_f32_e32 v20, v20
	ds_write_b32 v21, v20 offset:43568
	v_lshlrev_b64 v[20:21], 7, v[36:37]
	v_lshl_add_u64 v[42:43], v[32:33], 0, v[20:21]
	v_lshl_add_u64 v[44:45], v[34:35], 0, v[20:21]
	global_load_dwordx4 v[20:23], v[42:43], off
	global_load_dwordx4 v[24:27], v[44:45], off
	s_waitcnt vmcnt(0)
	v_mfma_f32_16x16x32_bf16 v[38:41], v[16:19], v[24:27], 0
	global_load_dwordx4 v[24:27], v[42:43], off offset:64
	s_nop 0
	global_load_dwordx4 v[42:45], v[44:45], off offset:64
	v_mfma_f32_16x16x32_bf16 v[20:23], v[12:15], v[20:23], 0
	s_waitcnt vmcnt(1)
	v_mfma_f32_16x16x32_bf16 v[24:27], v[4:7], v[24:27], v[20:23]
	s_waitcnt vmcnt(0)
	v_mfma_f32_16x16x32_bf16 v[20:23], v[8:11], v[42:45], v[38:41]
	global_load_dword v37, v[28:29], off offset:128
	s_nop 1
	global_load_dword v38, v[0:1], off offset:128
	s_waitcnt vmcnt(1)
	s_nop 0
	v_add_f32_e32 v24, v24, v37
	v_max_f32_e64 v39, -v24, 0
	v_mul_f32_e64 v24, |v24|, s36
	v_exp_f32_e32 v24, v24
	s_waitcnt vmcnt(0)
; __device__ __forceinline__ float sigmoidf_(float x) { return frcp_(1.f + __expf(-x)); }
; __device__ __forceinline__ float softplusf_(float x) { return fmaxf(x, 0.f) + __logf(1.f + __expf(-fabsf(x))); }
; __device__ __forceinline__ void prep_rwkv(const Params& p, int l, int item, char* smem) {
;     ...
; #pragma unroll
;     for (int jt = 0; jt < 8; ++jt) {
;       const int n = wave * 128 + jt * 16 + fr;
;       f32x4 cw = (f32x4){0.f, 0.f, 0.f, 0.f}, ca = (f32x4){0.f, 0.f, 0.f, 0.f};
; #pragma unroll
;       for (int ks = 0; ks < 2; ++ks) {
;         const bf16x8 bw = *(const bf16x8*)(W2T + (size_t)n * 64 + ks * 32 + fq);
;         const bf16x8 ba = *(const bf16x8*)(A2T + (size_t)n * 64 + ks * 32 + fq);
;         cw = __builtin_amdgcn_mfma_f32_16x16x32_bf16(atw[ks], bw, cw, 0, 0, 0);
;         ca = __builtin_amdgcn_mfma_f32_16x16x32_bf16(aad[ks], ba, ca, 0, 0, 0);
;       }
;       const float w0v = w0[n], a0v = a0[n];
; #pragma unroll
;       for (int r = 0; r < 4; ++r) {
;         const int tok = (lane >> 4) * 4 + r;
;         const float wl = w0v + cw[r];
;         const float wv = -softplusf_(-wl) - 0.5f;
;         sW[tok * 516 + n] = __expf(-__expf(wv));
;         sAs[tok * 516 + n] = sigmoidf_(a0v + ca[r]);
;       }
;     }
	v_add_f32_e32 v20, v20, v38
	v_mul_f32_e32 v20, 0xbfb8aa3b, v20
	v_exp_f32_e32 v20, v20
	v_add_f32_e32 v24, 1.0, v24
	v_cmp_gt_f32_e32 vcc, s72, v24
	v_add_f32_e32 v20, 1.0, v20
	s_nop 0
	v_cndmask_b32_e64 v40, 0, 32, vcc
	v_ldexp_f32 v24, v24, v40
	v_log_f32_e32 v24, v24
	v_rcp_f32_e32 v20, v20
	v_mul_f32_e32 v40, 0x3f317217, v24
	v_fma_f32 v40, v24, s33, -v40
	v_fmac_f32_e32 v40, 0x3377d1cf, v24
	v_fmac_f32_e32 v40, 0x3f317217, v24
	v_cmp_lt_f32_e64 s[40:41], |v24|, s34
	ds_write_b32 v31, v20 offset:37504
	v_add_f32_e32 v20, v25, v37
	v_cndmask_b32_e64 v24, v24, v40, s[40:41]
	v_cndmask_b32_e32 v40, 0, v184, vcc
	v_sub_f32_e32 v24, v24, v40
	v_add_f32_e32 v24, v39, v24
	v_sub_f32_e32 v24, -0.5, v24
	v_mul_f32_e32 v24, 0x3fb8aa3b, v24
	v_exp_f32_e32 v24, v24
	s_nop 0
	v_mul_f32_e32 v24, 0xbfb8aa3b, v24
	v_exp_f32_e32 v24, v24
	ds_write_b32 v31, v24 offset:4480
	v_max_f32_e64 v24, -v20, 0
	v_mul_f32_e64 v20, |v20|, s36
	v_exp_f32_e32 v20, v20
	s_nop 0
	v_add_f32_e32 v20, 1.0, v20
	v_cmp_gt_f32_e32 vcc, s72, v20
	s_nop 1
	v_cndmask_b32_e64 v25, 0, 32, vcc
	v_ldexp_f32 v20, v20, v25
	v_log_f32_e32 v20, v20
	s_nop 0
	v_mul_f32_e32 v25, 0x3f317217, v20
	v_fma_f32 v25, v20, s33, -v25
	v_fmac_f32_e32 v25, 0x3377d1cf, v20
	v_fmac_f32_e32 v25, 0x3f317217, v20
	v_cmp_lt_f32_e64 s[40:41], |v20|, s34
	s_nop 1
	v_cndmask_b32_e64 v20, v20, v25, s[40:41]
	v_cndmask_b32_e32 v25, 0, v184, vcc
	v_sub_f32_e32 v20, v20, v25
	v_add_f32_e32 v20, v24, v20
	v_sub_f32_e32 v20, -0.5, v20
	v_mul_f32_e32 v20, 0x3fb8aa3b, v20
	v_exp_f32_e32 v20, v20
	v_add_lshl_u32 v24, v2, v36, 2
	v_or_b32_e32 v36, 48, v30
	v_mul_f32_e32 v20, 0xbfb8aa3b, v20
	v_exp_f32_e32 v20, v20
	ds_write_b32 v24, v20 offset:6416
	v_add_f32_e32 v20, v21, v38
	v_mul_f32_e32 v20, 0xbfb8aa3b, v20
	v_exp_f32_e32 v20, v20
	s_nop 0
	v_add_f32_e32 v20, 1.0, v20
	v_rcp_f32_e32 v20, v20
	ds_write_b32 v24, v20 offset:39440
	v_add_f32_e32 v20, v26, v37
	v_max_f32_e64 v21, -v20, 0
	v_mul_f32_e64 v20, |v20|, s36
	v_exp_f32_e32 v20, v20
	s_nop 0
	v_add_f32_e32 v20, 1.0, v20
	v_cmp_gt_f32_e32 vcc, s72, v20
	s_nop 1
	v_cndmask_b32_e64 v25, 0, 32, vcc
	v_ldexp_f32 v20, v20, v25
	v_log_f32_e32 v20, v20
	s_nop 0
	v_mul_f32_e32 v25, 0x3f317217, v20
	v_fma_f32 v25, v20, s33, -v25
	v_fmac_f32_e32 v25, 0x3377d1cf, v20
	v_fmac_f32_e32 v25, 0x3f317217, v20
	v_cmp_lt_f32_e64 s[40:41], |v20|, s34
	s_nop 1
	v_cndmask_b32_e64 v20, v20, v25, s[40:41]
	v_cndmask_b32_e32 v25, 0, v184, vcc
	v_sub_f32_e32 v20, v20, v25
	v_add_f32_e32 v20, v21, v20
	v_sub_f32_e32 v20, -0.5, v20
	v_mul_f32_e32 v20, 0x3fb8aa3b, v20
	v_exp_f32_e32 v20, v20
	s_nop 0
	v_mul_f32_e32 v20, 0xbfb8aa3b, v20
	v_exp_f32_e32 v20, v20
	ds_write_b32 v24, v20 offset:8480
	v_add_f32_e32 v20, v22, v38
	v_mul_f32_e32 v20, 0xbfb8aa3b, v20
	v_exp_f32_e32 v20, v20
	s_nop 0
	v_add_f32_e32 v20, 1.0, v20
	v_rcp_f32_e32 v20, v20
	ds_write_b32 v24, v20 offset:41504
	v_add_f32_e32 v20, v27, v37
	v_max_f32_e64 v21, -v20, 0
	v_mul_f32_e64 v20, |v20|, s36
	v_exp_f32_e32 v20, v20
	v_ashrrev_i32_e32 v37, 31, v36
	v_add_f32_e32 v20, 1.0, v20
	v_cmp_gt_f32_e32 vcc, s72, v20
	s_nop 1
	v_cndmask_b32_e64 v22, 0, 32, vcc
	v_ldexp_f32 v20, v20, v22
	v_log_f32_e32 v20, v20
	s_nop 0
	v_mul_f32_e32 v22, 0x3f317217, v20
	v_fma_f32 v22, v20, s33, -v22
	v_fmac_f32_e32 v22, 0x3377d1cf, v20
	v_fmac_f32_e32 v22, 0x3f317217, v20
	v_cmp_lt_f32_e64 s[40:41], |v20|, s34
	s_nop 1
	v_cndmask_b32_e64 v20, v20, v22, s[40:41]
	v_cndmask_b32_e32 v22, 0, v184, vcc
	v_sub_f32_e32 v20, v20, v22
	v_add_f32_e32 v20, v21, v20
	v_sub_f32_e32 v20, -0.5, v20
	v_mul_f32_e32 v20, 0x3fb8aa3b, v20
	v_exp_f32_e32 v20, v20
	s_nop 0
	v_mul_f32_e32 v20, 0xbfb8aa3b, v20
	v_exp_f32_e32 v20, v20
	ds_write_b32 v24, v20 offset:10544
	v_add_f32_e32 v20, v23, v38
	v_mul_f32_e32 v20, 0xbfb8aa3b, v20
	v_exp_f32_e32 v20, v20
	s_nop 0
	v_add_f32_e32 v20, 1.0, v20
	v_rcp_f32_e32 v20, v20
	ds_write_b32 v24, v20 offset:43568
	v_lshlrev_b64 v[20:21], 7, v[36:37]
	v_lshl_add_u64 v[42:43], v[32:33], 0, v[20:21]
	v_lshl_add_u64 v[44:45], v[34:35], 0, v[20:21]
	global_load_dwordx4 v[20:23], v[42:43], off
	global_load_dwordx4 v[24:27], v[44:45], off
	s_waitcnt vmcnt(0)
	v_mfma_f32_16x16x32_bf16 v[38:41], v[16:19], v[24:27], 0
	global_load_dwordx4 v[24:27], v[42:43], off offset:64
	s_nop 0
	global_load_dwordx4 v[42:45], v[44:45], off offset:64
	v_mfma_f32_16x16x32_bf16 v[20:23], v[12:15], v[20:23], 0
	s_waitcnt vmcnt(1)
	v_mfma_f32_16x16x32_bf16 v[24:27], v[4:7], v[24:27], v[20:23]
	s_waitcnt vmcnt(0)
	v_mfma_f32_16x16x32_bf16 v[20:23], v[8:11], v[42:45], v[38:41]
	global_load_dword v37, v[28:29], off offset:192
	s_nop 1
	global_load_dword v38, v[0:1], off offset:192
	s_waitcnt vmcnt(1)
	s_nop 0
	v_add_f32_e32 v24, v24, v37
	v_max_f32_e64 v39, -v24, 0
	v_mul_f32_e64 v24, |v24|, s36
	v_exp_f32_e32 v24, v24
	s_waitcnt vmcnt(0)
; __device__ __forceinline__ float sigmoidf_(float x) { return frcp_(1.f + __expf(-x)); }
; __device__ __forceinline__ float softplusf_(float x) { return fmaxf(x, 0.f) + __logf(1.f + __expf(-fabsf(x))); }
; __device__ __forceinline__ void prep_rwkv(const Params& p, int l, int item, char* smem) {
;     ...
; #pragma unroll
;     for (int jt = 0; jt < 8; ++jt) {
;       const int n = wave * 128 + jt * 16 + fr;
;       f32x4 cw = (f32x4){0.f, 0.f, 0.f, 0.f}, ca = (f32x4){0.f, 0.f, 0.f, 0.f};
; #pragma unroll
;       for (int ks = 0; ks < 2; ++ks) {
;         const bf16x8 bw = *(const bf16x8*)(W2T + (size_t)n * 64 + ks * 32 + fq);
;         const bf16x8 ba = *(const bf16x8*)(A2T + (size_t)n * 64 + ks * 32 + fq);
;         cw = __builtin_amdgcn_mfma_f32_16x16x32_bf16(atw[ks], bw, cw, 0, 0, 0);
;         ca = __builtin_amdgcn_mfma_f32_16x16x32_bf16(aad[ks], ba, ca, 0, 0, 0);
;       }
;       const float w0v = w0[n], a0v = a0[n];
; #pragma unroll
;       for (int r = 0; r < 4; ++r) {
;         const int tok = (lane >> 4) * 4 + r;
;         const float wl = w0v + cw[r];
;         const float wv = -softplusf_(-wl) - 0.5f;
;         sW[tok * 516 + n] = __expf(-__expf(wv));
;         sAs[tok * 516 + n] = sigmoidf_(a0v + ca[r]);
;       }
;     }
	v_add_f32_e32 v20, v20, v38
	v_mul_f32_e32 v20, 0xbfb8aa3b, v20
	v_exp_f32_e32 v20, v20
	v_add_f32_e32 v24, 1.0, v24
	v_cmp_gt_f32_e32 vcc, s72, v24
	v_add_f32_e32 v20, 1.0, v20
	s_nop 0
	v_cndmask_b32_e64 v40, 0, 32, vcc
	v_ldexp_f32 v24, v24, v40
	v_log_f32_e32 v24, v24
	v_rcp_f32_e32 v20, v20
	v_mul_f32_e32 v40, 0x3f317217, v24
	v_fma_f32 v40, v24, s33, -v40
	v_fmac_f32_e32 v40, 0x3377d1cf, v24
	v_fmac_f32_e32 v40, 0x3f317217, v24
	v_cmp_lt_f32_e64 s[40:41], |v24|, s34
	ds_write_b32 v31, v20 offset:37568
	v_add_f32_e32 v20, v25, v37
	v_cndmask_b32_e64 v24, v24, v40, s[40:41]
	v_cndmask_b32_e32 v40, 0, v184, vcc
	v_sub_f32_e32 v24, v24, v40
	v_add_f32_e32 v24, v39, v24
	v_sub_f32_e32 v24, -0.5, v24
	v_mul_f32_e32 v24, 0x3fb8aa3b, v24
	v_exp_f32_e32 v24, v24
	s_nop 0
	v_mul_f32_e32 v24, 0xbfb8aa3b, v24
	v_exp_f32_e32 v24, v24
	ds_write_b32 v31, v24 offset:4544
	v_max_f32_e64 v24, -v20, 0
	v_mul_f32_e64 v20, |v20|, s36
	v_exp_f32_e32 v20, v20
	s_nop 0
	v_add_f32_e32 v20, 1.0, v20
	v_cmp_gt_f32_e32 vcc, s72, v20
	s_nop 1
	v_cndmask_b32_e64 v25, 0, 32, vcc
	v_ldexp_f32 v20, v20, v25
	v_log_f32_e32 v20, v20
	s_nop 0
	v_mul_f32_e32 v25, 0x3f317217, v20
	v_fma_f32 v25, v20, s33, -v25
	v_fmac_f32_e32 v25, 0x3377d1cf, v20
	v_fmac_f32_e32 v25, 0x3f317217, v20
	v_cmp_lt_f32_e64 s[40:41], |v20|, s34
	s_nop 1
	v_cndmask_b32_e64 v20, v20, v25, s[40:41]
	v_cndmask_b32_e32 v25, 0, v184, vcc
	v_sub_f32_e32 v20, v20, v25
	v_add_f32_e32 v20, v24, v20
	v_sub_f32_e32 v20, -0.5, v20
	v_mul_f32_e32 v20, 0x3fb8aa3b, v20
	v_exp_f32_e32 v20, v20
	v_add_lshl_u32 v24, v2, v36, 2
	v_or_b32_e32 v36, 64, v30
	v_mul_f32_e32 v20, 0xbfb8aa3b, v20
	v_exp_f32_e32 v20, v20
	ds_write_b32 v24, v20 offset:6416
	v_add_f32_e32 v20, v21, v38
	v_mul_f32_e32 v20, 0xbfb8aa3b, v20
	v_exp_f32_e32 v20, v20
	s_nop 0
	v_add_f32_e32 v20, 1.0, v20
	v_rcp_f32_e32 v20, v20
	ds_write_b32 v24, v20 offset:39440
	v_add_f32_e32 v20, v26, v37
	v_max_f32_e64 v21, -v20, 0
	v_mul_f32_e64 v20, |v20|, s36
	v_exp_f32_e32 v20, v20
	s_nop 0
	v_add_f32_e32 v20, 1.0, v20
	v_cmp_gt_f32_e32 vcc, s72, v20
	s_nop 1
	v_cndmask_b32_e64 v25, 0, 32, vcc
	v_ldexp_f32 v20, v20, v25
	v_log_f32_e32 v20, v20
	s_nop 0
	v_mul_f32_e32 v25, 0x3f317217, v20
	v_fma_f32 v25, v20, s33, -v25
	v_fmac_f32_e32 v25, 0x3377d1cf, v20
	v_fmac_f32_e32 v25, 0x3f317217, v20
	v_cmp_lt_f32_e64 s[40:41], |v20|, s34
	s_nop 1
	v_cndmask_b32_e64 v20, v20, v25, s[40:41]
	v_cndmask_b32_e32 v25, 0, v184, vcc
	v_sub_f32_e32 v20, v20, v25
	v_add_f32_e32 v20, v21, v20
	v_sub_f32_e32 v20, -0.5, v20
	v_mul_f32_e32 v20, 0x3fb8aa3b, v20
	v_exp_f32_e32 v20, v20
	s_nop 0
	v_mul_f32_e32 v20, 0xbfb8aa3b, v20
	v_exp_f32_e32 v20, v20
	ds_write_b32 v24, v20 offset:8480
	v_add_f32_e32 v20, v22, v38
	v_mul_f32_e32 v20, 0xbfb8aa3b, v20
	v_exp_f32_e32 v20, v20
	s_nop 0
	v_add_f32_e32 v20, 1.0, v20
	v_rcp_f32_e32 v20, v20
	ds_write_b32 v24, v20 offset:41504
	v_add_f32_e32 v20, v27, v37
	v_max_f32_e64 v21, -v20, 0
	v_mul_f32_e64 v20, |v20|, s36
	v_exp_f32_e32 v20, v20
	v_ashrrev_i32_e32 v37, 31, v36
	v_add_f32_e32 v20, 1.0, v20
	v_cmp_gt_f32_e32 vcc, s72, v20
	s_nop 1
	v_cndmask_b32_e64 v22, 0, 32, vcc
	v_ldexp_f32 v20, v20, v22
	v_log_f32_e32 v20, v20
	s_nop 0
	v_mul_f32_e32 v22, 0x3f317217, v20
	v_fma_f32 v22, v20, s33, -v22
	v_fmac_f32_e32 v22, 0x3377d1cf, v20
	v_fmac_f32_e32 v22, 0x3f317217, v20
	v_cmp_lt_f32_e64 s[40:41], |v20|, s34
	s_nop 1
	v_cndmask_b32_e64 v20, v20, v22, s[40:41]
	v_cndmask_b32_e32 v22, 0, v184, vcc
	v_sub_f32_e32 v20, v20, v22
	v_add_f32_e32 v20, v21, v20
	v_sub_f32_e32 v20, -0.5, v20
	v_mul_f32_e32 v20, 0x3fb8aa3b, v20
	v_exp_f32_e32 v20, v20
	s_nop 0
	v_mul_f32_e32 v20, 0xbfb8aa3b, v20
	v_exp_f32_e32 v20, v20
	ds_write_b32 v24, v20 offset:10544
	v_add_f32_e32 v20, v23, v38
	v_mul_f32_e32 v20, 0xbfb8aa3b, v20
	v_exp_f32_e32 v20, v20
	s_nop 0
	v_add_f32_e32 v20, 1.0, v20
	v_rcp_f32_e32 v20, v20
	ds_write_b32 v24, v20 offset:43568
	v_lshlrev_b64 v[20:21], 7, v[36:37]
	v_lshl_add_u64 v[42:43], v[32:33], 0, v[20:21]
	v_lshl_add_u64 v[44:45], v[34:35], 0, v[20:21]
	global_load_dwordx4 v[20:23], v[42:43], off
	global_load_dwordx4 v[24:27], v[44:45], off
	s_waitcnt vmcnt(0)
	v_mfma_f32_16x16x32_bf16 v[38:41], v[16:19], v[24:27], 0
	global_load_dwordx4 v[24:27], v[42:43], off offset:64
	s_nop 0
	global_load_dwordx4 v[42:45], v[44:45], off offset:64
	v_mfma_f32_16x16x32_bf16 v[20:23], v[12:15], v[20:23], 0
	s_waitcnt vmcnt(1)
	v_mfma_f32_16x16x32_bf16 v[24:27], v[4:7], v[24:27], v[20:23]
	s_waitcnt vmcnt(0)
	v_mfma_f32_16x16x32_bf16 v[20:23], v[8:11], v[42:45], v[38:41]
	global_load_dword v37, v[28:29], off offset:256
	s_nop 1
	global_load_dword v38, v[0:1], off offset:256
	s_waitcnt vmcnt(1)
	s_nop 0
	v_add_f32_e32 v24, v24, v37
	v_max_f32_e64 v39, -v24, 0
	v_mul_f32_e64 v24, |v24|, s36
	v_exp_f32_e32 v24, v24
	s_waitcnt vmcnt(0)
; __device__ __forceinline__ float sigmoidf_(float x) { return frcp_(1.f + __expf(-x)); }
; __device__ __forceinline__ float softplusf_(float x) { return fmaxf(x, 0.f) + __logf(1.f + __expf(-fabsf(x))); }
; __device__ __forceinline__ void prep_rwkv(const Params& p, int l, int item, char* smem) {
;     ...
; #pragma unroll
;     for (int jt = 0; jt < 8; ++jt) {
;       const int n = wave * 128 + jt * 16 + fr;
;       f32x4 cw = (f32x4){0.f, 0.f, 0.f, 0.f}, ca = (f32x4){0.f, 0.f, 0.f, 0.f};
; #pragma unroll
;       for (int ks = 0; ks < 2; ++ks) {
;         const bf16x8 bw = *(const bf16x8*)(W2T + (size_t)n * 64 + ks * 32 + fq);
;         const bf16x8 ba = *(const bf16x8*)(A2T + (size_t)n * 64 + ks * 32 + fq);
;         cw = __builtin_amdgcn_mfma_f32_16x16x32_bf16(atw[ks], bw, cw, 0, 0, 0);
;         ca = __builtin_amdgcn_mfma_f32_16x16x32_bf16(aad[ks], ba, ca, 0, 0, 0);
;       }
;       const float w0v = w0[n], a0v = a0[n];
; #pragma unroll
;       for (int r = 0; r < 4; ++r) {
;         const int tok = (lane >> 4) * 4 + r;
;         const float wl = w0v + cw[r];
;         const float wv = -softplusf_(-wl) - 0.5f;
;         sW[tok * 516 + n] = __expf(-__expf(wv));
;         sAs[tok * 516 + n] = sigmoidf_(a0v + ca[r]);
;       }
;     }
	v_add_f32_e32 v20, v20, v38
	v_mul_f32_e32 v20, 0xbfb8aa3b, v20
	v_exp_f32_e32 v20, v20
	v_add_f32_e32 v24, 1.0, v24
	v_cmp_gt_f32_e32 vcc, s72, v24
	v_add_f32_e32 v20, 1.0, v20
	s_nop 0
	v_cndmask_b32_e64 v40, 0, 32, vcc
	v_ldexp_f32 v24, v24, v40
	v_log_f32_e32 v24, v24
	v_rcp_f32_e32 v20, v20
	v_mul_f32_e32 v40, 0x3f317217, v24
	v_fma_f32 v40, v24, s33, -v40
	v_fmac_f32_e32 v40, 0x3377d1cf, v24
	v_fmac_f32_e32 v40, 0x3f317217, v24
	v_cmp_lt_f32_e64 s[40:41], |v24|, s34
	ds_write_b32 v31, v20 offset:37632
	v_add_f32_e32 v20, v25, v37
	v_cndmask_b32_e64 v24, v24, v40, s[40:41]
	v_cndmask_b32_e32 v40, 0, v184, vcc
	v_sub_f32_e32 v24, v24, v40
	v_add_f32_e32 v24, v39, v24
	v_sub_f32_e32 v24, -0.5, v24
	v_mul_f32_e32 v24, 0x3fb8aa3b, v24
	v_exp_f32_e32 v24, v24
	s_nop 0
	v_mul_f32_e32 v24, 0xbfb8aa3b, v24
	v_exp_f32_e32 v24, v24
	ds_write_b32 v31, v24 offset:4608
	v_max_f32_e64 v24, -v20, 0
	v_mul_f32_e64 v20, |v20|, s36
	v_exp_f32_e32 v20, v20
	s_nop 0
	v_add_f32_e32 v20, 1.0, v20
	v_cmp_gt_f32_e32 vcc, s72, v20
	s_nop 1
	v_cndmask_b32_e64 v25, 0, 32, vcc
	v_ldexp_f32 v20, v20, v25
	v_log_f32_e32 v20, v20
	s_nop 0
	v_mul_f32_e32 v25, 0x3f317217, v20
	v_fma_f32 v25, v20, s33, -v25
	v_fmac_f32_e32 v25, 0x3377d1cf, v20
	v_fmac_f32_e32 v25, 0x3f317217, v20
	v_cmp_lt_f32_e64 s[40:41], |v20|, s34
	s_nop 1
	v_cndmask_b32_e64 v20, v20, v25, s[40:41]
	v_cndmask_b32_e32 v25, 0, v184, vcc
	v_sub_f32_e32 v20, v20, v25
	v_add_f32_e32 v20, v24, v20
	v_sub_f32_e32 v20, -0.5, v20
	v_mul_f32_e32 v20, 0x3fb8aa3b, v20
	v_exp_f32_e32 v20, v20
	v_add_lshl_u32 v24, v2, v36, 2
	v_or_b32_e32 v36, 0x50, v30
	v_mul_f32_e32 v20, 0xbfb8aa3b, v20
	v_exp_f32_e32 v20, v20
	ds_write_b32 v24, v20 offset:6416
	v_add_f32_e32 v20, v21, v38
	v_mul_f32_e32 v20, 0xbfb8aa3b, v20
	v_exp_f32_e32 v20, v20
	s_nop 0
	v_add_f32_e32 v20, 1.0, v20
	v_rcp_f32_e32 v20, v20
	ds_write_b32 v24, v20 offset:39440
	v_add_f32_e32 v20, v26, v37
	v_max_f32_e64 v21, -v20, 0
	v_mul_f32_e64 v20, |v20|, s36
	v_exp_f32_e32 v20, v20
	s_nop 0
	v_add_f32_e32 v20, 1.0, v20
	v_cmp_gt_f32_e32 vcc, s72, v20
	s_nop 1
	v_cndmask_b32_e64 v25, 0, 32, vcc
	v_ldexp_f32 v20, v20, v25
	v_log_f32_e32 v20, v20
	s_nop 0
	v_mul_f32_e32 v25, 0x3f317217, v20
	v_fma_f32 v25, v20, s33, -v25
	v_fmac_f32_e32 v25, 0x3377d1cf, v20
	v_fmac_f32_e32 v25, 0x3f317217, v20
	v_cmp_lt_f32_e64 s[40:41], |v20|, s34
	s_nop 1
	v_cndmask_b32_e64 v20, v20, v25, s[40:41]
	v_cndmask_b32_e32 v25, 0, v184, vcc
	v_sub_f32_e32 v20, v20, v25
	v_add_f32_e32 v20, v21, v20
	v_sub_f32_e32 v20, -0.5, v20
	v_mul_f32_e32 v20, 0x3fb8aa3b, v20
	v_exp_f32_e32 v20, v20
	s_nop 0
	v_mul_f32_e32 v20, 0xbfb8aa3b, v20
	v_exp_f32_e32 v20, v20
	ds_write_b32 v24, v20 offset:8480
	v_add_f32_e32 v20, v22, v38
	v_mul_f32_e32 v20, 0xbfb8aa3b, v20
	v_exp_f32_e32 v20, v20
	s_nop 0
	v_add_f32_e32 v20, 1.0, v20
	v_rcp_f32_e32 v20, v20
	ds_write_b32 v24, v20 offset:41504
	v_add_f32_e32 v20, v27, v37
	v_max_f32_e64 v21, -v20, 0
	v_mul_f32_e64 v20, |v20|, s36
	v_exp_f32_e32 v20, v20
	v_ashrrev_i32_e32 v37, 31, v36
	v_add_f32_e32 v20, 1.0, v20
	v_cmp_gt_f32_e32 vcc, s72, v20
	s_nop 1
	v_cndmask_b32_e64 v22, 0, 32, vcc
	v_ldexp_f32 v20, v20, v22
	v_log_f32_e32 v20, v20
	s_nop 0
	v_mul_f32_e32 v22, 0x3f317217, v20
	v_fma_f32 v22, v20, s33, -v22
	v_fmac_f32_e32 v22, 0x3377d1cf, v20
	v_fmac_f32_e32 v22, 0x3f317217, v20
	v_cmp_lt_f32_e64 s[40:41], |v20|, s34
	s_nop 1
	v_cndmask_b32_e64 v20, v20, v22, s[40:41]
	v_cndmask_b32_e32 v22, 0, v184, vcc
	v_sub_f32_e32 v20, v20, v22
	v_add_f32_e32 v20, v21, v20
	v_sub_f32_e32 v20, -0.5, v20
	v_mul_f32_e32 v20, 0x3fb8aa3b, v20
	v_exp_f32_e32 v20, v20
	s_nop 0
	v_mul_f32_e32 v20, 0xbfb8aa3b, v20
	v_exp_f32_e32 v20, v20
	ds_write_b32 v24, v20 offset:10544
	v_add_f32_e32 v20, v23, v38
	v_mul_f32_e32 v20, 0xbfb8aa3b, v20
	v_exp_f32_e32 v20, v20
	s_nop 0
	v_add_f32_e32 v20, 1.0, v20
	v_rcp_f32_e32 v20, v20
	ds_write_b32 v24, v20 offset:43568
	v_lshlrev_b64 v[20:21], 7, v[36:37]
	v_lshl_add_u64 v[42:43], v[32:33], 0, v[20:21]
	v_lshl_add_u64 v[44:45], v[34:35], 0, v[20:21]
	global_load_dwordx4 v[20:23], v[42:43], off
	global_load_dwordx4 v[24:27], v[44:45], off
	s_waitcnt vmcnt(0)
	v_mfma_f32_16x16x32_bf16 v[38:41], v[16:19], v[24:27], 0
	global_load_dwordx4 v[24:27], v[42:43], off offset:64
	s_nop 0
	global_load_dwordx4 v[42:45], v[44:45], off offset:64
	v_mfma_f32_16x16x32_bf16 v[20:23], v[12:15], v[20:23], 0
	s_waitcnt vmcnt(1)
	v_mfma_f32_16x16x32_bf16 v[24:27], v[4:7], v[24:27], v[20:23]
	s_waitcnt vmcnt(0)
	v_mfma_f32_16x16x32_bf16 v[20:23], v[8:11], v[42:45], v[38:41]
	global_load_dword v37, v[28:29], off offset:320
	s_nop 1
	global_load_dword v38, v[0:1], off offset:320
	s_waitcnt vmcnt(1)
	s_nop 0
	v_add_f32_e32 v24, v24, v37
	v_max_f32_e64 v39, -v24, 0
	v_mul_f32_e64 v24, |v24|, s36
	v_exp_f32_e32 v24, v24
	s_waitcnt vmcnt(0)
; __device__ __forceinline__ float sigmoidf_(float x) { return frcp_(1.f + __expf(-x)); }
; __device__ __forceinline__ float softplusf_(float x) { return fmaxf(x, 0.f) + __logf(1.f + __expf(-fabsf(x))); }
; __device__ __forceinline__ void prep_rwkv(const Params& p, int l, int item, char* smem) {
;     ...
; #pragma unroll
;     for (int jt = 0; jt < 8; ++jt) {
;       const int n = wave * 128 + jt * 16 + fr;
;       f32x4 cw = (f32x4){0.f, 0.f, 0.f, 0.f}, ca = (f32x4){0.f, 0.f, 0.f, 0.f};
; #pragma unroll
;       for (int ks = 0; ks < 2; ++ks) {
;         const bf16x8 bw = *(const bf16x8*)(W2T + (size_t)n * 64 + ks * 32 + fq);
;         const bf16x8 ba = *(const bf16x8*)(A2T + (size_t)n * 64 + ks * 32 + fq);
;         cw = __builtin_amdgcn_mfma_f32_16x16x32_bf16(atw[ks], bw, cw, 0, 0, 0);
;         ca = __builtin_amdgcn_mfma_f32_16x16x32_bf16(aad[ks], ba, ca, 0, 0, 0);
;       }
;       const float w0v = w0[n], a0v = a0[n];
; #pragma unroll
;       for (int r = 0; r < 4; ++r) {
;         const int tok = (lane >> 4) * 4 + r;
;         const float wl = w0v + cw[r];
;         const float wv = -softplusf_(-wl) - 0.5f;
;         sW[tok * 516 + n] = __expf(-__expf(wv));
;         sAs[tok * 516 + n] = sigmoidf_(a0v + ca[r]);
;       }
;     }
	v_add_f32_e32 v20, v20, v38
	v_mul_f32_e32 v20, 0xbfb8aa3b, v20
	v_exp_f32_e32 v20, v20
	v_add_f32_e32 v24, 1.0, v24
	v_cmp_gt_f32_e32 vcc, s72, v24
	v_add_f32_e32 v20, 1.0, v20
	s_nop 0
	v_cndmask_b32_e64 v40, 0, 32, vcc
	v_ldexp_f32 v24, v24, v40
	v_log_f32_e32 v24, v24
	v_rcp_f32_e32 v20, v20
	v_mul_f32_e32 v40, 0x3f317217, v24
	v_fma_f32 v40, v24, s33, -v40
	v_fmac_f32_e32 v40, 0x3377d1cf, v24
	v_fmac_f32_e32 v40, 0x3f317217, v24
	v_cmp_lt_f32_e64 s[40:41], |v24|, s34
	ds_write_b32 v31, v20 offset:37696
	v_add_f32_e32 v20, v25, v37
	v_cndmask_b32_e64 v24, v24, v40, s[40:41]
	v_cndmask_b32_e32 v40, 0, v184, vcc
	v_sub_f32_e32 v24, v24, v40
	v_add_f32_e32 v24, v39, v24
	v_sub_f32_e32 v24, -0.5, v24
	v_mul_f32_e32 v24, 0x3fb8aa3b, v24
	v_exp_f32_e32 v24, v24
	s_nop 0
	v_mul_f32_e32 v24, 0xbfb8aa3b, v24
	v_exp_f32_e32 v24, v24
	ds_write_b32 v31, v24 offset:4672
	v_max_f32_e64 v24, -v20, 0
	v_mul_f32_e64 v20, |v20|, s36
	v_exp_f32_e32 v20, v20
	s_nop 0
	v_add_f32_e32 v20, 1.0, v20
	v_cmp_gt_f32_e32 vcc, s72, v20
	s_nop 1
	v_cndmask_b32_e64 v25, 0, 32, vcc
	v_ldexp_f32 v20, v20, v25
	v_log_f32_e32 v20, v20
	s_nop 0
	v_mul_f32_e32 v25, 0x3f317217, v20
	v_fma_f32 v25, v20, s33, -v25
	v_fmac_f32_e32 v25, 0x3377d1cf, v20
	v_fmac_f32_e32 v25, 0x3f317217, v20
	v_cmp_lt_f32_e64 s[40:41], |v20|, s34
	s_nop 1
	v_cndmask_b32_e64 v20, v20, v25, s[40:41]
	v_cndmask_b32_e32 v25, 0, v184, vcc
	v_sub_f32_e32 v20, v20, v25
	v_add_f32_e32 v20, v24, v20
	v_sub_f32_e32 v20, -0.5, v20
	v_mul_f32_e32 v20, 0x3fb8aa3b, v20
	v_exp_f32_e32 v20, v20
	v_add_lshl_u32 v24, v2, v36, 2
	v_or_b32_e32 v36, 0x60, v30
	v_mul_f32_e32 v20, 0xbfb8aa3b, v20
	v_exp_f32_e32 v20, v20
	ds_write_b32 v24, v20 offset:6416
	v_add_f32_e32 v20, v21, v38
	v_mul_f32_e32 v20, 0xbfb8aa3b, v20
	v_exp_f32_e32 v20, v20
	s_nop 0
	v_add_f32_e32 v20, 1.0, v20
	v_rcp_f32_e32 v20, v20
	ds_write_b32 v24, v20 offset:39440
	v_add_f32_e32 v20, v26, v37
	v_max_f32_e64 v21, -v20, 0
	v_mul_f32_e64 v20, |v20|, s36
	v_exp_f32_e32 v20, v20
	s_nop 0
	v_add_f32_e32 v20, 1.0, v20
	v_cmp_gt_f32_e32 vcc, s72, v20
	s_nop 1
	v_cndmask_b32_e64 v25, 0, 32, vcc
	v_ldexp_f32 v20, v20, v25
	v_log_f32_e32 v20, v20
	s_nop 0
	v_mul_f32_e32 v25, 0x3f317217, v20
	v_fma_f32 v25, v20, s33, -v25
	v_fmac_f32_e32 v25, 0x3377d1cf, v20
	v_fmac_f32_e32 v25, 0x3f317217, v20
	v_cmp_lt_f32_e64 s[40:41], |v20|, s34
	s_nop 1
	v_cndmask_b32_e64 v20, v20, v25, s[40:41]
	v_cndmask_b32_e32 v25, 0, v184, vcc
	v_sub_f32_e32 v20, v20, v25
	v_add_f32_e32 v20, v21, v20
	v_sub_f32_e32 v20, -0.5, v20
	v_mul_f32_e32 v20, 0x3fb8aa3b, v20
	v_exp_f32_e32 v20, v20
	s_nop 0
	v_mul_f32_e32 v20, 0xbfb8aa3b, v20
	v_exp_f32_e32 v20, v20
	ds_write_b32 v24, v20 offset:8480
	v_add_f32_e32 v20, v22, v38
	v_mul_f32_e32 v20, 0xbfb8aa3b, v20
	v_exp_f32_e32 v20, v20
	s_nop 0
	v_add_f32_e32 v20, 1.0, v20
	v_rcp_f32_e32 v20, v20
	ds_write_b32 v24, v20 offset:41504
	v_add_f32_e32 v20, v27, v37
	v_max_f32_e64 v21, -v20, 0
	v_mul_f32_e64 v20, |v20|, s36
	v_exp_f32_e32 v20, v20
	v_ashrrev_i32_e32 v37, 31, v36
	v_add_f32_e32 v20, 1.0, v20
	v_cmp_gt_f32_e32 vcc, s72, v20
	s_nop 1
	v_cndmask_b32_e64 v22, 0, 32, vcc
	v_ldexp_f32 v20, v20, v22
	v_log_f32_e32 v20, v20
	s_nop 0
	v_mul_f32_e32 v22, 0x3f317217, v20
	v_fma_f32 v22, v20, s33, -v22
	v_fmac_f32_e32 v22, 0x3377d1cf, v20
	v_fmac_f32_e32 v22, 0x3f317217, v20
	v_cmp_lt_f32_e64 s[40:41], |v20|, s34
	s_nop 1
	v_cndmask_b32_e64 v20, v20, v22, s[40:41]
	v_cndmask_b32_e32 v22, 0, v184, vcc
	v_sub_f32_e32 v20, v20, v22
	v_add_f32_e32 v20, v21, v20
	v_sub_f32_e32 v20, -0.5, v20
	v_mul_f32_e32 v20, 0x3fb8aa3b, v20
	v_exp_f32_e32 v20, v20
	s_nop 0
	v_mul_f32_e32 v20, 0xbfb8aa3b, v20
	v_exp_f32_e32 v20, v20
	ds_write_b32 v24, v20 offset:10544
	v_add_f32_e32 v20, v23, v38
	v_mul_f32_e32 v20, 0xbfb8aa3b, v20
	v_exp_f32_e32 v20, v20
	s_nop 0
	v_add_f32_e32 v20, 1.0, v20
	v_rcp_f32_e32 v20, v20
	ds_write_b32 v24, v20 offset:43568
	v_lshlrev_b64 v[20:21], 7, v[36:37]
	v_lshl_add_u64 v[42:43], v[32:33], 0, v[20:21]
	v_lshl_add_u64 v[44:45], v[34:35], 0, v[20:21]
	global_load_dwordx4 v[20:23], v[42:43], off
	global_load_dwordx4 v[24:27], v[44:45], off
	s_waitcnt vmcnt(0)
	v_mfma_f32_16x16x32_bf16 v[38:41], v[16:19], v[24:27], 0
	global_load_dwordx4 v[24:27], v[42:43], off offset:64
	s_nop 0
	global_load_dwordx4 v[42:45], v[44:45], off offset:64
	v_mfma_f32_16x16x32_bf16 v[20:23], v[12:15], v[20:23], 0
	s_waitcnt vmcnt(1)
	v_mfma_f32_16x16x32_bf16 v[24:27], v[4:7], v[24:27], v[20:23]
	s_waitcnt vmcnt(0)
	v_mfma_f32_16x16x32_bf16 v[20:23], v[8:11], v[42:45], v[38:41]
	global_load_dword v37, v[28:29], off offset:384
	s_nop 1
	global_load_dword v38, v[0:1], off offset:384
	s_waitcnt vmcnt(1)
	s_nop 0
	v_add_f32_e32 v24, v24, v37
	v_max_f32_e64 v39, -v24, 0
	v_mul_f32_e64 v24, |v24|, s36
	v_exp_f32_e32 v24, v24
	s_waitcnt vmcnt(0)
; __device__ __forceinline__ float sigmoidf_(float x) { return frcp_(1.f + __expf(-x)); }
; __device__ __forceinline__ float softplusf_(float x) { return fmaxf(x, 0.f) + __logf(1.f + __expf(-fabsf(x))); }
; __device__ __forceinline__ void prep_rwkv(const Params& p, int l, int item, char* smem) {
;     ...
; #pragma unroll
;     for (int jt = 0; jt < 8; ++jt) {
;       const int n = wave * 128 + jt * 16 + fr;
;       f32x4 cw = (f32x4){0.f, 0.f, 0.f, 0.f}, ca = (f32x4){0.f, 0.f, 0.f, 0.f};
; #pragma unroll
;       for (int ks = 0; ks < 2; ++ks) {
;         const bf16x8 bw = *(const bf16x8*)(W2T + (size_t)n * 64 + ks * 32 + fq);
;         const bf16x8 ba = *(const bf16x8*)(A2T + (size_t)n * 64 + ks * 32 + fq);
;         cw = __builtin_amdgcn_mfma_f32_16x16x32_bf16(atw[ks], bw, cw, 0, 0, 0);
;         ca = __builtin_amdgcn_mfma_f32_16x16x32_bf16(aad[ks], ba, ca, 0, 0, 0);
;       }
;       const float w0v = w0[n], a0v = a0[n];
; #pragma unroll
;       for (int r = 0; r < 4; ++r) {
;         const int tok = (lane >> 4) * 4 + r;
;         const float wl = w0v + cw[r];
;         const float wv = -softplusf_(-wl) - 0.5f;
;         sW[tok * 516 + n] = __expf(-__expf(wv));
;         sAs[tok * 516 + n] = sigmoidf_(a0v + ca[r]);
;       }
;     }
	v_add_f32_e32 v20, v20, v38
	v_mul_f32_e32 v20, 0xbfb8aa3b, v20
	v_exp_f32_e32 v20, v20
	v_add_f32_e32 v24, 1.0, v24
	v_cmp_gt_f32_e32 vcc, s72, v24
	v_add_f32_e32 v20, 1.0, v20
	s_nop 0
	v_cndmask_b32_e64 v40, 0, 32, vcc
	v_ldexp_f32 v24, v24, v40
	v_log_f32_e32 v24, v24
	v_rcp_f32_e32 v20, v20
	v_mul_f32_e32 v40, 0x3f317217, v24
	v_fma_f32 v40, v24, s33, -v40
	v_fmac_f32_e32 v40, 0x3377d1cf, v24
	v_fmac_f32_e32 v40, 0x3f317217, v24
	v_cmp_lt_f32_e64 s[40:41], |v24|, s34
	ds_write_b32 v31, v20 offset:37760
	v_add_f32_e32 v20, v25, v37
	v_cndmask_b32_e64 v24, v24, v40, s[40:41]
	v_cndmask_b32_e32 v40, 0, v184, vcc
	v_sub_f32_e32 v24, v24, v40
	v_add_f32_e32 v24, v39, v24
	v_sub_f32_e32 v24, -0.5, v24
	v_mul_f32_e32 v24, 0x3fb8aa3b, v24
	v_exp_f32_e32 v24, v24
	s_nop 0
	v_mul_f32_e32 v24, 0xbfb8aa3b, v24
	v_exp_f32_e32 v24, v24
	ds_write_b32 v31, v24 offset:4736
	v_max_f32_e64 v24, -v20, 0
	v_mul_f32_e64 v20, |v20|, s36
	v_exp_f32_e32 v20, v20
	s_nop 0
	v_add_f32_e32 v20, 1.0, v20
	v_cmp_gt_f32_e32 vcc, s72, v20
	s_nop 1
	v_cndmask_b32_e64 v25, 0, 32, vcc
	v_ldexp_f32 v20, v20, v25
	v_log_f32_e32 v20, v20
	s_nop 0
	v_mul_f32_e32 v25, 0x3f317217, v20
	v_fma_f32 v25, v20, s33, -v25
	v_fmac_f32_e32 v25, 0x3377d1cf, v20
	v_fmac_f32_e32 v25, 0x3f317217, v20
	v_cmp_lt_f32_e64 s[40:41], |v20|, s34
	s_nop 1
	v_cndmask_b32_e64 v20, v20, v25, s[40:41]
	v_cndmask_b32_e32 v25, 0, v184, vcc
	v_sub_f32_e32 v20, v20, v25
	v_add_f32_e32 v20, v24, v20
	v_sub_f32_e32 v20, -0.5, v20
	v_mul_f32_e32 v20, 0x3fb8aa3b, v20
	v_exp_f32_e32 v20, v20
	v_add_lshl_u32 v24, v2, v36, 2
	v_mul_f32_e32 v20, 0xbfb8aa3b, v20
	v_exp_f32_e32 v20, v20
	ds_write_b32 v24, v20 offset:6416
	v_add_f32_e32 v20, v21, v38
	v_mul_f32_e32 v20, 0xbfb8aa3b, v20
	v_exp_f32_e32 v20, v20
	s_nop 0
	v_add_f32_e32 v20, 1.0, v20
	v_rcp_f32_e32 v20, v20
	ds_write_b32 v24, v20 offset:39440
	v_add_f32_e32 v20, v26, v37
	v_max_f32_e64 v21, -v20, 0
	v_mul_f32_e64 v20, |v20|, s36
	v_exp_f32_e32 v20, v20
	s_nop 0
	v_add_f32_e32 v20, 1.0, v20
	v_cmp_gt_f32_e32 vcc, s72, v20
	s_nop 1
	v_cndmask_b32_e64 v25, 0, 32, vcc
	v_ldexp_f32 v20, v20, v25
	v_log_f32_e32 v20, v20
	s_nop 0
	v_mul_f32_e32 v25, 0x3f317217, v20
	v_fma_f32 v25, v20, s33, -v25
	v_fmac_f32_e32 v25, 0x3377d1cf, v20
	v_fmac_f32_e32 v25, 0x3f317217, v20
	v_cmp_lt_f32_e64 s[40:41], |v20|, s34
	s_nop 1
	v_cndmask_b32_e64 v20, v20, v25, s[40:41]
	v_cndmask_b32_e32 v25, 0, v184, vcc
	v_sub_f32_e32 v20, v20, v25
	v_add_f32_e32 v20, v21, v20
	v_sub_f32_e32 v20, -0.5, v20
	v_mul_f32_e32 v20, 0x3fb8aa3b, v20
	v_exp_f32_e32 v20, v20
	s_nop 0
	v_mul_f32_e32 v20, 0xbfb8aa3b, v20
	v_exp_f32_e32 v20, v20
	ds_write_b32 v24, v20 offset:8480
	v_add_f32_e32 v20, v22, v38
	v_mul_f32_e32 v20, 0xbfb8aa3b, v20
	v_exp_f32_e32 v20, v20
	s_nop 0
	v_add_f32_e32 v20, 1.0, v20
	v_rcp_f32_e32 v20, v20
	ds_write_b32 v24, v20 offset:41504
	v_add_f32_e32 v20, v27, v37
	v_max_f32_e64 v21, -v20, 0
	v_mul_f32_e64 v20, |v20|, s36
	v_exp_f32_e32 v20, v20
	s_nop 0
	v_add_f32_e32 v20, 1.0, v20
	v_cmp_gt_f32_e32 vcc, s72, v20
	s_nop 1
	v_cndmask_b32_e64 v22, 0, 32, vcc
	v_ldexp_f32 v20, v20, v22
	v_log_f32_e32 v20, v20
	s_nop 0
	v_mul_f32_e32 v22, 0x3f317217, v20
	v_fma_f32 v22, v20, s33, -v22
	v_fmac_f32_e32 v22, 0x3377d1cf, v20
	v_fmac_f32_e32 v22, 0x3f317217, v20
	v_cmp_lt_f32_e64 s[40:41], |v20|, s34
	s_nop 1
	v_cndmask_b32_e64 v20, v20, v22, s[40:41]
	v_cndmask_b32_e32 v22, 0, v184, vcc
	v_sub_f32_e32 v20, v20, v22
	v_add_f32_e32 v20, v21, v20
	v_sub_f32_e32 v20, -0.5, v20
	v_mul_f32_e32 v20, 0x3fb8aa3b, v20
	v_exp_f32_e32 v20, v20
	s_nop 0
	v_mul_f32_e32 v20, 0xbfb8aa3b, v20
	v_exp_f32_e32 v20, v20
	ds_write_b32 v24, v20 offset:10544
	v_add_f32_e32 v20, v23, v38
	v_mul_f32_e32 v20, 0xbfb8aa3b, v20
	v_exp_f32_e32 v20, v20
	s_nop 0
	v_add_f32_e32 v20, 1.0, v20
	v_rcp_f32_e32 v20, v20
	ds_write_b32 v24, v20 offset:43568
	v_or_b32_e32 v20, 0x70, v30
	v_ashrrev_i32_e32 v21, 31, v20
	v_lshlrev_b64 v[22:23], 7, v[20:21]
	v_lshl_add_u64 v[26:27], v[32:33], 0, v[22:23]
	v_lshl_add_u64 v[36:37], v[34:35], 0, v[22:23]
	global_load_dwordx4 v[22:25], v[26:27], off
	global_load_dwordx4 v[32:35], v[36:37], off
	s_waitcnt vmcnt(1)
	v_mfma_f32_16x16x32_bf16 v[12:15], v[12:15], v[22:25], 0
	v_add_lshl_u32 v2, v2, v20, 2
	s_waitcnt vmcnt(0)
	v_mfma_f32_16x16x32_bf16 v[16:19], v[16:19], v[32:35], 0
	global_load_dwordx4 v[22:25], v[26:27], off offset:64
	global_load_dwordx4 v[32:35], v[36:37], off offset:64
	s_waitcnt vmcnt(1)
	v_mfma_f32_16x16x32_bf16 v[12:15], v[4:7], v[22:25], v[12:15]
	s_waitcnt vmcnt(0)
	v_mfma_f32_16x16x32_bf16 v[4:7], v[8:11], v[32:35], v[16:19]
	global_load_dword v8, v[28:29], off offset:448
	s_nop 0
	global_load_dword v0, v[0:1], off offset:448
	s_waitcnt vmcnt(1)
	s_nop 1
	v_add_f32_e32 v1, v12, v8
	v_max_f32_e64 v9, -v1, 0
	v_mul_f32_e64 v1, |v1|, s36
	v_exp_f32_e32 v1, v1
	s_nop 0
	v_add_f32_e32 v1, 1.0, v1
	v_cmp_gt_f32_e32 vcc, s72, v1
	s_nop 1
	v_cndmask_b32_e64 v10, 0, 32, vcc
	v_ldexp_f32 v1, v1, v10
	v_log_f32_e32 v1, v1
	s_nop 0
	v_mul_f32_e32 v10, 0x3f317217, v1
	v_fma_f32 v10, v1, s33, -v10
	v_fmac_f32_e32 v10, 0x3377d1cf, v1
	v_fmac_f32_e32 v10, 0x3f317217, v1
	v_cmp_lt_f32_e64 s[40:41], |v1|, s34
	s_nop 1
	v_cndmask_b32_e64 v1, v1, v10, s[40:41]
	v_cndmask_b32_e32 v10, 0, v184, vcc
	v_sub_f32_e32 v1, v1, v10
	v_add_f32_e32 v1, v9, v1
	v_sub_f32_e32 v1, -0.5, v1
	v_mul_f32_e32 v1, 0x3fb8aa3b, v1
	v_exp_f32_e32 v1, v1
	s_nop 0
	v_mul_f32_e32 v1, 0xbfb8aa3b, v1
	v_exp_f32_e32 v1, v1
	ds_write_b32 v31, v1 offset:4800
	s_waitcnt vmcnt(0)
; __device__ __forceinline__ float sigmoidf_(float x) { return frcp_(1.f + __expf(-x)); }
; __device__ __forceinline__ float softplusf_(float x) { return fmaxf(x, 0.f) + __logf(1.f + __expf(-fabsf(x))); }
; __device__ __forceinline__ void prep_rwkv(const Params& p, int l, int item, char* smem) {
;     ...
; #pragma unroll
;     for (int jt = 0; jt < 8; ++jt) {
;       const int n = wave * 128 + jt * 16 + fr;
;       f32x4 cw = (f32x4){0.f, 0.f, 0.f, 0.f}, ca = (f32x4){0.f, 0.f, 0.f, 0.f};
; #pragma unroll
;       for (int ks = 0; ks < 2; ++ks) {
;         const bf16x8 bw = *(const bf16x8*)(W2T + (size_t)n * 64 + ks * 32 + fq);
;         const bf16x8 ba = *(const bf16x8*)(A2T + (size_t)n * 64 + ks * 32 + fq);
;         cw = __builtin_amdgcn_mfma_f32_16x16x32_bf16(atw[ks], bw, cw, 0, 0, 0);
;         ca = __builtin_amdgcn_mfma_f32_16x16x32_bf16(aad[ks], ba, ca, 0, 0, 0);
;       }
;       const float w0v = w0[n], a0v = a0[n];
; #pragma unroll
;       for (int r = 0; r < 4; ++r) {
;         const int tok = (lane >> 4) * 4 + r;
;         const float wl = w0v + cw[r];
;         const float wv = -softplusf_(-wl) - 0.5f;
;         sW[tok * 516 + n] = __expf(-__expf(wv));
;         sAs[tok * 516 + n] = sigmoidf_(a0v + ca[r]);
;       }
;     }
;   }
;   __syncthreads();
;   {
;     const int chunk = tid & 127, ch4 = chunk * 4, head = chunk >> 4;
	v_add_f32_e32 v1, v4, v0
	v_mul_f32_e32 v1, 0xbfb8aa3b, v1
	v_exp_f32_e32 v1, v1
	s_nop 0
	v_add_f32_e32 v1, 1.0, v1
	v_rcp_f32_e32 v1, v1
	ds_write_b32 v31, v1 offset:37824
	v_add_f32_e32 v1, v13, v8
	v_max_f32_e64 v4, -v1, 0
	v_mul_f32_e64 v1, |v1|, s36
	v_exp_f32_e32 v1, v1
	s_nop 0
	v_add_f32_e32 v1, 1.0, v1
	v_cmp_gt_f32_e32 vcc, s72, v1
	s_nop 1
	v_cndmask_b32_e64 v9, 0, 32, vcc
	v_ldexp_f32 v1, v1, v9
	v_log_f32_e32 v1, v1
	s_nop 0
	v_mul_f32_e32 v9, 0x3f317217, v1
	v_fma_f32 v9, v1, s33, -v9
	v_fmac_f32_e32 v9, 0x3377d1cf, v1
	v_fmac_f32_e32 v9, 0x3f317217, v1
	v_cmp_lt_f32_e64 s[40:41], |v1|, s34
	s_nop 1
	v_cndmask_b32_e64 v1, v1, v9, s[40:41]
	v_cndmask_b32_e32 v9, 0, v184, vcc
	v_sub_f32_e32 v1, v1, v9
	v_add_f32_e32 v1, v4, v1
	v_sub_f32_e32 v1, -0.5, v1
	v_mul_f32_e32 v1, 0x3fb8aa3b, v1
	v_exp_f32_e32 v1, v1
	s_nop 0
	v_mul_f32_e32 v1, 0xbfb8aa3b, v1
	v_exp_f32_e32 v1, v1
	ds_write_b32 v2, v1 offset:6416
	v_add_f32_e32 v1, v5, v0
	v_mul_f32_e32 v1, 0xbfb8aa3b, v1
	v_exp_f32_e32 v1, v1
	s_nop 0
	v_add_f32_e32 v1, 1.0, v1
	v_rcp_f32_e32 v1, v1
	ds_write_b32 v2, v1 offset:39440
	v_add_f32_e32 v1, v14, v8
	v_max_f32_e64 v4, -v1, 0
	v_mul_f32_e64 v1, |v1|, s36
	v_exp_f32_e32 v1, v1
	s_nop 0
	v_add_f32_e32 v1, 1.0, v1
	v_cmp_gt_f32_e32 vcc, s72, v1
	s_nop 1
	v_cndmask_b32_e64 v5, 0, 32, vcc
	v_ldexp_f32 v1, v1, v5
	v_log_f32_e32 v1, v1
	s_nop 0
	v_mul_f32_e32 v5, 0x3f317217, v1
	v_fma_f32 v5, v1, s33, -v5
	v_fmac_f32_e32 v5, 0x3377d1cf, v1
	v_fmac_f32_e32 v5, 0x3f317217, v1
	v_cmp_lt_f32_e64 s[40:41], |v1|, s34
	s_nop 1
	v_cndmask_b32_e64 v1, v1, v5, s[40:41]
	v_cndmask_b32_e32 v5, 0, v184, vcc
	v_sub_f32_e32 v1, v1, v5
	v_add_f32_e32 v1, v4, v1
	v_sub_f32_e32 v1, -0.5, v1
	v_mul_f32_e32 v1, 0x3fb8aa3b, v1
	v_exp_f32_e32 v1, v1
	s_nop 0
	v_mul_f32_e32 v1, 0xbfb8aa3b, v1
	v_exp_f32_e32 v1, v1
	ds_write_b32 v2, v1 offset:8480
	v_add_f32_e32 v1, v6, v0
	v_mul_f32_e32 v1, 0xbfb8aa3b, v1
	v_exp_f32_e32 v1, v1
	v_add_f32_e32 v0, v7, v0
	v_mul_f32_e32 v0, 0xbfb8aa3b, v0
	v_exp_f32_e32 v0, v0
	v_add_f32_e32 v1, 1.0, v1
	v_rcp_f32_e32 v1, v1
	v_add_f32_e32 v0, 1.0, v0
	v_rcp_f32_e32 v0, v0
	ds_write_b32 v2, v1 offset:41504
	v_add_f32_e32 v1, v15, v8
	v_max_f32_e64 v4, -v1, 0
	v_mul_f32_e64 v1, |v1|, s36
	v_exp_f32_e32 v1, v1
	ds_write_b32 v2, v0 offset:43568
	v_and_b32_e32 v0, 0x7f, v58
	v_add_f32_e32 v1, 1.0, v1
	v_cmp_gt_f32_e32 vcc, s72, v1
	s_nop 1
	v_cndmask_b32_e64 v5, 0, 32, vcc
	v_ldexp_f32 v1, v1, v5
	v_log_f32_e32 v1, v1
	s_nop 0
	v_mul_f32_e32 v5, 0x3f317217, v1
	v_fma_f32 v5, v1, s33, -v5
	v_fmac_f32_e32 v5, 0x3377d1cf, v1
	v_fmac_f32_e32 v5, 0x3f317217, v1
	v_cmp_lt_f32_e64 s[40:41], |v1|, s34
	s_nop 1
	v_cndmask_b32_e64 v1, v1, v5, s[40:41]
	v_cndmask_b32_e32 v5, 0, v184, vcc
	v_sub_f32_e32 v1, v1, v5
	v_add_f32_e32 v1, v4, v1
	v_sub_f32_e32 v1, -0.5, v1
	v_mul_f32_e32 v1, 0x3fb8aa3b, v1
	v_exp_f32_e32 v1, v1
	s_nop 0
	v_mul_f32_e32 v1, 0xbfb8aa3b, v1
	v_exp_f32_e32 v1, v1
	ds_write_b32 v2, v1 offset:10544
	v_lshlrev_b32_e32 v1, 4, v0
	s_waitcnt lgkmcnt(0)
	s_barrier
; __device__ __forceinline__ float bflo(unsigned u) { return __uint_as_float(u << 16); }
; __device__ __forceinline__ float bfhi(unsigned u) { return __uint_as_float(u & 0xffff0000u); }
; __device__ __forceinline__ void prep_rwkv(const Params& p, int l, int item, char* smem) {
;     ...
;   {
;     const int chunk = tid & 127, ch4 = chunk * 4, head = chunk >> 4;
;     const float4 mur = *(const float4*)(mu + ch4), muk = *(const float4*)(mu + 512 + ch4), muv = *(const float4*)(mu + 1024 + ch4);
;     const float4 kkc = *(const float4*)(p.in[16] + (size_t)l * 512 + ch4);
;     const float4 kac = *(const float4*)(p.in[17] + (size_t)l * 512 + ch4);
;     const float4 rkc = *(const float4*)(p.in[18] + (size_t)l * 512 + ch4);
; #pragma unroll
;     for (int i = 0; i < 8; ++i) {
;       const int tok = (tid >> 7) + 2 * i;
;       const int row = row0 + tok;
;       int seq, t; row_to_seq(row, seq, t);
;       const uint2 pr_ = *(const uint2*)(PRE + (size_t)row * PRE_W + ch4);
;       const uint2 pk_ = *(const uint2*)(PRE + (size_t)row * PRE_W + 512 + ch4);
;       const uint2 pv_ = *(const uint2*)(PRE + (size_t)row * PRE_W + 1024 + ch4);
;       float4 qr, qk, qv;
;       if (t > 0) {
;         const uint2 a_ = *(const uint2*)(PRE + (size_t)(row - 1) * PRE_W + ch4);
;         const uint2 b_ = *(const uint2*)(PRE + (size_t)(row - 1) * PRE_W + 512 + ch4);
;         const uint2 c_ = *(const uint2*)(PRE + (size_t)(row - 1) * PRE_W + 1024 + ch4);
;         qr = make_float4(bflo(a_.x), bfhi(a_.x), bflo(a_.y), bfhi(a_.y));
;         qk = make_float4(bflo(b_.x), bfhi(b_.x), bflo(b_.y), bfhi(b_.y));
;         qv = make_float4(bflo(c_.x), bfhi(c_.x), bflo(c_.y), bfhi(c_.y));
;       } else if (seq >= 8) {
;         const float* sh = shift_in + (size_t)(seq - 8) * 1664;
;         qr = *(const float4*)(sh + ch4); qk = *(const float4*)(sh + 512 + ch4); qv = *(const float4*)(sh + 1024 + ch4);
	global_load_dwordx4 v[12:15], v1, s[90:91]
	global_load_dwordx4 v[4:7], v1, s[0:1]
	global_load_dwordx4 v[16:19], v1, s[90:91] offset:2048
	v_readlane_b32 s0, v240, 15
	v_readlane_b32 s1, v240, 16
	s_nop 4
	global_load_dwordx4 v[20:23], v1, s[0:1]
	v_readlane_b32 s0, v240, 17
	v_readlane_b32 s1, v240, 18
	s_nop 4
	global_load_dwordx4 v[24:27], v1, s[0:1]
	v_readlane_b32 s0, v240, 19
	v_readlane_b32 s1, v240, 20
	s_nop 4
	global_load_dwordx4 v[8:11], v1, s[0:1]
	s_movk_i32 s0, 0x407f
	v_cmp_lt_i32_e32 vcc, s0, v50
	s_and_saveexec_b64 s[16:17], vcc
	s_xor_b64 s[16:17], exec, s[16:17]
	v_add_u32_e32 v28, 0xffffbf88, v50
	s_or_saveexec_b64 s[38:39], s[16:17]
	s_mov_b64 s[16:17], 0
	s_xor_b64 exec, exec, s[38:39]
	s_mov_b32 s0, 0xfe03f81
	v_mul_hi_i32 v1, v50, s0
	v_lshrrev_b32_e32 v2, 31, v1
	v_ashrrev_i32_e32 v1, 7, v1
	v_add_u32_e32 v28, v1, v2
	s_movk_i32 s0, 0xf7f0
	v_mad_i32_i24 v1, v28, s0, v50
	v_cmp_lt_i32_e32 vcc, 0, v1
	s_and_b64 s[16:17], vcc, exec
	s_or_b64 exec, exec, s[38:39]
	v_lshlrev_b32_e32 v1, 2, v0
	v_mov_b64_e32 v[30:31], s[2:3]
	s_movk_i32 s0, 0x2200
	v_mad_i64_i32 v[30:31], s[26:27], v50, s0, v[30:31]
	v_lshlrev_b32_e32 v2, 1, v1
	v_lshl_add_u64 v[30:31], v[30:31], 0, v[2:3]
	global_load_dwordx2 v[88:89], v[30:31], off
	global_load_dwordx2 v[90:91], v[30:31], off offset:1024
	global_load_dwordx2 v[92:93], v[30:31], off offset:2048
	v_add_co_u32_e32 v196, vcc, 0xffffde00, v30
	s_nop 1
	v_addc_co_u32_e32 v197, vcc, -1, v31, vcc
	global_load_dwordx2 v[136:137], v[196:197], off
	global_load_dwordx2 v[138:139], v[196:197], off offset:1024
	global_load_dwordx2 v[140:141], v[196:197], off offset:2048
	v_mov_b32_e32 v194, v30
	v_mov_b32_e32 v195, v31
	v_add_co_u32_e32 v194, vcc, 0x4400, v194
	s_nop 1
	v_addc_co_u32_e32 v195, vcc, 0, v195, vcc
	v_add_co_u32_e32 v196, vcc, 0x4400, v196
	s_nop 1
	v_addc_co_u32_e32 v197, vcc, 0, v197, vcc
	global_load_dwordx2 v[94:95], v[194:195], off
	global_load_dwordx2 v[96:97], v[194:195], off offset:1024
	global_load_dwordx2 v[98:99], v[194:195], off offset:2048
	global_load_dwordx2 v[142:143], v[196:197], off
	global_load_dwordx2 v[144:145], v[196:197], off offset:1024
	global_load_dwordx2 v[146:147], v[196:197], off offset:2048
	v_add_co_u32_e32 v194, vcc, 0x4400, v194
	s_nop 1
	v_addc_co_u32_e32 v195, vcc, 0, v195, vcc
	v_add_co_u32_e32 v196, vcc, 0x4400, v196
	s_nop 1
	v_addc_co_u32_e32 v197, vcc, 0, v197, vcc
	global_load_dwordx2 v[100:101], v[194:195], off
	global_load_dwordx2 v[102:103], v[194:195], off offset:1024
	global_load_dwordx2 v[104:105], v[194:195], off offset:2048
	global_load_dwordx2 v[148:149], v[196:197], off
	global_load_dwordx2 v[150:151], v[196:197], off offset:1024
	global_load_dwordx2 v[152:153], v[196:197], off offset:2048
	v_add_co_u32_e32 v194, vcc, 0x4400, v194
	s_nop 1
	v_addc_co_u32_e32 v195, vcc, 0, v195, vcc
	v_add_co_u32_e32 v196, vcc, 0x4400, v196
	s_nop 1
	v_addc_co_u32_e32 v197, vcc, 0, v197, vcc
	global_load_dwordx2 v[106:107], v[194:195], off
	global_load_dwordx2 v[108:109], v[194:195], off offset:1024
	global_load_dwordx2 v[110:111], v[194:195], off offset:2048
	global_load_dwordx2 v[154:155], v[196:197], off
	global_load_dwordx2 v[156:157], v[196:197], off offset:1024
	global_load_dwordx2 v[158:159], v[196:197], off offset:2048
	v_add_co_u32_e32 v194, vcc, 0x4400, v194
	s_nop 1
	v_addc_co_u32_e32 v195, vcc, 0, v195, vcc
	v_add_co_u32_e32 v196, vcc, 0x4400, v196
	s_nop 1
	v_addc_co_u32_e32 v197, vcc, 0, v197, vcc
	global_load_dwordx2 v[112:113], v[194:195], off
	global_load_dwordx2 v[114:115], v[194:195], off offset:1024
	global_load_dwordx2 v[116:117], v[194:195], off offset:2048
	global_load_dwordx2 v[160:161], v[196:197], off
	global_load_dwordx2 v[162:163], v[196:197], off offset:1024
	global_load_dwordx2 v[164:165], v[196:197], off offset:2048
	v_add_co_u32_e32 v194, vcc, 0x4400, v194
	s_nop 1
	v_addc_co_u32_e32 v195, vcc, 0, v195, vcc
	v_add_co_u32_e32 v196, vcc, 0x4400, v196
	s_nop 1
	v_addc_co_u32_e32 v197, vcc, 0, v197, vcc
	global_load_dwordx2 v[118:119], v[194:195], off
	global_load_dwordx2 v[120:121], v[194:195], off offset:1024
	global_load_dwordx2 v[122:123], v[194:195], off offset:2048
	global_load_dwordx2 v[166:167], v[196:197], off
	global_load_dwordx2 v[168:169], v[196:197], off offset:1024
	global_load_dwordx2 v[170:171], v[196:197], off offset:2048
	v_add_co_u32_e32 v194, vcc, 0x4400, v194
	s_nop 1
	v_addc_co_u32_e32 v195, vcc, 0, v195, vcc
	v_add_co_u32_e32 v196, vcc, 0x4400, v196
	s_nop 1
	v_addc_co_u32_e32 v197, vcc, 0, v197, vcc
	global_load_dwordx2 v[124:125], v[194:195], off
	global_load_dwordx2 v[126:127], v[194:195], off offset:1024
	global_load_dwordx2 v[128:129], v[194:195], off offset:2048
	global_load_dwordx2 v[172:173], v[196:197], off
	global_load_dwordx2 v[174:175], v[196:197], off offset:1024
	global_load_dwordx2 v[176:177], v[196:197], off offset:2048
	v_add_co_u32_e32 v194, vcc, 0x4400, v194
	s_nop 1
	v_addc_co_u32_e32 v195, vcc, 0, v195, vcc
	v_add_co_u32_e32 v196, vcc, 0x4400, v196
	s_nop 1
	v_addc_co_u32_e32 v197, vcc, 0, v197, vcc
	global_load_dwordx2 v[130:131], v[194:195], off
	global_load_dwordx2 v[132:133], v[194:195], off offset:1024
	global_load_dwordx2 v[134:135], v[194:195], off offset:2048
	global_load_dwordx2 v[198:199], v[196:197], off
	global_load_dwordx2 v[200:201], v[196:197], off offset:1024
	global_load_dwordx2 v[202:203], v[196:197], off offset:2048
	s_waitcnt vmcnt(0)
	v_mov_b32_e32 v54, v88
	v_mov_b32_e32 v55, v89
	v_mov_b32_e32 v46, v90
	v_mov_b32_e32 v47, v91
	v_mov_b32_e32 v44, v92
	v_mov_b32_e32 v45, v93
	s_xor_b64 s[16:17], s[16:17], -1
	s_and_saveexec_b64 s[26:27], s[16:17]
	s_xor_b64 s[16:17], exec, s[26:27]
	s_cbranch_execz .LBB0_468
	v_cmp_lt_i32_e32 vcc, 7, v28
	v_mov_b32_e32 v39, 0
	v_mov_b32_e32 v57, 0
	v_mov_b32_e32 v38, 0
	v_mov_b32_e32 v56, 0
	v_mov_b32_e32 v37, 0
	v_mov_b32_e32 v36, 0
	v_mov_b32_e32 v31, 0
	v_mov_b32_e32 v30, 0
	v_mov_b32_e32 v53, 0
	v_mov_b32_e32 v52, 0
	v_mov_b32_e32 v35, 0
	v_mov_b32_e32 v34, 0
	s_and_saveexec_b64 s[38:39], vcc
	s_cbranch_execz .LBB0_467
	v_add_u32_e32 v30, -8, v28
	v_mov_b64_e32 v[28:29], s[28:29]
	s_movk_i32 s0, 0x1a00
	v_mad_u64_u32 v[28:29], s[26:27], v30, s0, v[28:29]
	v_lshlrev_b32_e32 v30, 2, v1
	v_mov_b32_e32 v31, v3
	v_lshl_add_u64 v[28:29], v[28:29], 0, v[30:31]
	global_load_dwordx4 v[32:35], v[28:29], off
	global_load_dwordx4 v[36:39], v[28:29], off offset:2048
	v_add_co_u32_e32 v28, vcc, 0x1000, v28
	s_waitcnt vmcnt(1)
	v_mov_b32_e32 v53, v34
	v_addc_co_u32_e32 v29, vcc, 0, v29, vcc
	global_load_dwordx4 v[28:31], v[28:29], off
	s_waitcnt vmcnt(1)
	v_mov_b32_e32 v57, v38
	v_mov_b32_e32 v38, v37
	v_mov_b32_e32 v56, v36
	v_mov_b32_e32 v52, v32
	v_mov_b32_e32 v34, v33
	s_waitcnt vmcnt(0)
	v_mov_b32_e32 v37, v30
	v_mov_b32_e32 v36, v28
	v_mov_b32_e32 v30, v29

; __device__ __forceinline__ void prep_rwkv(const Params& p, int l, int item, char* smem) {
;     ...
;       if (t > 0) {
;         const uint2 a_ = *(const uint2*)(PRE + (size_t)(row - 1) * PRE_W + ch4);
;         const uint2 b_ = *(const uint2*)(PRE + (size_t)(row - 1) * PRE_W + 512 + ch4);
;         const uint2 c_ = *(const uint2*)(PRE + (size_t)(row - 1) * PRE_W + 1024 + ch4);
;         qr = make_float4(bflo(a_.x), bfhi(a_.x), bflo(a_.y), bfhi(a_.y));
;         qk = make_float4(bflo(b_.x), bfhi(b_.x), bflo(b_.y), bfhi(b_.y));
;         qv = make_float4(bflo(c_.x), bfhi(c_.x), bflo(c_.y), bfhi(c_.y));
;       } else if (seq >= 8) {
;         const float* sh = shift_in + (size_t)(seq - 8) * 1664;
;         qr = *(const float4*)(sh + ch4); qk = *(const float4*)(sh + 512 + ch4); qv = *(const float4*)(sh + 1024 + ch4);
;       } else {
;         qr = qk = qv = make_float4(0.f, 0.f, 0.f, 0.f);
;       }
;       const float4 dec = *(const float4*)(sW + tok * 516 + ch4);
;       const float4 as = *(const float4*)(sAs + tok * 516 + ch4);
;       const float pr4[4] = {bflo(pr_.x), bfhi(pr_.x), bflo(pr_.y), bfhi(pr_.y)};
;       const float pk4[4] = {bflo(pk_.x), bfhi(pk_.x), bflo(pk_.y), bfhi(pk_.y)};
;       const float pv4[4] = {bflo(pv_.x), bfhi(pv_.x), bflo(pv_.y), bfhi(pv_.y)};
;       const float qr4[4] = {qr.x, qr.y, qr.z, qr.w}, qk4[4] = {qk.x, qk.y, qk.z, qk.w}, qv4[4] = {qv.x, qv.y, qv.z, qv.w};
;       const float mr4[4] = {mur.x, mur.y, mur.z, mur.w}, mk4[4] = {muk.x, muk.y, muk.z, muk.w}, mv4[4] = {muv.x, muv.y, muv.z, muv.w};
;       const float kk4[4] = {kkc.x, kkc.y, kkc.z, kkc.w}, ka4[4] = {kac.x, kac.y, kac.z, kac.w}, rk4[4] = {rkc.x, rkc.y, rkc.z, rkc.w};
;       const float de4[4] = {dec.x, dec.y, dec.z, dec.w}, as4[4] = {as.x, as.y, as.z, as.w};
;       float r[4], kx[4], v[4], kkr[4];
;       float ssq = 0.f;
; #pragma unroll
;       for (int j = 0; j < 4; ++j) {
;         r[j] = pr4[j] + (qr4[j] - pr4[j]) * mr4[j];
;         kx[j] = pk4[j] + (qk4[j] - pk4[j]) * mk4[j];
;         v[j] = pv4[j] + (qv4[j] - pv4[j]) * mv4[j];
;         kkr[j] = kx[j] * kk4[j];
;         ssq += kkr[j] * kkr[j];
;       }
;       ssq = red16(ssq);
;       const float rn = rsqrtf(ssq + 1e-6f);
;       float fA[4], fWR[4], fB[4], fK[4];
;       float br = 0.f, kr = 0.f, rks = 0.f;
; #pragma unroll
;       for (int j = 0; j < 4; ++j) {
;         const float kk = kkr[j] * rn;
.LBB0_468:
	s_andn2_saveexec_b64 s[16:17], s[16:17]
	s_cbranch_execz .LBB0_470
	v_add_u32_e32 v30, -1, v50
	v_mov_b64_e32 v[28:29], s[2:3]
	s_movk_i32 s0, 0x2200
	v_mad_i64_i32 v[28:29], s[26:27], v30, s0, v[28:29]
	v_lshl_add_u64 v[28:29], v[28:29], 0, v[2:3]
	v_mov_b32_e32 v30, v140
	v_mov_b32_e32 v31, v141
	v_mov_b32_e32 v32, v136
	v_mov_b32_e32 v33, v137
	s_nop 0
	v_mov_b32_e32 v28, v138
	v_mov_b32_e32 v29, v139
	v_lshlrev_b32_e32 v36, 16, v30
	v_lshlrev_b32_e32 v52, 16, v32
	v_lshlrev_b32_e32 v53, 16, v33
	v_and_b32_e32 v35, 0xffff0000, v33
	v_and_b32_e32 v34, 0xffff0000, v32
	v_lshlrev_b32_e32 v56, 16, v28
	v_and_b32_e32 v38, 0xffff0000, v28
	v_lshlrev_b32_e32 v57, 16, v29
	v_and_b32_e32 v39, 0xffff0000, v29
	v_lshlrev_b32_e32 v37, 16, v31
	v_and_b32_e32 v31, 0xffff0000, v31
	v_and_b32_e32 v30, 0xffff0000, v30
.LBB0_470:
	s_or_b64 exec, exec, s[16:17]
	v_readlane_b32 s0, v241, 11
	v_lshlrev_b32_e32 v48, 2, v1
	v_mov_b32_e32 v49, v3
	v_readlane_b32 s1, v241, 12
	v_readlane_b32 s16, v243, 14
	v_and_b32_e32 v0, 0x7c, v0
	v_lshl_add_u64 v[42:43], s[0:1], 0, v[48:49]
	v_mov_b32_e32 v1, v3
	v_readlane_b32 s17, v243, 15
	s_movk_i32 s0, 0x810
	v_ashrrev_i32_e32 v51, 31, v50
	v_lshl_add_u64 v[0:1], s[16:17], 0, v[0:1]
	v_mad_u64_u32 v[28:29], s[16:17], v60, s0, v[48:49]
	ds_read_b128 v[62:65], v28 offset:37376
	ds_read_b128 v[66:69], v28 offset:4352
	v_lshlrev_b32_e32 v71, 16, v47
	v_lshlrev_b32_e32 v70, 16, v46
	v_and_b32_e32 v73, 0xffff0000, v47
	v_and_b32_e32 v72, 0xffff0000, v46
	v_lshlrev_b32_e32 v75, 16, v45
	v_lshlrev_b32_e32 v74, 16, v44
	v_and_b32_e32 v77, 0xffff0000, v45
	v_and_b32_e32 v76, 0xffff0000, v44
	v_lshlrev_b64 v[44:45], 11, v[50:51]
	v_lshl_add_u64 v[84:85], v[42:43], 0, v[44:45]
	v_pk_add_f32 v[46:47], v[56:57], v[70:71] neg_lo:[0,1] neg_hi:[0,1]
	v_mov_b32_e32 v44, v16
	v_mov_b32_e32 v45, v18
	v_pk_add_f32 v[38:39], v[38:39], v[72:73] neg_lo:[0,1] neg_hi:[0,1]
	v_mov_b32_e32 v18, v17
	s_waitcnt lgkmcnt(1)
	v_add_f32_e32 v28, -1.0, v62
	v_pk_fma_f32 v[56:57], v[44:45], v[46:47], v[70:71]
	v_mov_b32_e32 v46, v20
	v_mov_b32_e32 v47, v22
	v_pk_fma_f32 v[16:17], v[18:19], v[38:39], v[72:73]
	v_mov_b32_e32 v22, v21
	v_fma_f32 v29, v24, v28, 1.0
	v_add_f32_e32 v28, -1.0, v63
	v_pk_mul_f32 v[70:71], v[46:47], v[56:57]
	v_pk_mul_f32 v[20:21], v[22:23], v[16:17]
	v_fma_f32 v79, v25, v28, 1.0
	v_add_f32_e32 v28, -1.0, v64
	v_mov_b32_e32 v38, v70
	v_mov_b32_e32 v39, v20
	v_fma_f32 v81, v26, v28, 1.0
	v_add_f32_e32 v28, -1.0, v65
	v_pk_mul_f32 v[38:39], v[38:39], v[38:39]
	v_mov_b32_e32 v72, v71
	v_mov_b32_e32 v73, v21
	v_fma_f32 v83, v27, v28, 1.0
	v_pk_mul_f32 v[72:73], v[72:73], v[72:73]
	v_add_f32_e32 v28, v38, v39
	v_add_f32_e32 v28, v28, v72
	v_add_f32_e32 v28, v28, v73
	s_waitcnt lgkmcnt(0)
	global_store_dwordx4 v[84:85], v[66:69], off
	v_mov_b32_e32 v87, v56
	v_add_f32_dpp v28, v28, v28 quad_perm:[1,0,3,2] row_mask:0xf bank_mask:0xf bound_ctrl:1
	v_mov_b32_e32 v78, v63
	v_cmp_eq_u32_e64 s[40:41], 0, v59
	v_add_f32_dpp v28, v28, v28 quad_perm:[2,3,0,1] row_mask:0xf bank_mask:0xf bound_ctrl:1
	v_mov_b32_e32 v80, v64
	v_mov_b32_e32 v82, v65
	v_add_f32_dpp v28, v28, v28 row_half_mirror row_mask:0xf bank_mask:0xf bound_ctrl:1
	v_lshl_add_u64 v[40:41], s[74:75], 0, v[2:3]
	s_movk_i32 s0, 0x1400
	v_add_f32_dpp v28, v28, v28 row_mirror row_mask:0xf bank_mask:0xf bound_ctrl:1
	v_add_f32_e32 v28, 0x358637bd, v28
	v_mul_f32_e32 v38, 0x4b800000, v28
	v_cmp_gt_f32_e32 vcc, s72, v28
	v_lshlrev_b32_e32 v33, 16, v55
	v_lshlrev_b32_e32 v32, 16, v54
	v_cndmask_b32_e32 v28, v28, v38, vcc
	v_rsq_f32_e32 v28, v28
	v_mad_i64_i32 v[38:39], s[16:17], v50, s0, v[40:41]
	v_and_b32_e32 v55, 0xffff0000, v55
	v_mul_f32_e32 v49, 0x45800000, v28
	v_cndmask_b32_e32 v72, v28, v49, vcc
	v_pk_mul_f32 v[70:71], v[70:71], v[72:73] op_sel_hi:[1,0] neg_lo:[0,1] neg_hi:[0,1]
	v_pk_mul_f32 v[20:21], v[20:21], v[72:73] op_sel_hi:[1,0] neg_lo:[0,1] neg_hi:[0,1]
	v_pk_add_f32 v[84:85], v[70:71], 0 neg_lo:[1,1] neg_hi:[1,1]
	v_mov_b32_e32 v28, v62
	v_mov_b32_e32 v86, v84
	v_pk_add_f32 v[62:63], v[20:21], 0 neg_lo:[1,1] neg_hi:[1,1]
	v_pk_mul_f32 v[28:29], v[28:29], v[86:87]
	v_mov_b32_e32 v72, v62
	v_mov_b32_e32 v73, v16
	v_and_b32_sdwa v56, v28, v183 dst_sel:DWORD dst_unused:UNUSED_PAD src0_sel:WORD_1 src1_sel:DWORD
	v_pk_mul_f32 v[72:73], v[78:79], v[72:73]
	v_add3_u32 v59, v28, v56, s37
	v_and_b32_sdwa v61, v72, v183 dst_sel:DWORD dst_unused:UNUSED_PAD src0_sel:WORD_1 src1_sel:DWORD
	v_mov_b32_e32 v56, v85
	v_mov_b32_e32 v16, v63
	v_pk_mul_f32 v[56:57], v[80:81], v[56:57]
	v_pk_mul_f32 v[62:63], v[82:83], v[16:17]
	v_add3_u32 v17, v72, v61, s37
	v_and_b32_sdwa v28, v73, v183 dst_sel:DWORD dst_unused:UNUSED_PAD src0_sel:WORD_1 src1_sel:DWORD
	v_and_b32_e32 v78, 0xffff0000, v17
	v_and_b32_sdwa v17, v56, v183 dst_sel:DWORD dst_unused:UNUSED_PAD src0_sel:WORD_1 src1_sel:DWORD
	v_add3_u32 v16, v73, v28, s37
	v_add3_u32 v56, v56, v17, s37
	v_and_b32_sdwa v17, v62, v183 dst_sel:DWORD dst_unused:UNUSED_PAD src0_sel:WORD_1 src1_sel:DWORD
	v_and_b32_e32 v79, 0xffff0000, v16
	v_and_b32_sdwa v16, v57, v183 dst_sel:DWORD dst_unused:UNUSED_PAD src0_sel:WORD_1 src1_sel:DWORD
	v_add3_u32 v17, v62, v17, s37
	v_add3_u32 v61, v57, v16, s37
	v_and_b32_sdwa v16, v63, v183 dst_sel:DWORD dst_unused:UNUSED_PAD src0_sel:WORD_1 src1_sel:DWORD
	v_and_b32_e32 v82, 0xffff0000, v17
	v_and_b32_sdwa v17, v70, v183 dst_sel:DWORD dst_unused:UNUSED_PAD src0_sel:WORD_1 src1_sel:DWORD
	v_add3_u32 v16, v63, v16, s37
	v_add3_u32 v28, v70, v17, s37
	v_and_b32_sdwa v17, v21, v183 dst_sel:DWORD dst_unused:UNUSED_PAD src0_sel:WORD_1 src1_sel:DWORD
	v_and_b32_sdwa v62, v20, v183 dst_sel:DWORD dst_unused:UNUSED_PAD src0_sel:WORD_1 src1_sel:DWORD
; __device__ __forceinline__ unsigned pack2(float a, float b) { return (unsigned)f2bf(a) | ((unsigned)f2bf(b) << 16); }
; __device__ __forceinline__ float rbf(float f) { return bf2f(f2bf(f)); }
; __device__ __forceinline__ float red16(float v) { v = red8(v); v += dppf<0x140>(v); return v; }
; __device__ __forceinline__ void prep_rwkv(const Params& p, int l, int item, char* smem) {
;     ...
;       float fA[4], fWR[4], fB[4], fK[4];
;       float br = 0.f, kr = 0.f, rks = 0.f;
; #pragma unroll
;       for (int j = 0; j < 4; ++j) {
;         const float kk = kkr[j] * rn;
;         const float kp = kx[j] * (1.f + (as4[j] - 1.f) * ka4[j]);
;         fA[j] = -kk; fWR[j] = de4[j] * r[j]; fB[j] = kk * as4[j]; fK[j] = kp;
;         br += rbf(fB[j]) * r[j];
;         kr += rbf(fK[j]) * r[j];
;         rks += r[j] * kp * rk4[j];
;       }
;       br = red16(br); kr = red16(kr); rks = red16(rks);
;       *(float4*)(RWW + (size_t)row * 512 + ch4) = dec;
;       bf16_t* d5 = RW5 + (size_t)row * 5 * 512 + ch4;
;       *(uint2*)(d5) = make_uint2(pack2(fA[0], fA[1]), pack2(fA[2], fA[3]));
;       *(uint2*)(d5 + 512) = make_uint2(pack2(fWR[0], fWR[1]), pack2(fWR[2], fWR[3]));
;       *(uint2*)(d5 + 1024) = make_uint2(pack2(fB[0], fB[1]), pack2(fB[2], fB[3]));
;       *(uint2*)(d5 + 1536) = make_uint2(pack2(fK[0], fK[1]), pack2(fK[2], fK[3]));
;       *(uint2*)(d5 + 2048) = make_uint2(pack2(v[0], v[1]), pack2(v[2], v[3]));
;       if ((chunk & 15) == 0) *(float4*)(RWSC + ((size_t)row * 8 + head) * 4) = make_float4(br, kr, rks, 0.f);
	v_and_b32_e32 v83, 0xffff0000, v16
	v_and_b32_sdwa v16, v71, v183 dst_sel:DWORD dst_unused:UNUSED_PAD src0_sel:WORD_1 src1_sel:DWORD
	v_add3_u32 v17, v21, v17, s37
	v_add3_u32 v20, v20, v62, s37
	v_add3_u32 v16, v71, v16, s37
	v_and_b32_e32 v17, 0xffff0000, v17
	v_and_b32_e32 v20, 0xffff0000, v20
	v_or_b32_sdwa v17, v17, v16 dst_sel:DWORD dst_unused:UNUSED_PAD src0_sel:DWORD src1_sel:WORD_1
	v_or_b32_sdwa v16, v20, v28 dst_sel:DWORD dst_unused:UNUSED_PAD src0_sel:DWORD src1_sel:WORD_1
	v_and_b32_e32 v54, 0xffff0000, v54
	global_store_dwordx2 v[38:39], v[16:17], off
	v_pk_add_f32 v[20:21], v[52:53], v[32:33] neg_lo:[0,1] neg_hi:[0,1]
	v_mov_b32_e32 v16, v12
	v_mov_b32_e32 v17, v14
	v_pk_fma_f32 v[20:21], v[16:17], v[20:21], v[32:33]
	v_pk_add_f32 v[32:33], v[34:35], v[54:55] neg_lo:[0,1] neg_hi:[0,1]
	v_mov_b32_e32 v14, v13
	v_pk_fma_f32 v[12:13], v[14:15], v[32:33], v[54:55]
	v_mov_b32_e32 v32, v66
	v_mov_b32_e32 v33, v68
	v_mul_f32_e32 v28, v20, v29
	v_and_b32_sdwa v49, v29, v183 dst_sel:DWORD dst_unused:UNUSED_PAD src0_sel:WORD_1 src1_sel:DWORD
	v_pk_mul_f32 v[34:35], v[20:21], v[32:33]
	v_fma_f32 v32, v8, v28, 0
	v_mul_f32_e32 v28, v12, v73
	v_add3_u32 v49, v29, v49, s37
	v_fmac_f32_e32 v32, v9, v28
	v_mul_f32_e32 v28, v21, v57
	v_and_b32_e32 v65, 0xffff0000, v49
	v_and_b32_e32 v64, 0xffff0000, v59
	v_fmac_f32_e32 v32, v10, v28
	v_mul_f32_e32 v28, v13, v63
	v_fmac_f32_e32 v32, v11, v28
	v_pk_fma_f32 v[28:29], v[20:21], v[64:65], 0 op_sel_hi:[0,1,0]
	v_and_b32_e32 v81, 0xffff0000, v61
	v_and_b32_e32 v80, 0xffff0000, v56
	v_pk_fma_f32 v[28:29], v[12:13], v[78:79], v[28:29] op_sel_hi:[0,1,1]
	v_mov_b32_e32 v68, v67
	v_pk_fma_f32 v[20:21], v[20:21], v[80:81], v[28:29] op_sel:[1,0,0]
	v_pk_mul_f32 v[52:53], v[12:13], v[68:69]
	v_pk_fma_f32 v[12:13], v[12:13], v[82:83], v[20:21] op_sel:[1,0,0]
	v_pk_add_f32 v[30:31], v[30:31], v[76:77] neg_lo:[0,1] neg_hi:[0,1]
	s_nop 0
	v_mov_b32_dpp v20, v12 quad_perm:[1,0,3,2] row_mask:0xf bank_mask:0xf bound_ctrl:1
	v_mov_b32_dpp v21, v13 quad_perm:[1,0,3,2] row_mask:0xf bank_mask:0xf bound_ctrl:1
	v_pk_add_f32 v[12:13], v[12:13], v[20:21]
	s_nop 1
	v_mov_b32_dpp v20, v12 quad_perm:[2,3,0,1] row_mask:0xf bank_mask:0xf bound_ctrl:1
	v_mov_b32_dpp v21, v13 quad_perm:[2,3,0,1] row_mask:0xf bank_mask:0xf bound_ctrl:1
	v_pk_add_f32 v[12:13], v[12:13], v[20:21]
	s_nop 1
	v_mov_b32_dpp v20, v12 row_half_mirror row_mask:0xf bank_mask:0xf bound_ctrl:1
	v_mov_b32_dpp v21, v13 row_half_mirror row_mask:0xf bank_mask:0xf bound_ctrl:1
	v_pk_add_f32 v[20:21], v[12:13], v[20:21]
	v_add_f32_dpp v12, v32, v32 quad_perm:[1,0,3,2] row_mask:0xf bank_mask:0xf bound_ctrl:1
	v_and_b32_sdwa v13, v34, v183 dst_sel:DWORD dst_unused:UNUSED_PAD src0_sel:WORD_1 src1_sel:DWORD
	v_add3_u32 v34, v34, v13, s37
	v_add_f32_dpp v12, v12, v12 quad_perm:[2,3,0,1] row_mask:0xf bank_mask:0xf bound_ctrl:1
	v_and_b32_sdwa v13, v53, v183 dst_sel:DWORD dst_unused:UNUSED_PAD src0_sel:WORD_1 src1_sel:DWORD
	v_add3_u32 v13, v53, v13, s37
	v_add_f32_dpp v32, v12, v12 row_half_mirror row_mask:0xf bank_mask:0xf bound_ctrl:1
	v_and_b32_sdwa v12, v35, v183 dst_sel:DWORD dst_unused:UNUSED_PAD src0_sel:WORD_1 src1_sel:DWORD
	v_add3_u32 v12, v35, v12, s37
	v_and_b32_sdwa v35, v52, v183 dst_sel:DWORD dst_unused:UNUSED_PAD src0_sel:WORD_1 src1_sel:DWORD
	v_add3_u32 v35, v52, v35, s37
	v_and_b32_e32 v13, 0xffff0000, v13
	v_and_b32_e32 v35, 0xffff0000, v35
	v_or_b32_sdwa v13, v13, v12 dst_sel:DWORD dst_unused:UNUSED_PAD src0_sel:DWORD src1_sel:WORD_1
	v_or_b32_sdwa v12, v35, v34 dst_sel:DWORD dst_unused:UNUSED_PAD src0_sel:DWORD src1_sel:WORD_1
	global_store_dwordx2 v[38:39], v[12:13], off offset:1024
	v_or_b32_sdwa v13, v82, v56 dst_sel:DWORD dst_unused:UNUSED_PAD src0_sel:DWORD src1_sel:WORD_1
	v_or_b32_sdwa v12, v78, v59 dst_sel:DWORD dst_unused:UNUSED_PAD src0_sel:DWORD src1_sel:WORD_1
	global_store_dwordx2 v[38:39], v[12:13], off offset:2048
	v_or_b32_sdwa v13, v83, v61 dst_sel:DWORD dst_unused:UNUSED_PAD src0_sel:DWORD src1_sel:WORD_1
	v_or_b32_sdwa v12, v79, v49 dst_sel:DWORD dst_unused:UNUSED_PAD src0_sel:DWORD src1_sel:WORD_1
	global_store_dwordx2 v[38:39], v[12:13], off offset:3072
	v_pk_add_f32 v[34:35], v[36:37], v[74:75] neg_lo:[0,1] neg_hi:[0,1]
	v_mov_b32_e32 v12, v4
	v_mov_b32_e32 v13, v6
	v_pk_fma_f32 v[34:35], v[12:13], v[34:35], v[74:75]
	v_mov_b32_e32 v6, v5
	v_pk_fma_f32 v[4:5], v[6:7], v[30:31], v[76:77]
	v_and_b32_sdwa v31, v34, v183 dst_sel:DWORD dst_unused:UNUSED_PAD src0_sel:WORD_1 src1_sel:DWORD
	v_and_b32_sdwa v30, v35, v183 dst_sel:DWORD dst_unused:UNUSED_PAD src0_sel:WORD_1 src1_sel:DWORD
	v_add3_u32 v31, v34, v31, s37
	v_and_b32_sdwa v34, v5, v183 dst_sel:DWORD dst_unused:UNUSED_PAD src0_sel:WORD_1 src1_sel:DWORD
	v_add3_u32 v30, v35, v30, s37
	v_and_b32_sdwa v35, v4, v183 dst_sel:DWORD dst_unused:UNUSED_PAD src0_sel:WORD_1 src1_sel:DWORD
	v_add3_u32 v5, v5, v34, s37
	v_add3_u32 v4, v4, v35, s37
	v_and_b32_e32 v5, 0xffff0000, v5
	v_and_b32_e32 v4, 0xffff0000, v4
	v_or_b32_sdwa v5, v5, v30 dst_sel:DWORD dst_unused:UNUSED_PAD src0_sel:DWORD src1_sel:WORD_1
	v_add_co_u32_e32 v30, vcc, 0x1000, v38
	v_mov_b32_dpp v28, v20 row_mirror row_mask:0xf bank_mask:0xf bound_ctrl:1
	v_mov_b32_dpp v29, v21 row_mirror row_mask:0xf bank_mask:0xf bound_ctrl:1
	v_mov_b32_dpp v33, v32 row_mirror row_mask:0xf bank_mask:0xf bound_ctrl:1
	v_or_b32_sdwa v4, v4, v31 dst_sel:DWORD dst_unused:UNUSED_PAD src0_sel:DWORD src1_sel:WORD_1
	v_addc_co_u32_e32 v31, vcc, 0, v39, vcc
	global_store_dwordx2 v[30:31], v[4:5], off
	s_and_saveexec_b64 s[16:17], s[40:41]
	s_cbranch_execz .LBB0_472
	v_lshlrev_b64 v[4:5], 7, v[50:51]
	v_lshl_add_u64 v[4:5], v[0:1], 0, v[4:5]
	v_add_f32_e32 v30, v32, v33
	v_pk_add_f32 v[28:29], v[20:21], v[28:29]
	v_mov_b32_e32 v31, v3
	global_store_dwordx4 v[4:5], v[28:31], off
; __device__ __forceinline__ float bflo(unsigned u) { return __uint_as_float(u << 16); }
; __device__ __forceinline__ float bfhi(unsigned u) { return __uint_as_float(u & 0xffff0000u); }
; __device__ __forceinline__ void prep_rwkv(const Params& p, int l, int item, char* smem) {
;     ...
;       const int tok = (tid >> 7) + 2 * i;
;       const int row = row0 + tok;
;       int seq, t; row_to_seq(row, seq, t);
;       const uint2 pr_ = *(const uint2*)(PRE + (size_t)row * PRE_W + ch4);
;       const uint2 pk_ = *(const uint2*)(PRE + (size_t)row * PRE_W + 512 + ch4);
;       const uint2 pv_ = *(const uint2*)(PRE + (size_t)row * PRE_W + 1024 + ch4);
;       float4 qr, qk, qv;
;       if (t > 0) {
;         const uint2 a_ = *(const uint2*)(PRE + (size_t)(row - 1) * PRE_W + ch4);
;         const uint2 b_ = *(const uint2*)(PRE + (size_t)(row - 1) * PRE_W + 512 + ch4);
;         const uint2 c_ = *(const uint2*)(PRE + (size_t)(row - 1) * PRE_W + 1024 + ch4);
;         qr = make_float4(bflo(a_.x), bfhi(a_.x), bflo(a_.y), bfhi(a_.y));
;         qk = make_float4(bflo(b_.x), bfhi(b_.x), bflo(b_.y), bfhi(b_.y));
;         qv = make_float4(bflo(c_.x), bfhi(c_.x), bflo(c_.y), bfhi(c_.y));
;       } else if (seq >= 8) {
;         const float* sh = shift_in + (size_t)(seq - 8) * 1664;
;         qr = *(const float4*)(sh + ch4); qk = *(const float4*)(sh + 512 + ch4); qv = *(const float4*)(sh + 1024 + ch4);
;       } else {
;         qr = qk = qv = make_float4(0.f, 0.f, 0.f, 0.f);
.LBB0_472:
	s_or_b64 exec, exec, s[16:17]
	v_add_u32_e32 v59, 2, v60
	v_add_u32_e32 v4, s23, v59
	s_movk_i32 s0, 0x407f
	v_cmp_lt_i32_e32 vcc, s0, v4
	s_and_saveexec_b64 s[16:17], vcc
	s_xor_b64 s[16:17], exec, s[16:17]
	v_add_u32_e32 v5, 0xffffbf88, v4
	s_or_saveexec_b64 s[16:17], s[16:17]
	s_mov_b64 s[38:39], 0
	s_xor_b64 exec, exec, s[16:17]
	s_mov_b32 s0, 0xfe03f81
	v_mul_hi_i32 v5, v4, s0
	v_lshrrev_b32_e32 v20, 31, v5
	v_ashrrev_i32_e32 v5, 7, v5
	v_add_u32_e32 v5, v5, v20
	s_movk_i32 s0, 0xf7f0
	v_mad_i32_i24 v20, v5, s0, v4
	v_cmp_lt_i32_e32 vcc, 0, v20
	s_and_b64 s[38:39], vcc, exec
	s_or_b64 exec, exec, s[16:17]
	v_mov_b64_e32 v[20:21], s[2:3]
	s_movk_i32 s0, 0x2200
	v_mad_i64_i32 v[20:21], s[16:17], v4, s0, v[20:21]
	v_lshl_add_u64 v[20:21], v[20:21], 0, v[2:3]
	v_mov_b32_e32 v54, v94
	v_mov_b32_e32 v55, v95
	v_mov_b32_e32 v52, v96
	v_mov_b32_e32 v53, v97
	v_mov_b32_e32 v50, v98
	v_mov_b32_e32 v51, v99
	s_xor_b64 s[16:17], s[38:39], -1
	s_and_saveexec_b64 s[26:27], s[16:17]
	s_xor_b64 s[16:17], exec, s[26:27]
	s_cbranch_execz .LBB0_480
	v_cmp_lt_i32_e32 vcc, 7, v5
	v_mov_b32_e32 v39, 0
	v_mov_b32_e32 v57, 0
	v_mov_b32_e32 v38, 0
	v_mov_b32_e32 v56, 0
	v_mov_b32_e32 v21, 0
	v_mov_b32_e32 v20, 0
	v_mov_b32_e32 v31, 0
	v_mov_b32_e32 v30, 0
	v_mov_b32_e32 v37, 0
	v_mov_b32_e32 v36, 0
	v_mov_b32_e32 v35, 0
	v_mov_b32_e32 v34, 0
	s_and_saveexec_b64 s[38:39], vcc
	s_cbranch_execz .LBB0_479
	v_add_u32_e32 v5, -8, v5
	v_mov_b64_e32 v[20:21], s[28:29]
	s_movk_i32 s0, 0x1a00
	v_mad_u64_u32 v[20:21], s[26:27], v5, s0, v[20:21]
	v_mov_b32_e32 v49, v3
	v_lshl_add_u64 v[20:21], v[20:21], 0, v[48:49]
	global_load_dwordx4 v[32:35], v[20:21], off
	global_load_dwordx4 v[36:39], v[20:21], off offset:2048
	v_add_co_u32_e32 v20, vcc, 0x1000, v20
	s_waitcnt vmcnt(0)
	v_mov_b32_e32 v57, v38
	v_addc_co_u32_e32 v21, vcc, 0, v21, vcc
	global_load_dwordx4 v[28:31], v[20:21], off
	v_mov_b32_e32 v38, v37
	v_mov_b32_e32 v56, v36
	v_mov_b32_e32 v37, v34
	v_mov_b32_e32 v36, v32
	v_mov_b32_e32 v34, v33
	s_waitcnt vmcnt(0)
	v_mov_b32_e32 v21, v30
	v_mov_b32_e32 v20, v28
	v_mov_b32_e32 v30, v29

; __device__ __forceinline__ void prep_rwkv(const Params& p, int l, int item, char* smem) {
;     ...
;       if (t > 0) {
;         const uint2 a_ = *(const uint2*)(PRE + (size_t)(row - 1) * PRE_W + ch4);
;         const uint2 b_ = *(const uint2*)(PRE + (size_t)(row - 1) * PRE_W + 512 + ch4);
;         const uint2 c_ = *(const uint2*)(PRE + (size_t)(row - 1) * PRE_W + 1024 + ch4);
;         qr = make_float4(bflo(a_.x), bfhi(a_.x), bflo(a_.y), bfhi(a_.y));
;         qk = make_float4(bflo(b_.x), bfhi(b_.x), bflo(b_.y), bfhi(b_.y));
;         qv = make_float4(bflo(c_.x), bfhi(c_.x), bflo(c_.y), bfhi(c_.y));
;       } else if (seq >= 8) {
;         const float* sh = shift_in + (size_t)(seq - 8) * 1664;
;         qr = *(const float4*)(sh + ch4); qk = *(const float4*)(sh + 512 + ch4); qv = *(const float4*)(sh + 1024 + ch4);
;       } else {
;         qr = qk = qv = make_float4(0.f, 0.f, 0.f, 0.f);
;       }
;       const float4 dec = *(const float4*)(sW + tok * 516 + ch4);
;       const float4 as = *(const float4*)(sAs + tok * 516 + ch4);
;       const float pr4[4] = {bflo(pr_.x), bfhi(pr_.x), bflo(pr_.y), bfhi(pr_.y)};
;       const float pk4[4] = {bflo(pk_.x), bfhi(pk_.x), bflo(pk_.y), bfhi(pk_.y)};
;       const float pv4[4] = {bflo(pv_.x), bfhi(pv_.x), bflo(pv_.y), bfhi(pv_.y)};
;       const float qr4[4] = {qr.x, qr.y, qr.z, qr.w}, qk4[4] = {qk.x, qk.y, qk.z, qk.w}, qv4[4] = {qv.x, qv.y, qv.z, qv.w};
;       const float mr4[4] = {mur.x, mur.y, mur.z, mur.w}, mk4[4] = {muk.x, muk.y, muk.z, muk.w}, mv4[4] = {muv.x, muv.y, muv.z, muv.w};
;       const float kk4[4] = {kkc.x, kkc.y, kkc.z, kkc.w}, ka4[4] = {kac.x, kac.y, kac.z, kac.w}, rk4[4] = {rkc.x, rkc.y, rkc.z, rkc.w};
;       const float de4[4] = {dec.x, dec.y, dec.z, dec.w}, as4[4] = {as.x, as.y, as.z, as.w};
;       float r[4], kx[4], v[4], kkr[4];
;       float ssq = 0.f;
; #pragma unroll
;       for (int j = 0; j < 4; ++j) {
;         r[j] = pr4[j] + (qr4[j] - pr4[j]) * mr4[j];
;         kx[j] = pk4[j] + (qk4[j] - pk4[j]) * mk4[j];
;         v[j] = pv4[j] + (qv4[j] - pv4[j]) * mv4[j];
;         kkr[j] = kx[j] * kk4[j];
;         ssq += kkr[j] * kkr[j];
;       }
;       ssq = red16(ssq);
;       const float rn = rsqrtf(ssq + 1e-6f);
;       float fA[4], fWR[4], fB[4], fK[4];
;       float br = 0.f, kr = 0.f, rks = 0.f;
; #pragma unroll
;       for (int j = 0; j < 4; ++j) {
;         const float kk = kkr[j] * rn;
.LBB0_480:
	s_andn2_saveexec_b64 s[16:17], s[16:17]
	s_cbranch_execz .LBB0_482
	v_add_u32_e32 v5, -1, v4
	v_mov_b64_e32 v[20:21], s[2:3]
	s_movk_i32 s0, 0x2200
	v_mad_i64_i32 v[20:21], s[26:27], v5, s0, v[20:21]
	v_lshl_add_u64 v[20:21], v[20:21], 0, v[2:3]
	v_mov_b32_e32 v28, v146
	v_mov_b32_e32 v29, v147
	v_mov_b32_e32 v30, v142
	v_mov_b32_e32 v31, v143
	s_nop 0
	v_mov_b32_e32 v20, v144
	v_mov_b32_e32 v21, v145
	v_lshlrev_b32_e32 v36, 16, v30
	v_lshlrev_b32_e32 v37, 16, v31
	v_and_b32_e32 v35, 0xffff0000, v31
	v_and_b32_e32 v34, 0xffff0000, v30
	v_lshlrev_b32_e32 v56, 16, v20
	v_and_b32_e32 v38, 0xffff0000, v20
	v_lshlrev_b32_e32 v57, 16, v21
	v_and_b32_e32 v39, 0xffff0000, v21
	v_lshlrev_b32_e32 v20, 16, v28
	v_lshlrev_b32_e32 v21, 16, v29
	v_and_b32_e32 v31, 0xffff0000, v29
	v_and_b32_e32 v30, 0xffff0000, v28
.LBB0_482:
	s_or_b64 exec, exec, s[16:17]
	s_movk_i32 s0, 0x810
	v_mad_u64_u32 v[28:29], s[16:17], v59, s0, v[48:49]
	ds_read_b128 v[62:65], v28 offset:37376
	v_lshlrev_b32_e32 v67, 16, v53
	v_lshlrev_b32_e32 v66, 16, v52
	v_and_b32_e32 v69, 0xffff0000, v53
	v_and_b32_e32 v68, 0xffff0000, v52
	v_pk_add_f32 v[56:57], v[56:57], v[66:67] neg_lo:[0,1] neg_hi:[0,1]
	v_pk_add_f32 v[38:39], v[38:39], v[68:69] neg_lo:[0,1] neg_hi:[0,1]
	v_lshlrev_b32_e32 v71, 16, v51
	v_lshlrev_b32_e32 v70, 16, v50
	v_and_b32_e32 v73, 0xffff0000, v51
	v_and_b32_e32 v72, 0xffff0000, v50
	ds_read_b128 v[50:53], v28 offset:4352
	s_waitcnt lgkmcnt(1)
	v_add_f32_e32 v28, -1.0, v62
	v_pk_fma_f32 v[56:57], v[44:45], v[56:57], v[66:67]
	v_pk_fma_f32 v[38:39], v[18:19], v[38:39], v[68:69]
	v_fma_f32 v29, v24, v28, 1.0
	v_add_f32_e32 v28, -1.0, v63
	v_pk_mul_f32 v[66:67], v[46:47], v[56:57]
	v_pk_mul_f32 v[68:69], v[22:23], v[38:39]
	v_fma_f32 v75, v25, v28, 1.0
	v_add_f32_e32 v28, -1.0, v64
	v_mov_b32_e32 v82, v66
	v_mov_b32_e32 v83, v68
	v_fma_f32 v77, v26, v28, 1.0
	v_add_f32_e32 v28, -1.0, v65
	v_pk_mul_f32 v[82:83], v[82:83], v[82:83]
	v_mov_b32_e32 v84, v67
	v_mov_b32_e32 v85, v69
	v_fma_f32 v79, v27, v28, 1.0
	v_pk_mul_f32 v[84:85], v[84:85], v[84:85]
	v_add_f32_e32 v28, v82, v83
	v_add_f32_e32 v28, v28, v84
	v_add_f32_e32 v28, v28, v85
	v_mov_b32_e32 v74, v63
	v_mov_b32_e32 v85, v56
	v_add_f32_dpp v28, v28, v28 quad_perm:[1,0,3,2] row_mask:0xf bank_mask:0xf bound_ctrl:1
	v_mov_b32_e32 v78, v65
	v_lshlrev_b32_e32 v33, 16, v55
	v_add_f32_dpp v28, v28, v28 quad_perm:[2,3,0,1] row_mask:0xf bank_mask:0xf bound_ctrl:1
	v_lshlrev_b32_e32 v32, 16, v54
	v_and_b32_e32 v55, 0xffff0000, v55
	v_add_f32_dpp v28, v28, v28 row_half_mirror row_mask:0xf bank_mask:0xf bound_ctrl:1
	v_and_b32_e32 v54, 0xffff0000, v54
	v_pk_add_f32 v[36:37], v[36:37], v[32:33] neg_lo:[0,1] neg_hi:[0,1]
	v_add_f32_dpp v28, v28, v28 row_mirror row_mask:0xf bank_mask:0xf bound_ctrl:1
	v_add_f32_e32 v28, 0x358637bd, v28
	v_mul_f32_e32 v49, 0x4b800000, v28
	v_cmp_gt_f32_e32 vcc, s72, v28
	v_pk_fma_f32 v[32:33], v[16:17], v[36:37], v[32:33]
	v_pk_add_f32 v[34:35], v[34:35], v[54:55] neg_lo:[0,1] neg_hi:[0,1]
	v_cndmask_b32_e32 v28, v28, v49, vcc
	v_rsq_f32_e32 v28, v28
	v_pk_fma_f32 v[34:35], v[14:15], v[34:35], v[54:55]
	v_ashrrev_i32_e32 v5, 31, v4
	v_lshlrev_b64 v[80:81], 11, v[4:5]
	v_mul_f32_e32 v49, 0x45800000, v28
	v_cndmask_b32_e32 v76, v28, v49, vcc
	v_pk_mul_f32 v[66:67], v[66:67], v[76:77] op_sel_hi:[1,0] neg_lo:[0,1] neg_hi:[0,1]
	v_mov_b32_e32 v28, v62
	v_pk_add_f32 v[82:83], v[66:67], 0 neg_lo:[1,1] neg_hi:[1,1]
	v_pk_mul_f32 v[62:63], v[68:69], v[76:77] op_sel_hi:[1,0] neg_lo:[0,1] neg_hi:[0,1]
	v_mov_b32_e32 v84, v82
	v_pk_add_f32 v[68:69], v[62:63], 0 neg_lo:[1,1] neg_hi:[1,1]
	v_pk_mul_f32 v[28:29], v[28:29], v[84:85]
	v_mov_b32_e32 v84, v68
	v_mov_b32_e32 v85, v38
	v_and_b32_sdwa v56, v28, v183 dst_sel:DWORD dst_unused:UNUSED_PAD src0_sel:WORD_1 src1_sel:DWORD
	v_pk_mul_f32 v[74:75], v[74:75], v[84:85]
	v_add3_u32 v59, v28, v56, s37
	v_and_b32_sdwa v61, v74, v183 dst_sel:DWORD dst_unused:UNUSED_PAD src0_sel:WORD_1 src1_sel:DWORD
	v_mov_b32_e32 v76, v64
	v_mov_b32_e32 v56, v83
	v_and_b32_sdwa v28, v75, v183 dst_sel:DWORD dst_unused:UNUSED_PAD src0_sel:WORD_1 src1_sel:DWORD
	v_pk_mul_f32 v[56:57], v[76:77], v[56:57]
	v_mov_b32_e32 v38, v69
	v_add3_u32 v61, v74, v61, s37
	v_pk_mul_f32 v[38:39], v[78:79], v[38:39]
	v_add3_u32 v28, v75, v28, s37
	v_and_b32_e32 v68, 0xffff0000, v61
	v_and_b32_sdwa v61, v56, v183 dst_sel:DWORD dst_unused:UNUSED_PAD src0_sel:WORD_1 src1_sel:DWORD
	v_and_b32_e32 v69, 0xffff0000, v28
	v_and_b32_sdwa v28, v57, v183 dst_sel:DWORD dst_unused:UNUSED_PAD src0_sel:WORD_1 src1_sel:DWORD
	v_add3_u32 v56, v56, v61, s37
	v_and_b32_sdwa v61, v38, v183 dst_sel:DWORD dst_unused:UNUSED_PAD src0_sel:WORD_1 src1_sel:DWORD
	v_add3_u32 v74, v57, v28, s37
	v_and_b32_sdwa v28, v39, v183 dst_sel:DWORD dst_unused:UNUSED_PAD src0_sel:WORD_1 src1_sel:DWORD
	v_add3_u32 v38, v38, v61, s37
	v_add3_u32 v28, v39, v28, s37
	v_and_b32_e32 v78, 0xffff0000, v38
	v_and_b32_sdwa v38, v66, v183 dst_sel:DWORD dst_unused:UNUSED_PAD src0_sel:WORD_1 src1_sel:DWORD
	v_and_b32_sdwa v61, v63, v183 dst_sel:DWORD dst_unused:UNUSED_PAD src0_sel:WORD_1 src1_sel:DWORD
	v_and_b32_e32 v79, 0xffff0000, v28
	v_and_b32_sdwa v28, v67, v183 dst_sel:DWORD dst_unused:UNUSED_PAD src0_sel:WORD_1 src1_sel:DWORD
	v_add3_u32 v38, v66, v38, s37
	v_and_b32_sdwa v66, v62, v183 dst_sel:DWORD dst_unused:UNUSED_PAD src0_sel:WORD_1 src1_sel:DWORD
	v_add3_u32 v61, v63, v61, s37
	v_add3_u32 v28, v67, v28, s37
	v_add3_u32 v62, v62, v66, s37
	v_and_b32_e32 v61, 0xffff0000, v61
	v_and_b32_e32 v62, 0xffff0000, v62
	v_or_b32_sdwa v63, v61, v28 dst_sel:DWORD dst_unused:UNUSED_PAD src0_sel:DWORD src1_sel:WORD_1
	v_mul_f32_e32 v28, v32, v29
	v_and_b32_sdwa v49, v29, v183 dst_sel:DWORD dst_unused:UNUSED_PAD src0_sel:WORD_1 src1_sel:DWORD
	v_or_b32_sdwa v62, v62, v38 dst_sel:DWORD dst_unused:UNUSED_PAD src0_sel:DWORD src1_sel:WORD_1
	v_fma_f32 v38, v8, v28, 0
	v_mul_f32_e32 v28, v34, v75
	v_add3_u32 v49, v29, v49, s37
	v_fmac_f32_e32 v38, v9, v28
	v_mul_f32_e32 v28, v33, v57
	v_and_b32_e32 v65, 0xffff0000, v49
	v_and_b32_e32 v64, 0xffff0000, v59
	v_fmac_f32_e32 v38, v10, v28
	v_mul_f32_e32 v28, v35, v39
	v_fmac_f32_e32 v38, v11, v28
	v_pk_fma_f32 v[28:29], v[32:33], v[64:65], 0 op_sel_hi:[0,1,0]
	v_lshl_add_u64 v[80:81], v[42:43], 0, v[80:81]
	v_and_b32_e32 v77, 0xffff0000, v74
	v_and_b32_e32 v76, 0xffff0000, v56
	s_waitcnt lgkmcnt(0)
; __device__ __forceinline__ void prep_rwkv(const Params& p, int l, int item, char* smem) {
;     ...
;       const int tok = (tid >> 7) + 2 * i;
;       const int row = row0 + tok;
;       int seq, t; row_to_seq(row, seq, t);
;       const uint2 pr_ = *(const uint2*)(PRE + (size_t)row * PRE_W + ch4);
;       const uint2 pk_ = *(const uint2*)(PRE + (size_t)row * PRE_W + 512 + ch4);
;       const uint2 pv_ = *(const uint2*)(PRE + (size_t)row * PRE_W + 1024 + ch4);
;       float4 qr, qk, qv;
;       if (t > 0) {
;         const uint2 a_ = *(const uint2*)(PRE + (size_t)(row - 1) * PRE_W + ch4);
;         const uint2 b_ = *(const uint2*)(PRE + (size_t)(row - 1) * PRE_W + 512 + ch4);
;         const uint2 c_ = *(const uint2*)(PRE + (size_t)(row - 1) * PRE_W + 1024 + ch4);
;         qr = make_float4(bflo(a_.x), bfhi(a_.x), bflo(a_.y), bfhi(a_.y));
;         qk = make_float4(bflo(b_.x), bfhi(b_.x), bflo(b_.y), bfhi(b_.y));
;         qv = make_float4(bflo(c_.x), bfhi(c_.x), bflo(c_.y), bfhi(c_.y));
;       } else if (seq >= 8) {
;         const float* sh = shift_in + (size_t)(seq - 8) * 1664;
;         qr = *(const float4*)(sh + ch4); qk = *(const float4*)(sh + 512 + ch4); qv = *(const float4*)(sh + 1024 + ch4);
;       } else {
;     ...
;       float fA[4], fWR[4], fB[4], fK[4];
;       float br = 0.f, kr = 0.f, rks = 0.f;
; #pragma unroll
;       for (int j = 0; j < 4; ++j) {
;         const float kk = kkr[j] * rn;
;         const float kp = kx[j] * (1.f + (as4[j] - 1.f) * ka4[j]);
;         fA[j] = -kk; fWR[j] = de4[j] * r[j]; fB[j] = kk * as4[j]; fK[j] = kp;
;         br += rbf(fB[j]) * r[j];
;         kr += rbf(fK[j]) * r[j];
;         rks += r[j] * kp * rk4[j];
;       }
;       br = red16(br); kr = red16(kr); rks = red16(rks);
;       *(float4*)(RWW + (size_t)row * 512 + ch4) = dec;
;       bf16_t* d5 = RW5 + (size_t)row * 5 * 512 + ch4;
;       *(uint2*)(d5) = make_uint2(pack2(fA[0], fA[1]), pack2(fA[2], fA[3]));
;       *(uint2*)(d5 + 512) = make_uint2(pack2(fWR[0], fWR[1]), pack2(fWR[2], fWR[3]));
;       *(uint2*)(d5 + 1024) = make_uint2(pack2(fB[0], fB[1]), pack2(fB[2], fB[3]));
;       *(uint2*)(d5 + 1536) = make_uint2(pack2(fK[0], fK[1]), pack2(fK[2], fK[3]));
;       *(uint2*)(d5 + 2048) = make_uint2(pack2(v[0], v[1]), pack2(v[2], v[3]));
;       if ((chunk & 15) == 0) *(float4*)(RWSC + ((size_t)row * 8 + head) * 4) = make_float4(br, kr, rks, 0.f);
	v_mov_b32_e32 v36, v50
	v_mov_b32_e32 v37, v52
	v_pk_fma_f32 v[28:29], v[34:35], v[68:69], v[28:29] op_sel_hi:[0,1,1]
	global_store_dwordx4 v[80:81], v[50:53], off
	v_pk_mul_f32 v[36:37], v[32:33], v[36:37]
	v_pk_fma_f32 v[28:29], v[32:33], v[76:77], v[28:29] op_sel:[1,0,0]
	v_mov_b32_e32 v52, v51
	v_pk_mul_f32 v[50:51], v[34:35], v[52:53]
	v_pk_fma_f32 v[28:29], v[34:35], v[78:79], v[28:29] op_sel:[1,0,0]
	v_add_f32_dpp v34, v38, v38 quad_perm:[1,0,3,2] row_mask:0xf bank_mask:0xf bound_ctrl:1
	v_and_b32_sdwa v38, v37, v183 dst_sel:DWORD dst_unused:UNUSED_PAD src0_sel:WORD_1 src1_sel:DWORD
	v_and_b32_sdwa v39, v36, v183 dst_sel:DWORD dst_unused:UNUSED_PAD src0_sel:WORD_1 src1_sel:DWORD
	v_add3_u32 v36, v36, v39, s37
	v_add3_u32 v37, v37, v38, s37
	v_and_b32_sdwa v38, v51, v183 dst_sel:DWORD dst_unused:UNUSED_PAD src0_sel:WORD_1 src1_sel:DWORD
	v_and_b32_sdwa v39, v50, v183 dst_sel:DWORD dst_unused:UNUSED_PAD src0_sel:WORD_1 src1_sel:DWORD
	v_add3_u32 v38, v51, v38, s37
	v_add3_u32 v39, v50, v39, s37
	s_movk_i32 s0, 0x1400
	v_and_b32_e32 v38, 0xffff0000, v38
	v_and_b32_e32 v39, 0xffff0000, v39
	v_mad_i64_i32 v[80:81], s[16:17], v4, s0, v[40:41]
	v_or_b32_sdwa v37, v38, v37 dst_sel:DWORD dst_unused:UNUSED_PAD src0_sel:DWORD src1_sel:WORD_1
	v_or_b32_sdwa v36, v39, v36 dst_sel:DWORD dst_unused:UNUSED_PAD src0_sel:DWORD src1_sel:WORD_1
	global_store_dwordx2 v[80:81], v[36:37], off offset:1024
	v_or_b32_sdwa v37, v78, v56 dst_sel:DWORD dst_unused:UNUSED_PAD src0_sel:DWORD src1_sel:WORD_1
	v_or_b32_sdwa v36, v68, v59 dst_sel:DWORD dst_unused:UNUSED_PAD src0_sel:DWORD src1_sel:WORD_1
	v_pk_add_f32 v[20:21], v[20:21], v[70:71] neg_lo:[0,1] neg_hi:[0,1]
	v_mov_b32_dpp v32, v28 quad_perm:[1,0,3,2] row_mask:0xf bank_mask:0xf bound_ctrl:1
	v_mov_b32_dpp v33, v29 quad_perm:[1,0,3,2] row_mask:0xf bank_mask:0xf bound_ctrl:1
	global_store_dwordx2 v[80:81], v[36:37], off offset:2048
	v_or_b32_sdwa v37, v79, v74 dst_sel:DWORD dst_unused:UNUSED_PAD src0_sel:DWORD src1_sel:WORD_1
	v_or_b32_sdwa v36, v69, v49 dst_sel:DWORD dst_unused:UNUSED_PAD src0_sel:DWORD src1_sel:WORD_1
	v_pk_fma_f32 v[20:21], v[12:13], v[20:21], v[70:71]
	v_pk_add_f32 v[30:31], v[30:31], v[72:73] neg_lo:[0,1] neg_hi:[0,1]
	v_pk_add_f32 v[28:29], v[28:29], v[32:33]
	global_store_dwordx2 v[80:81], v[36:37], off offset:3072
	v_pk_fma_f32 v[30:31], v[6:7], v[30:31], v[72:73]
	v_and_b32_sdwa v37, v20, v183 dst_sel:DWORD dst_unused:UNUSED_PAD src0_sel:WORD_1 src1_sel:DWORD
	v_mov_b32_dpp v32, v28 quad_perm:[2,3,0,1] row_mask:0xf bank_mask:0xf bound_ctrl:1
	v_mov_b32_dpp v33, v29 quad_perm:[2,3,0,1] row_mask:0xf bank_mask:0xf bound_ctrl:1
	v_and_b32_sdwa v36, v21, v183 dst_sel:DWORD dst_unused:UNUSED_PAD src0_sel:WORD_1 src1_sel:DWORD
	v_add3_u32 v20, v20, v37, s37
	v_and_b32_sdwa v37, v30, v183 dst_sel:DWORD dst_unused:UNUSED_PAD src0_sel:WORD_1 src1_sel:DWORD
	v_pk_add_f32 v[28:29], v[28:29], v[32:33]
	v_add3_u32 v21, v21, v36, s37
	v_and_b32_sdwa v36, v31, v183 dst_sel:DWORD dst_unused:UNUSED_PAD src0_sel:WORD_1 src1_sel:DWORD
	v_add3_u32 v30, v30, v37, s37
	v_mov_b32_dpp v32, v28 row_half_mirror row_mask:0xf bank_mask:0xf bound_ctrl:1
	v_mov_b32_dpp v33, v29 row_half_mirror row_mask:0xf bank_mask:0xf bound_ctrl:1
	v_add_f32_dpp v34, v34, v34 quad_perm:[2,3,0,1] row_mask:0xf bank_mask:0xf bound_ctrl:1
	v_add3_u32 v31, v31, v36, s37
	v_and_b32_e32 v30, 0xffff0000, v30
	v_pk_add_f32 v[28:29], v[28:29], v[32:33]
	v_add_f32_dpp v34, v34, v34 row_half_mirror row_mask:0xf bank_mask:0xf bound_ctrl:1
	v_and_b32_e32 v31, 0xffff0000, v31
	v_or_b32_sdwa v20, v30, v20 dst_sel:DWORD dst_unused:UNUSED_PAD src0_sel:DWORD src1_sel:WORD_1
	v_add_co_u32_e32 v30, vcc, 0x1000, v80
	v_mov_b32_dpp v32, v28 row_mirror row_mask:0xf bank_mask:0xf bound_ctrl:1
	v_mov_b32_dpp v33, v29 row_mirror row_mask:0xf bank_mask:0xf bound_ctrl:1
	v_mov_b32_dpp v35, v34 row_mirror row_mask:0xf bank_mask:0xf bound_ctrl:1
	v_or_b32_sdwa v21, v31, v21 dst_sel:DWORD dst_unused:UNUSED_PAD src0_sel:DWORD src1_sel:WORD_1
	v_addc_co_u32_e32 v31, vcc, 0, v81, vcc
	global_store_dwordx2 v[80:81], v[62:63], off
	global_store_dwordx2 v[30:31], v[20:21], off
	s_and_saveexec_b64 s[16:17], s[40:41]
	s_cbranch_execz .LBB0_484
	v_lshlrev_b64 v[4:5], 7, v[4:5]
	v_lshl_add_u64 v[4:5], v[0:1], 0, v[4:5]
	v_add_f32_e32 v30, v34, v35
	v_pk_add_f32 v[28:29], v[28:29], v[32:33]
	v_mov_b32_e32 v31, v3
	global_store_dwordx4 v[4:5], v[28:31], off
.LBB0_484:
	s_or_b64 exec, exec, s[16:17]
	v_add_u32_e32 v59, 4, v60
	v_add_u32_e32 v4, s23, v59
	s_movk_i32 s0, 0x407f
	v_cmp_lt_i32_e32 vcc, s0, v4
	s_and_saveexec_b64 s[16:17], vcc
	s_xor_b64 s[16:17], exec, s[16:17]
	v_add_u32_e32 v5, 0xffffbf88, v4
	s_or_saveexec_b64 s[16:17], s[16:17]
	s_mov_b64 s[38:39], 0
	s_xor_b64 exec, exec, s[16:17]
	s_mov_b32 s0, 0xfe03f81
	v_mul_hi_i32 v5, v4, s0
	v_lshrrev_b32_e32 v20, 31, v5
	v_ashrrev_i32_e32 v5, 7, v5
	v_add_u32_e32 v5, v5, v20
	s_movk_i32 s0, 0xf7f0
	v_mad_i32_i24 v20, v5, s0, v4
	v_cmp_lt_i32_e32 vcc, 0, v20
	s_and_b64 s[38:39], vcc, exec
	s_or_b64 exec, exec, s[16:17]
	v_mov_b64_e32 v[20:21], s[2:3]
	s_movk_i32 s0, 0x2200
	v_mad_i64_i32 v[20:21], s[16:17], v4, s0, v[20:21]
	v_lshl_add_u64 v[20:21], v[20:21], 0, v[2:3]
	v_mov_b32_e32 v54, v100
	v_mov_b32_e32 v55, v101
	v_mov_b32_e32 v52, v102
	v_mov_b32_e32 v53, v103
	v_mov_b32_e32 v50, v104
	v_mov_b32_e32 v51, v105
	s_xor_b64 s[16:17], s[38:39], -1
	s_and_saveexec_b64 s[26:27], s[16:17]
	s_xor_b64 s[16:17], exec, s[26:27]
	s_cbranch_execz .LBB0_492
	v_cmp_lt_i32_e32 vcc, 7, v5
	v_mov_b32_e32 v39, 0
	v_mov_b32_e32 v57, 0
	v_mov_b32_e32 v38, 0
	v_mov_b32_e32 v56, 0
	v_mov_b32_e32 v21, 0
	v_mov_b32_e32 v20, 0
	v_mov_b32_e32 v31, 0
	v_mov_b32_e32 v30, 0
	v_mov_b32_e32 v37, 0
	v_mov_b32_e32 v36, 0
	v_mov_b32_e32 v35, 0
	v_mov_b32_e32 v34, 0
	s_and_saveexec_b64 s[38:39], vcc
	s_cbranch_execz .LBB0_491
	v_add_u32_e32 v5, -8, v5
	v_mov_b64_e32 v[20:21], s[28:29]
	s_movk_i32 s0, 0x1a00
	v_mad_u64_u32 v[20:21], s[26:27], v5, s0, v[20:21]
	v_mov_b32_e32 v49, v3
	v_lshl_add_u64 v[20:21], v[20:21], 0, v[48:49]
	global_load_dwordx4 v[32:35], v[20:21], off
	global_load_dwordx4 v[36:39], v[20:21], off offset:2048
	v_add_co_u32_e32 v20, vcc, 0x1000, v20
	s_waitcnt vmcnt(0)
	v_mov_b32_e32 v57, v38
	v_addc_co_u32_e32 v21, vcc, 0, v21, vcc
	global_load_dwordx4 v[28:31], v[20:21], off
	v_mov_b32_e32 v38, v37
	v_mov_b32_e32 v56, v36
	v_mov_b32_e32 v37, v34
	v_mov_b32_e32 v36, v32
	v_mov_b32_e32 v34, v33
	s_waitcnt vmcnt(0)
	v_mov_b32_e32 v21, v30
	v_mov_b32_e32 v20, v28
	v_mov_b32_e32 v30, v29

; __device__ __forceinline__ float bflo(unsigned u) { return __uint_as_float(u << 16); }
; __device__ __forceinline__ float bfhi(unsigned u) { return __uint_as_float(u & 0xffff0000u); }
; __device__ __forceinline__ void prep_rwkv(const Params& p, int l, int item, char* smem) {
;     ...
;       if (t > 0) {
;         const uint2 a_ = *(const uint2*)(PRE + (size_t)(row - 1) * PRE_W + ch4);
;         const uint2 b_ = *(const uint2*)(PRE + (size_t)(row - 1) * PRE_W + 512 + ch4);
;         const uint2 c_ = *(const uint2*)(PRE + (size_t)(row - 1) * PRE_W + 1024 + ch4);
;         qr = make_float4(bflo(a_.x), bfhi(a_.x), bflo(a_.y), bfhi(a_.y));
;         qk = make_float4(bflo(b_.x), bfhi(b_.x), bflo(b_.y), bfhi(b_.y));
;         qv = make_float4(bflo(c_.x), bfhi(c_.x), bflo(c_.y), bfhi(c_.y));
.LBB0_492:
	s_andn2_saveexec_b64 s[16:17], s[16:17]
	s_cbranch_execz .LBB0_494
	v_add_u32_e32 v5, -1, v4
	v_mov_b64_e32 v[20:21], s[2:3]
	s_movk_i32 s0, 0x2200
	v_mad_i64_i32 v[20:21], s[26:27], v5, s0, v[20:21]
	v_lshl_add_u64 v[20:21], v[20:21], 0, v[2:3]
	v_mov_b32_e32 v28, v152
	v_mov_b32_e32 v29, v153
	v_mov_b32_e32 v30, v148
	v_mov_b32_e32 v31, v149
	s_nop 0
	v_mov_b32_e32 v20, v150
	v_mov_b32_e32 v21, v151
	v_lshlrev_b32_e32 v36, 16, v30
	v_lshlrev_b32_e32 v37, 16, v31
	v_and_b32_e32 v35, 0xffff0000, v31
	v_and_b32_e32 v34, 0xffff0000, v30
	v_lshlrev_b32_e32 v56, 16, v20
	v_and_b32_e32 v38, 0xffff0000, v20
	v_lshlrev_b32_e32 v57, 16, v21
	v_and_b32_e32 v39, 0xffff0000, v21
	v_lshlrev_b32_e32 v20, 16, v28
	v_lshlrev_b32_e32 v21, 16, v29
	v_and_b32_e32 v31, 0xffff0000, v29
	v_and_b32_e32 v30, 0xffff0000, v28

; __device__ __forceinline__ float bflo(unsigned u) { return __uint_as_float(u << 16); }
; __device__ __forceinline__ float bfhi(unsigned u) { return __uint_as_float(u & 0xffff0000u); }
; __device__ __forceinline__ void prep_rwkv(const Params& p, int l, int item, char* smem) {
;     ...
;       const int tok = (tid >> 7) + 2 * i;
;       const int row = row0 + tok;
;       int seq, t; row_to_seq(row, seq, t);
;       const uint2 pr_ = *(const uint2*)(PRE + (size_t)row * PRE_W + ch4);
;       const uint2 pk_ = *(const uint2*)(PRE + (size_t)row * PRE_W + 512 + ch4);
;       const uint2 pv_ = *(const uint2*)(PRE + (size_t)row * PRE_W + 1024 + ch4);
;       float4 qr, qk, qv;
;       if (t > 0) {
;         const uint2 a_ = *(const uint2*)(PRE + (size_t)(row - 1) * PRE_W + ch4);
;         const uint2 b_ = *(const uint2*)(PRE + (size_t)(row - 1) * PRE_W + 512 + ch4);
;         const uint2 c_ = *(const uint2*)(PRE + (size_t)(row - 1) * PRE_W + 1024 + ch4);
;         qr = make_float4(bflo(a_.x), bfhi(a_.x), bflo(a_.y), bfhi(a_.y));
;         qk = make_float4(bflo(b_.x), bfhi(b_.x), bflo(b_.y), bfhi(b_.y));
;         qv = make_float4(bflo(c_.x), bfhi(c_.x), bflo(c_.y), bfhi(c_.y));
;       } else if (seq >= 8) {
;         const float* sh = shift_in + (size_t)(seq - 8) * 1664;
;         qr = *(const float4*)(sh + ch4); qk = *(const float4*)(sh + 512 + ch4); qv = *(const float4*)(sh + 1024 + ch4);
;       } else {
;         qr = qk = qv = make_float4(0.f, 0.f, 0.f, 0.f);
.LBB0_496:
	s_or_b64 exec, exec, s[16:17]
	v_add_u32_e32 v59, 6, v60
	v_add_u32_e32 v4, s23, v59
	s_movk_i32 s0, 0x407f
	v_cmp_lt_i32_e32 vcc, s0, v4
	s_and_saveexec_b64 s[16:17], vcc
	s_xor_b64 s[16:17], exec, s[16:17]
	v_add_u32_e32 v5, 0xffffbf88, v4
	s_or_saveexec_b64 s[16:17], s[16:17]
	s_mov_b64 s[38:39], 0
	s_xor_b64 exec, exec, s[16:17]
	s_mov_b32 s0, 0xfe03f81
	v_mul_hi_i32 v5, v4, s0
	v_lshrrev_b32_e32 v20, 31, v5
	v_ashrrev_i32_e32 v5, 7, v5
	v_add_u32_e32 v5, v5, v20
	s_movk_i32 s0, 0xf7f0
	v_mad_i32_i24 v20, v5, s0, v4
	v_cmp_lt_i32_e32 vcc, 0, v20
	s_and_b64 s[38:39], vcc, exec
	s_or_b64 exec, exec, s[16:17]
	v_mov_b64_e32 v[20:21], s[2:3]
	s_movk_i32 s0, 0x2200
	v_mad_i64_i32 v[20:21], s[16:17], v4, s0, v[20:21]
	v_lshl_add_u64 v[20:21], v[20:21], 0, v[2:3]
	v_mov_b32_e32 v54, v106
	v_mov_b32_e32 v55, v107
	v_mov_b32_e32 v52, v108
	v_mov_b32_e32 v53, v109
	v_mov_b32_e32 v50, v110
	v_mov_b32_e32 v51, v111
	s_xor_b64 s[16:17], s[38:39], -1
	s_and_saveexec_b64 s[26:27], s[16:17]
	s_xor_b64 s[16:17], exec, s[26:27]
	s_cbranch_execz .LBB0_504
	v_cmp_lt_i32_e32 vcc, 7, v5
	v_mov_b32_e32 v39, 0
	v_mov_b32_e32 v57, 0
	v_mov_b32_e32 v38, 0
	v_mov_b32_e32 v56, 0
	v_mov_b32_e32 v21, 0
	v_mov_b32_e32 v20, 0
	v_mov_b32_e32 v31, 0
	v_mov_b32_e32 v30, 0
	v_mov_b32_e32 v37, 0
	v_mov_b32_e32 v36, 0
	v_mov_b32_e32 v35, 0
	v_mov_b32_e32 v34, 0
	s_and_saveexec_b64 s[38:39], vcc
	s_cbranch_execz .LBB0_503
	v_add_u32_e32 v5, -8, v5
	v_mov_b64_e32 v[20:21], s[28:29]
	s_movk_i32 s0, 0x1a00
	v_mad_u64_u32 v[20:21], s[26:27], v5, s0, v[20:21]
	v_mov_b32_e32 v49, v3
	v_lshl_add_u64 v[20:21], v[20:21], 0, v[48:49]
	global_load_dwordx4 v[32:35], v[20:21], off
	global_load_dwordx4 v[36:39], v[20:21], off offset:2048
	v_add_co_u32_e32 v20, vcc, 0x1000, v20
	s_waitcnt vmcnt(0)
	v_mov_b32_e32 v57, v38
	v_addc_co_u32_e32 v21, vcc, 0, v21, vcc
	global_load_dwordx4 v[28:31], v[20:21], off
	v_mov_b32_e32 v38, v37
	v_mov_b32_e32 v56, v36
	v_mov_b32_e32 v37, v34
	v_mov_b32_e32 v36, v32
	v_mov_b32_e32 v34, v33
	s_waitcnt vmcnt(0)
	v_mov_b32_e32 v21, v30
	v_mov_b32_e32 v20, v28
	v_mov_b32_e32 v30, v29

; __device__ __forceinline__ float bflo(unsigned u) { return __uint_as_float(u << 16); }
; __device__ __forceinline__ float bfhi(unsigned u) { return __uint_as_float(u & 0xffff0000u); }
; __device__ __forceinline__ void prep_rwkv(const Params& p, int l, int item, char* smem) {
;     ...
;       if (t > 0) {
;         const uint2 a_ = *(const uint2*)(PRE + (size_t)(row - 1) * PRE_W + ch4);
;         const uint2 b_ = *(const uint2*)(PRE + (size_t)(row - 1) * PRE_W + 512 + ch4);
;         const uint2 c_ = *(const uint2*)(PRE + (size_t)(row - 1) * PRE_W + 1024 + ch4);
;         qr = make_float4(bflo(a_.x), bfhi(a_.x), bflo(a_.y), bfhi(a_.y));
;         qk = make_float4(bflo(b_.x), bfhi(b_.x), bflo(b_.y), bfhi(b_.y));
;         qv = make_float4(bflo(c_.x), bfhi(c_.x), bflo(c_.y), bfhi(c_.y));
.LBB0_504:
	s_andn2_saveexec_b64 s[16:17], s[16:17]
	s_cbranch_execz .LBB0_506
	v_add_u32_e32 v5, -1, v4
	v_mov_b64_e32 v[20:21], s[2:3]
	s_movk_i32 s0, 0x2200
	v_mad_i64_i32 v[20:21], s[26:27], v5, s0, v[20:21]
	v_lshl_add_u64 v[20:21], v[20:21], 0, v[2:3]
	v_mov_b32_e32 v28, v158
	v_mov_b32_e32 v29, v159
	v_mov_b32_e32 v30, v154
	v_mov_b32_e32 v31, v155
	s_nop 0
	v_mov_b32_e32 v20, v156
	v_mov_b32_e32 v21, v157
	v_lshlrev_b32_e32 v36, 16, v30
	v_lshlrev_b32_e32 v37, 16, v31
	v_and_b32_e32 v35, 0xffff0000, v31
	v_and_b32_e32 v34, 0xffff0000, v30
	v_lshlrev_b32_e32 v56, 16, v20
	v_and_b32_e32 v38, 0xffff0000, v20
	v_lshlrev_b32_e32 v57, 16, v21
	v_and_b32_e32 v39, 0xffff0000, v21
	v_lshlrev_b32_e32 v20, 16, v28
	v_lshlrev_b32_e32 v21, 16, v29
	v_and_b32_e32 v31, 0xffff0000, v29
	v_and_b32_e32 v30, 0xffff0000, v28

; __device__ __forceinline__ float bflo(unsigned u) { return __uint_as_float(u << 16); }
; __device__ __forceinline__ float bfhi(unsigned u) { return __uint_as_float(u & 0xffff0000u); }
; __device__ __forceinline__ void prep_rwkv(const Params& p, int l, int item, char* smem) {
;     ...
;       const int tok = (tid >> 7) + 2 * i;
;       const int row = row0 + tok;
;       int seq, t; row_to_seq(row, seq, t);
;       const uint2 pr_ = *(const uint2*)(PRE + (size_t)row * PRE_W + ch4);
;       const uint2 pk_ = *(const uint2*)(PRE + (size_t)row * PRE_W + 512 + ch4);
;       const uint2 pv_ = *(const uint2*)(PRE + (size_t)row * PRE_W + 1024 + ch4);
;       float4 qr, qk, qv;
;       if (t > 0) {
;         const uint2 a_ = *(const uint2*)(PRE + (size_t)(row - 1) * PRE_W + ch4);
;         const uint2 b_ = *(const uint2*)(PRE + (size_t)(row - 1) * PRE_W + 512 + ch4);
;         const uint2 c_ = *(const uint2*)(PRE + (size_t)(row - 1) * PRE_W + 1024 + ch4);
;         qr = make_float4(bflo(a_.x), bfhi(a_.x), bflo(a_.y), bfhi(a_.y));
;         qk = make_float4(bflo(b_.x), bfhi(b_.x), bflo(b_.y), bfhi(b_.y));
;         qv = make_float4(bflo(c_.x), bfhi(c_.x), bflo(c_.y), bfhi(c_.y));
;       } else if (seq >= 8) {
;         const float* sh = shift_in + (size_t)(seq - 8) * 1664;
;         qr = *(const float4*)(sh + ch4); qk = *(const float4*)(sh + 512 + ch4); qv = *(const float4*)(sh + 1024 + ch4);
;       } else {
;         qr = qk = qv = make_float4(0.f, 0.f, 0.f, 0.f);
.LBB0_508:
	s_or_b64 exec, exec, s[16:17]
	v_add_u32_e32 v59, 8, v60
	v_add_u32_e32 v4, s23, v59
	s_movk_i32 s0, 0x407f
	v_cmp_lt_i32_e32 vcc, s0, v4
	s_and_saveexec_b64 s[16:17], vcc
	s_xor_b64 s[16:17], exec, s[16:17]
	v_add_u32_e32 v5, 0xffffbf88, v4
	s_or_saveexec_b64 s[16:17], s[16:17]
	s_mov_b64 s[38:39], 0
	s_xor_b64 exec, exec, s[16:17]
	s_mov_b32 s0, 0xfe03f81
	v_mul_hi_i32 v5, v4, s0
	v_lshrrev_b32_e32 v20, 31, v5
	v_ashrrev_i32_e32 v5, 7, v5
	v_add_u32_e32 v5, v5, v20
	s_movk_i32 s0, 0xf7f0
	v_mad_i32_i24 v20, v5, s0, v4
	v_cmp_lt_i32_e32 vcc, 0, v20
	s_and_b64 s[38:39], vcc, exec
	s_or_b64 exec, exec, s[16:17]
	v_mov_b64_e32 v[20:21], s[2:3]
	s_movk_i32 s0, 0x2200
	v_mad_i64_i32 v[20:21], s[16:17], v4, s0, v[20:21]
	v_lshl_add_u64 v[20:21], v[20:21], 0, v[2:3]
	v_mov_b32_e32 v54, v112
	v_mov_b32_e32 v55, v113
	v_mov_b32_e32 v52, v114
	v_mov_b32_e32 v53, v115
	v_mov_b32_e32 v50, v116
	v_mov_b32_e32 v51, v117
	s_xor_b64 s[16:17], s[38:39], -1
	s_and_saveexec_b64 s[26:27], s[16:17]
	s_xor_b64 s[16:17], exec, s[26:27]
	s_cbranch_execz .LBB0_516
	v_cmp_lt_i32_e32 vcc, 7, v5
	v_mov_b32_e32 v39, 0
	v_mov_b32_e32 v57, 0
	v_mov_b32_e32 v38, 0
	v_mov_b32_e32 v56, 0
	v_mov_b32_e32 v21, 0
	v_mov_b32_e32 v20, 0
	v_mov_b32_e32 v31, 0
	v_mov_b32_e32 v30, 0
	v_mov_b32_e32 v37, 0
	v_mov_b32_e32 v36, 0
	v_mov_b32_e32 v35, 0
	v_mov_b32_e32 v34, 0
	s_and_saveexec_b64 s[38:39], vcc
	s_cbranch_execz .LBB0_515
	v_add_u32_e32 v5, -8, v5
	v_mov_b64_e32 v[20:21], s[28:29]
	s_movk_i32 s0, 0x1a00
	v_mad_u64_u32 v[20:21], s[26:27], v5, s0, v[20:21]
	v_mov_b32_e32 v49, v3
	v_lshl_add_u64 v[20:21], v[20:21], 0, v[48:49]
	global_load_dwordx4 v[32:35], v[20:21], off
	global_load_dwordx4 v[36:39], v[20:21], off offset:2048
	v_add_co_u32_e32 v20, vcc, 0x1000, v20
	s_waitcnt vmcnt(0)
	v_mov_b32_e32 v57, v38
	v_addc_co_u32_e32 v21, vcc, 0, v21, vcc
	global_load_dwordx4 v[28:31], v[20:21], off
	v_mov_b32_e32 v38, v37
	v_mov_b32_e32 v56, v36
	v_mov_b32_e32 v37, v34
	v_mov_b32_e32 v36, v32
	v_mov_b32_e32 v34, v33
	s_waitcnt vmcnt(0)
	v_mov_b32_e32 v21, v30
	v_mov_b32_e32 v20, v28
	v_mov_b32_e32 v30, v29

; __device__ __forceinline__ float bflo(unsigned u) { return __uint_as_float(u << 16); }
; __device__ __forceinline__ float bfhi(unsigned u) { return __uint_as_float(u & 0xffff0000u); }
; __device__ __forceinline__ void prep_rwkv(const Params& p, int l, int item, char* smem) {
;     ...
;       if (t > 0) {
;         const uint2 a_ = *(const uint2*)(PRE + (size_t)(row - 1) * PRE_W + ch4);
;         const uint2 b_ = *(const uint2*)(PRE + (size_t)(row - 1) * PRE_W + 512 + ch4);
;         const uint2 c_ = *(const uint2*)(PRE + (size_t)(row - 1) * PRE_W + 1024 + ch4);
;         qr = make_float4(bflo(a_.x), bfhi(a_.x), bflo(a_.y), bfhi(a_.y));
;         qk = make_float4(bflo(b_.x), bfhi(b_.x), bflo(b_.y), bfhi(b_.y));
;         qv = make_float4(bflo(c_.x), bfhi(c_.x), bflo(c_.y), bfhi(c_.y));
.LBB0_516:
	s_andn2_saveexec_b64 s[16:17], s[16:17]
	s_cbranch_execz .LBB0_518
	v_add_u32_e32 v5, -1, v4
	v_mov_b64_e32 v[20:21], s[2:3]
	s_movk_i32 s0, 0x2200
	v_mad_i64_i32 v[20:21], s[26:27], v5, s0, v[20:21]
	v_lshl_add_u64 v[20:21], v[20:21], 0, v[2:3]
	v_mov_b32_e32 v28, v164
	v_mov_b32_e32 v29, v165
	v_mov_b32_e32 v30, v160
	v_mov_b32_e32 v31, v161
	s_nop 0
	v_mov_b32_e32 v20, v162
	v_mov_b32_e32 v21, v163
	v_lshlrev_b32_e32 v36, 16, v30
	v_lshlrev_b32_e32 v37, 16, v31
	v_and_b32_e32 v35, 0xffff0000, v31
	v_and_b32_e32 v34, 0xffff0000, v30
	v_lshlrev_b32_e32 v56, 16, v20
	v_and_b32_e32 v38, 0xffff0000, v20
	v_lshlrev_b32_e32 v57, 16, v21
	v_and_b32_e32 v39, 0xffff0000, v21
	v_lshlrev_b32_e32 v20, 16, v28
	v_lshlrev_b32_e32 v21, 16, v29
	v_and_b32_e32 v31, 0xffff0000, v29
	v_and_b32_e32 v30, 0xffff0000, v28

; __device__ __forceinline__ float bflo(unsigned u) { return __uint_as_float(u << 16); }
; __device__ __forceinline__ float bfhi(unsigned u) { return __uint_as_float(u & 0xffff0000u); }
; __device__ __forceinline__ void prep_rwkv(const Params& p, int l, int item, char* smem) {
;     ...
;       const int tok = (tid >> 7) + 2 * i;
;       const int row = row0 + tok;
;       int seq, t; row_to_seq(row, seq, t);
;       const uint2 pr_ = *(const uint2*)(PRE + (size_t)row * PRE_W + ch4);
;       const uint2 pk_ = *(const uint2*)(PRE + (size_t)row * PRE_W + 512 + ch4);
;       const uint2 pv_ = *(const uint2*)(PRE + (size_t)row * PRE_W + 1024 + ch4);
;       float4 qr, qk, qv;
;       if (t > 0) {
;         const uint2 a_ = *(const uint2*)(PRE + (size_t)(row - 1) * PRE_W + ch4);
;         const uint2 b_ = *(const uint2*)(PRE + (size_t)(row - 1) * PRE_W + 512 + ch4);
;         const uint2 c_ = *(const uint2*)(PRE + (size_t)(row - 1) * PRE_W + 1024 + ch4);
;         qr = make_float4(bflo(a_.x), bfhi(a_.x), bflo(a_.y), bfhi(a_.y));
;         qk = make_float4(bflo(b_.x), bfhi(b_.x), bflo(b_.y), bfhi(b_.y));
;         qv = make_float4(bflo(c_.x), bfhi(c_.x), bflo(c_.y), bfhi(c_.y));
;       } else if (seq >= 8) {
;         const float* sh = shift_in + (size_t)(seq - 8) * 1664;
;         qr = *(const float4*)(sh + ch4); qk = *(const float4*)(sh + 512 + ch4); qv = *(const float4*)(sh + 1024 + ch4);
;       } else {
;         qr = qk = qv = make_float4(0.f, 0.f, 0.f, 0.f);
.LBB0_520:
	s_or_b64 exec, exec, s[16:17]
	v_add_u32_e32 v59, 10, v60
	v_add_u32_e32 v4, s23, v59
	s_movk_i32 s0, 0x407f
	v_cmp_lt_i32_e32 vcc, s0, v4
	s_and_saveexec_b64 s[16:17], vcc
	s_xor_b64 s[16:17], exec, s[16:17]
	v_add_u32_e32 v5, 0xffffbf88, v4
	s_or_saveexec_b64 s[16:17], s[16:17]
	s_mov_b64 s[38:39], 0
	s_xor_b64 exec, exec, s[16:17]
	s_mov_b32 s0, 0xfe03f81
	v_mul_hi_i32 v5, v4, s0
	v_lshrrev_b32_e32 v20, 31, v5
	v_ashrrev_i32_e32 v5, 7, v5
	v_add_u32_e32 v5, v5, v20
	s_movk_i32 s0, 0xf7f0
	v_mad_i32_i24 v20, v5, s0, v4
	v_cmp_lt_i32_e32 vcc, 0, v20
	s_and_b64 s[38:39], vcc, exec
	s_or_b64 exec, exec, s[16:17]
	v_mov_b64_e32 v[20:21], s[2:3]
	s_movk_i32 s0, 0x2200
	v_mad_i64_i32 v[20:21], s[16:17], v4, s0, v[20:21]
	v_lshl_add_u64 v[20:21], v[20:21], 0, v[2:3]
	v_mov_b32_e32 v54, v118
	v_mov_b32_e32 v55, v119
	v_mov_b32_e32 v52, v120
	v_mov_b32_e32 v53, v121
	v_mov_b32_e32 v50, v122
	v_mov_b32_e32 v51, v123
	s_xor_b64 s[16:17], s[38:39], -1
	s_and_saveexec_b64 s[26:27], s[16:17]
	s_xor_b64 s[16:17], exec, s[26:27]
	s_cbranch_execz .LBB0_528
	v_cmp_lt_i32_e32 vcc, 7, v5
	v_mov_b32_e32 v39, 0
	v_mov_b32_e32 v57, 0
	v_mov_b32_e32 v38, 0
	v_mov_b32_e32 v56, 0
	v_mov_b32_e32 v21, 0
	v_mov_b32_e32 v20, 0
	v_mov_b32_e32 v31, 0
	v_mov_b32_e32 v30, 0
	v_mov_b32_e32 v37, 0
	v_mov_b32_e32 v36, 0
	v_mov_b32_e32 v35, 0
	v_mov_b32_e32 v34, 0
	s_and_saveexec_b64 s[38:39], vcc
	s_cbranch_execz .LBB0_527
	v_add_u32_e32 v5, -8, v5
	v_mov_b64_e32 v[20:21], s[28:29]
	s_movk_i32 s0, 0x1a00
	v_mad_u64_u32 v[20:21], s[26:27], v5, s0, v[20:21]
	v_mov_b32_e32 v49, v3
	v_lshl_add_u64 v[20:21], v[20:21], 0, v[48:49]
	global_load_dwordx4 v[32:35], v[20:21], off
	global_load_dwordx4 v[36:39], v[20:21], off offset:2048
	v_add_co_u32_e32 v20, vcc, 0x1000, v20
	s_waitcnt vmcnt(0)
	v_mov_b32_e32 v57, v38
	v_addc_co_u32_e32 v21, vcc, 0, v21, vcc
	global_load_dwordx4 v[28:31], v[20:21], off
	v_mov_b32_e32 v38, v37
	v_mov_b32_e32 v56, v36
	v_mov_b32_e32 v37, v34
	v_mov_b32_e32 v36, v32
	v_mov_b32_e32 v34, v33
	s_waitcnt vmcnt(0)
	v_mov_b32_e32 v21, v30
	v_mov_b32_e32 v20, v28
	v_mov_b32_e32 v30, v29

; __device__ __forceinline__ float bflo(unsigned u) { return __uint_as_float(u << 16); }
; __device__ __forceinline__ float bfhi(unsigned u) { return __uint_as_float(u & 0xffff0000u); }
; __device__ __forceinline__ void prep_rwkv(const Params& p, int l, int item, char* smem) {
;     ...
;       if (t > 0) {
;         const uint2 a_ = *(const uint2*)(PRE + (size_t)(row - 1) * PRE_W + ch4);
;         const uint2 b_ = *(const uint2*)(PRE + (size_t)(row - 1) * PRE_W + 512 + ch4);
;         const uint2 c_ = *(const uint2*)(PRE + (size_t)(row - 1) * PRE_W + 1024 + ch4);
;         qr = make_float4(bflo(a_.x), bfhi(a_.x), bflo(a_.y), bfhi(a_.y));
;         qk = make_float4(bflo(b_.x), bfhi(b_.x), bflo(b_.y), bfhi(b_.y));
;         qv = make_float4(bflo(c_.x), bfhi(c_.x), bflo(c_.y), bfhi(c_.y));
.LBB0_528:
	s_andn2_saveexec_b64 s[16:17], s[16:17]
	s_cbranch_execz .LBB0_530
	v_add_u32_e32 v5, -1, v4
	v_mov_b64_e32 v[20:21], s[2:3]
	s_movk_i32 s0, 0x2200
	v_mad_i64_i32 v[20:21], s[26:27], v5, s0, v[20:21]
	v_lshl_add_u64 v[20:21], v[20:21], 0, v[2:3]
	v_mov_b32_e32 v28, v170
	v_mov_b32_e32 v29, v171
	v_mov_b32_e32 v30, v166
	v_mov_b32_e32 v31, v167
	s_nop 0
	v_mov_b32_e32 v20, v168
	v_mov_b32_e32 v21, v169
	v_lshlrev_b32_e32 v36, 16, v30
	v_lshlrev_b32_e32 v37, 16, v31
	v_and_b32_e32 v35, 0xffff0000, v31
	v_and_b32_e32 v34, 0xffff0000, v30
	v_lshlrev_b32_e32 v56, 16, v20
	v_and_b32_e32 v38, 0xffff0000, v20
	v_lshlrev_b32_e32 v57, 16, v21
	v_and_b32_e32 v39, 0xffff0000, v21
	v_lshlrev_b32_e32 v20, 16, v28
	v_lshlrev_b32_e32 v21, 16, v29
	v_and_b32_e32 v31, 0xffff0000, v29
	v_and_b32_e32 v30, 0xffff0000, v28

; __device__ __forceinline__ float bflo(unsigned u) { return __uint_as_float(u << 16); }
; __device__ __forceinline__ float bfhi(unsigned u) { return __uint_as_float(u & 0xffff0000u); }
; __device__ __forceinline__ void prep_rwkv(const Params& p, int l, int item, char* smem) {
;     ...
;       const int tok = (tid >> 7) + 2 * i;
;       const int row = row0 + tok;
;       int seq, t; row_to_seq(row, seq, t);
;       const uint2 pr_ = *(const uint2*)(PRE + (size_t)row * PRE_W + ch4);
;       const uint2 pk_ = *(const uint2*)(PRE + (size_t)row * PRE_W + 512 + ch4);
;       const uint2 pv_ = *(const uint2*)(PRE + (size_t)row * PRE_W + 1024 + ch4);
;       float4 qr, qk, qv;
;       if (t > 0) {
;         const uint2 a_ = *(const uint2*)(PRE + (size_t)(row - 1) * PRE_W + ch4);
;         const uint2 b_ = *(const uint2*)(PRE + (size_t)(row - 1) * PRE_W + 512 + ch4);
;         const uint2 c_ = *(const uint2*)(PRE + (size_t)(row - 1) * PRE_W + 1024 + ch4);
;         qr = make_float4(bflo(a_.x), bfhi(a_.x), bflo(a_.y), bfhi(a_.y));
;         qk = make_float4(bflo(b_.x), bfhi(b_.x), bflo(b_.y), bfhi(b_.y));
;         qv = make_float4(bflo(c_.x), bfhi(c_.x), bflo(c_.y), bfhi(c_.y));
;       } else if (seq >= 8) {
;         const float* sh = shift_in + (size_t)(seq - 8) * 1664;
;         qr = *(const float4*)(sh + ch4); qk = *(const float4*)(sh + 512 + ch4); qv = *(const float4*)(sh + 1024 + ch4);
;       } else {
;         qr = qk = qv = make_float4(0.f, 0.f, 0.f, 0.f);
.LBB0_532:
	s_or_b64 exec, exec, s[16:17]
	v_add_u32_e32 v59, 12, v60
	v_add_u32_e32 v4, s23, v59
	s_movk_i32 s0, 0x407f
	v_cmp_lt_i32_e32 vcc, s0, v4
	s_and_saveexec_b64 s[16:17], vcc
	s_xor_b64 s[16:17], exec, s[16:17]
	v_add_u32_e32 v5, 0xffffbf88, v4
	s_or_saveexec_b64 s[16:17], s[16:17]
	s_mov_b64 s[38:39], 0
	s_xor_b64 exec, exec, s[16:17]
	s_mov_b32 s0, 0xfe03f81
	v_mul_hi_i32 v5, v4, s0
	v_lshrrev_b32_e32 v20, 31, v5
	v_ashrrev_i32_e32 v5, 7, v5
	v_add_u32_e32 v5, v5, v20
	s_movk_i32 s0, 0xf7f0
	v_mad_i32_i24 v20, v5, s0, v4
	v_cmp_lt_i32_e32 vcc, 0, v20
	s_and_b64 s[38:39], vcc, exec
	s_or_b64 exec, exec, s[16:17]
	v_mov_b64_e32 v[20:21], s[2:3]
	s_movk_i32 s0, 0x2200
	v_mad_i64_i32 v[20:21], s[16:17], v4, s0, v[20:21]
	v_lshl_add_u64 v[20:21], v[20:21], 0, v[2:3]
	v_mov_b32_e32 v54, v124
	v_mov_b32_e32 v55, v125
	v_mov_b32_e32 v52, v126
	v_mov_b32_e32 v53, v127
	v_mov_b32_e32 v50, v128
	v_mov_b32_e32 v51, v129
	s_xor_b64 s[16:17], s[38:39], -1
	s_and_saveexec_b64 s[26:27], s[16:17]
	s_xor_b64 s[16:17], exec, s[26:27]
	s_cbranch_execz .LBB0_540
	v_cmp_lt_i32_e32 vcc, 7, v5
	v_mov_b32_e32 v39, 0
	v_mov_b32_e32 v57, 0
	v_mov_b32_e32 v38, 0
	v_mov_b32_e32 v56, 0
	v_mov_b32_e32 v21, 0
	v_mov_b32_e32 v20, 0
	v_mov_b32_e32 v31, 0
	v_mov_b32_e32 v30, 0
	v_mov_b32_e32 v37, 0
	v_mov_b32_e32 v36, 0
	v_mov_b32_e32 v35, 0
	v_mov_b32_e32 v34, 0
	s_and_saveexec_b64 s[38:39], vcc
	s_cbranch_execz .LBB0_539
	v_add_u32_e32 v5, -8, v5
	v_mov_b64_e32 v[20:21], s[28:29]
	s_movk_i32 s0, 0x1a00
	v_mad_u64_u32 v[20:21], s[26:27], v5, s0, v[20:21]
	v_mov_b32_e32 v49, v3
	v_lshl_add_u64 v[20:21], v[20:21], 0, v[48:49]
	global_load_dwordx4 v[32:35], v[20:21], off
	global_load_dwordx4 v[36:39], v[20:21], off offset:2048
	v_add_co_u32_e32 v20, vcc, 0x1000, v20
	s_waitcnt vmcnt(0)
	v_mov_b32_e32 v57, v38
	v_addc_co_u32_e32 v21, vcc, 0, v21, vcc
	global_load_dwordx4 v[28:31], v[20:21], off
	v_mov_b32_e32 v38, v37
	v_mov_b32_e32 v56, v36
	v_mov_b32_e32 v37, v34
	v_mov_b32_e32 v36, v32
	v_mov_b32_e32 v34, v33
	s_waitcnt vmcnt(0)
	v_mov_b32_e32 v21, v30
	v_mov_b32_e32 v20, v28
	v_mov_b32_e32 v30, v29

; __device__ __forceinline__ float bflo(unsigned u) { return __uint_as_float(u << 16); }
; __device__ __forceinline__ float bfhi(unsigned u) { return __uint_as_float(u & 0xffff0000u); }
; __device__ __forceinline__ void prep_rwkv(const Params& p, int l, int item, char* smem) {
;     ...
;       if (t > 0) {
;         const uint2 a_ = *(const uint2*)(PRE + (size_t)(row - 1) * PRE_W + ch4);
;         const uint2 b_ = *(const uint2*)(PRE + (size_t)(row - 1) * PRE_W + 512 + ch4);
;         const uint2 c_ = *(const uint2*)(PRE + (size_t)(row - 1) * PRE_W + 1024 + ch4);
;         qr = make_float4(bflo(a_.x), bfhi(a_.x), bflo(a_.y), bfhi(a_.y));
;         qk = make_float4(bflo(b_.x), bfhi(b_.x), bflo(b_.y), bfhi(b_.y));
;         qv = make_float4(bflo(c_.x), bfhi(c_.x), bflo(c_.y), bfhi(c_.y));
.LBB0_540:
	s_andn2_saveexec_b64 s[16:17], s[16:17]
	s_cbranch_execz .LBB0_542
	v_add_u32_e32 v5, -1, v4
	v_mov_b64_e32 v[20:21], s[2:3]
	s_movk_i32 s0, 0x2200
	v_mad_i64_i32 v[20:21], s[26:27], v5, s0, v[20:21]
	v_lshl_add_u64 v[20:21], v[20:21], 0, v[2:3]
	v_mov_b32_e32 v28, v176
	v_mov_b32_e32 v29, v177
	v_mov_b32_e32 v30, v172
	v_mov_b32_e32 v31, v173
	s_nop 0
	v_mov_b32_e32 v20, v174
	v_mov_b32_e32 v21, v175
	v_lshlrev_b32_e32 v36, 16, v30
	v_lshlrev_b32_e32 v37, 16, v31
	v_and_b32_e32 v35, 0xffff0000, v31
	v_and_b32_e32 v34, 0xffff0000, v30
	v_lshlrev_b32_e32 v56, 16, v20
	v_and_b32_e32 v38, 0xffff0000, v20
	v_lshlrev_b32_e32 v57, 16, v21
	v_and_b32_e32 v39, 0xffff0000, v21
	v_lshlrev_b32_e32 v20, 16, v28
	v_lshlrev_b32_e32 v21, 16, v29
	v_and_b32_e32 v31, 0xffff0000, v29
	v_and_b32_e32 v30, 0xffff0000, v28

; __device__ __forceinline__ float bflo(unsigned u) { return __uint_as_float(u << 16); }
; __device__ __forceinline__ float bfhi(unsigned u) { return __uint_as_float(u & 0xffff0000u); }
; __device__ __forceinline__ void prep_rwkv(const Params& p, int l, int item, char* smem) {
;     ...
;       const int tok = (tid >> 7) + 2 * i;
;       const int row = row0 + tok;
;       int seq, t; row_to_seq(row, seq, t);
;       const uint2 pr_ = *(const uint2*)(PRE + (size_t)row * PRE_W + ch4);
;       const uint2 pk_ = *(const uint2*)(PRE + (size_t)row * PRE_W + 512 + ch4);
;       const uint2 pv_ = *(const uint2*)(PRE + (size_t)row * PRE_W + 1024 + ch4);
;       float4 qr, qk, qv;
;       if (t > 0) {
;         const uint2 a_ = *(const uint2*)(PRE + (size_t)(row - 1) * PRE_W + ch4);
;         const uint2 b_ = *(const uint2*)(PRE + (size_t)(row - 1) * PRE_W + 512 + ch4);
;         const uint2 c_ = *(const uint2*)(PRE + (size_t)(row - 1) * PRE_W + 1024 + ch4);
;         qr = make_float4(bflo(a_.x), bfhi(a_.x), bflo(a_.y), bfhi(a_.y));
;         qk = make_float4(bflo(b_.x), bfhi(b_.x), bflo(b_.y), bfhi(b_.y));
;         qv = make_float4(bflo(c_.x), bfhi(c_.x), bflo(c_.y), bfhi(c_.y));
;       } else if (seq >= 8) {
;         const float* sh = shift_in + (size_t)(seq - 8) * 1664;
;         qr = *(const float4*)(sh + ch4); qk = *(const float4*)(sh + 512 + ch4); qv = *(const float4*)(sh + 1024 + ch4);
;       } else {
;         qr = qk = qv = make_float4(0.f, 0.f, 0.f, 0.f);
.LBB0_544:
	s_or_b64 exec, exec, s[16:17]
	v_add_u32_e32 v59, 14, v60
	v_add_u32_e32 v4, s23, v59
	s_movk_i32 s0, 0x407f
	v_cmp_lt_i32_e32 vcc, s0, v4
	s_and_saveexec_b64 s[16:17], vcc
	s_xor_b64 s[16:17], exec, s[16:17]
	v_add_u32_e32 v5, 0xffffbf88, v4
	s_or_saveexec_b64 s[16:17], s[16:17]
	s_mov_b64 s[38:39], 0
	s_xor_b64 exec, exec, s[16:17]
	s_mov_b32 s0, 0xfe03f81
	v_mul_hi_i32 v5, v4, s0
	v_lshrrev_b32_e32 v20, 31, v5
	v_ashrrev_i32_e32 v5, 7, v5
	v_add_u32_e32 v5, v5, v20
	s_movk_i32 s0, 0xf7f0
	v_mad_i32_i24 v20, v5, s0, v4
	v_cmp_lt_i32_e32 vcc, 0, v20
	s_and_b64 s[38:39], vcc, exec
	s_or_b64 exec, exec, s[16:17]
	v_mov_b64_e32 v[20:21], s[2:3]
	s_movk_i32 s0, 0x2200
	v_mad_i64_i32 v[20:21], s[16:17], v4, s0, v[20:21]
	v_lshl_add_u64 v[20:21], v[20:21], 0, v[2:3]
	v_mov_b32_e32 v56, v130
	v_mov_b32_e32 v57, v131
	v_mov_b32_e32 v54, v132
	v_mov_b32_e32 v55, v133
	v_mov_b32_e32 v52, v134
	v_mov_b32_e32 v53, v135
	s_xor_b64 s[16:17], s[38:39], -1
	s_and_saveexec_b64 s[26:27], s[16:17]
	s_xor_b64 s[16:17], exec, s[26:27]
	s_cbranch_execz .LBB0_552
	v_cmp_lt_i32_e32 vcc, 7, v5
	v_mov_b32_e32 v39, 0
	v_mov_b32_e32 v51, 0
	v_mov_b32_e32 v38, 0
	v_mov_b32_e32 v50, 0
	v_mov_b32_e32 v21, 0
	v_mov_b32_e32 v20, 0
	v_mov_b32_e32 v31, 0
	v_mov_b32_e32 v30, 0
	v_mov_b32_e32 v37, 0
	v_mov_b32_e32 v36, 0
	v_mov_b32_e32 v35, 0
	v_mov_b32_e32 v34, 0
	s_and_saveexec_b64 s[38:39], vcc
	s_cbranch_execz .LBB0_551
	v_add_u32_e32 v2, -8, v5
	v_mov_b64_e32 v[20:21], s[28:29]
	s_movk_i32 s0, 0x1a00
	v_mad_u64_u32 v[20:21], s[26:27], v2, s0, v[20:21]
	v_mov_b32_e32 v49, v3
	v_lshl_add_u64 v[20:21], v[20:21], 0, v[48:49]
	global_load_dwordx4 v[32:35], v[20:21], off
	global_load_dwordx4 v[36:39], v[20:21], off offset:2048
	v_add_co_u32_e32 v20, vcc, 0x1000, v20
	s_waitcnt vmcnt(0)
	v_mov_b32_e32 v51, v38
	v_addc_co_u32_e32 v21, vcc, 0, v21, vcc
	global_load_dwordx4 v[28:31], v[20:21], off
	v_mov_b32_e32 v38, v37
	v_mov_b32_e32 v50, v36
	v_mov_b32_e32 v37, v34
	v_mov_b32_e32 v36, v32
	v_mov_b32_e32 v34, v33
	s_waitcnt vmcnt(0)
	v_mov_b32_e32 v21, v30
	v_mov_b32_e32 v20, v28
	v_mov_b32_e32 v30, v29

; __device__ __forceinline__ void prep_rwkv(const Params& p, int l, int item, char* smem) {
;     ...
;       if (t > 0) {
;         const uint2 a_ = *(const uint2*)(PRE + (size_t)(row - 1) * PRE_W + ch4);
;         const uint2 b_ = *(const uint2*)(PRE + (size_t)(row - 1) * PRE_W + 512 + ch4);
;         const uint2 c_ = *(const uint2*)(PRE + (size_t)(row - 1) * PRE_W + 1024 + ch4);
;         qr = make_float4(bflo(a_.x), bfhi(a_.x), bflo(a_.y), bfhi(a_.y));
;         qk = make_float4(bflo(b_.x), bfhi(b_.x), bflo(b_.y), bfhi(b_.y));
;         qv = make_float4(bflo(c_.x), bfhi(c_.x), bflo(c_.y), bfhi(c_.y));
;       } else if (seq >= 8) {
;         const float* sh = shift_in + (size_t)(seq - 8) * 1664;
;         qr = *(const float4*)(sh + ch4); qk = *(const float4*)(sh + 512 + ch4); qv = *(const float4*)(sh + 1024 + ch4);
;       } else {
;         qr = qk = qv = make_float4(0.f, 0.f, 0.f, 0.f);
;       }
;       const float4 dec = *(const float4*)(sW + tok * 516 + ch4);
;       const float4 as = *(const float4*)(sAs + tok * 516 + ch4);
;       const float pr4[4] = {bflo(pr_.x), bfhi(pr_.x), bflo(pr_.y), bfhi(pr_.y)};
;       const float pk4[4] = {bflo(pk_.x), bfhi(pk_.x), bflo(pk_.y), bfhi(pk_.y)};
;       const float pv4[4] = {bflo(pv_.x), bfhi(pv_.x), bflo(pv_.y), bfhi(pv_.y)};
;       const float qr4[4] = {qr.x, qr.y, qr.z, qr.w}, qk4[4] = {qk.x, qk.y, qk.z, qk.w}, qv4[4] = {qv.x, qv.y, qv.z, qv.w};
;       const float mr4[4] = {mur.x, mur.y, mur.z, mur.w}, mk4[4] = {muk.x, muk.y, muk.z, muk.w}, mv4[4] = {muv.x, muv.y, muv.z, muv.w};
;       const float kk4[4] = {kkc.x, kkc.y, kkc.z, kkc.w}, ka4[4] = {kac.x, kac.y, kac.z, kac.w}, rk4[4] = {rkc.x, rkc.y, rkc.z, rkc.w};
;       const float de4[4] = {dec.x, dec.y, dec.z, dec.w}, as4[4] = {as.x, as.y, as.z, as.w};
;       float r[4], kx[4], v[4], kkr[4];
;       float ssq = 0.f;
; #pragma unroll
;       for (int j = 0; j < 4; ++j) {
;         r[j] = pr4[j] + (qr4[j] - pr4[j]) * mr4[j];
;         kx[j] = pk4[j] + (qk4[j] - pk4[j]) * mk4[j];
;         v[j] = pv4[j] + (qv4[j] - pv4[j]) * mv4[j];
;         kkr[j] = kx[j] * kk4[j];
;         ssq += kkr[j] * kkr[j];
;       }
;       ssq = red16(ssq);
;       const float rn = rsqrtf(ssq + 1e-6f);
;       float fA[4], fWR[4], fB[4], fK[4];
;       float br = 0.f, kr = 0.f, rks = 0.f;
; #pragma unroll
;       for (int j = 0; j < 4; ++j) {
;         const float kk = kkr[j] * rn;
.LBB0_552:
	s_andn2_saveexec_b64 s[16:17], s[16:17]
	s_cbranch_execz .LBB0_554
	v_add_u32_e32 v5, -1, v4
	v_mov_b64_e32 v[20:21], s[2:3]
	s_movk_i32 s0, 0x2200
	v_mad_i64_i32 v[20:21], s[26:27], v5, s0, v[20:21]
	v_lshl_add_u64 v[20:21], v[20:21], 0, v[2:3]
	v_mov_b32_e32 v28, v202
	v_mov_b32_e32 v29, v203
	v_mov_b32_e32 v30, v198
	v_mov_b32_e32 v31, v199
	s_nop 0
	v_mov_b32_e32 v20, v200
	v_mov_b32_e32 v21, v201
	v_lshlrev_b32_e32 v36, 16, v30
	v_lshlrev_b32_e32 v37, 16, v31
	v_and_b32_e32 v35, 0xffff0000, v31
	v_and_b32_e32 v34, 0xffff0000, v30
	v_lshlrev_b32_e32 v50, 16, v20
	v_and_b32_e32 v38, 0xffff0000, v20
	v_lshlrev_b32_e32 v51, 16, v21
	v_and_b32_e32 v39, 0xffff0000, v21
	v_lshlrev_b32_e32 v20, 16, v28
	v_lshlrev_b32_e32 v21, 16, v29
	v_and_b32_e32 v31, 0xffff0000, v29
	v_and_b32_e32 v30, 0xffff0000, v28
.LBB0_554:
	s_or_b64 exec, exec, s[16:17]
	s_movk_i32 s0, 0x810
	v_mad_u64_u32 v[48:49], s[16:17], v59, s0, v[48:49]
	ds_read_b128 v[60:63], v48 offset:37376
	v_ashrrev_i32_e32 v5, 31, v4
	v_lshlrev_b32_e32 v33, 16, v53
	v_and_b32_e32 v29, 0xffff0000, v53
	v_lshlrev_b32_e32 v67, 16, v55
	s_waitcnt lgkmcnt(0)
	v_add_f32_e32 v2, -1.0, v60
	v_fma_f32 v49, v24, v2, 1.0
	v_add_f32_e32 v2, -1.0, v61
	v_fma_f32 v53, v25, v2, 1.0
	v_add_f32_e32 v2, -1.0, v62
	v_fma_f32 v69, v26, v2, 1.0
	v_add_f32_e32 v2, -1.0, v63
	v_lshlrev_b64 v[24:25], 11, v[4:5]
	v_fma_f32 v71, v27, v2, 1.0
	v_lshl_add_u64 v[42:43], v[42:43], 0, v[24:25]
	ds_read_b128 v[24:27], v48 offset:4352
	v_lshlrev_b32_e32 v66, 16, v54
	v_and_b32_e32 v55, 0xffff0000, v55
	v_and_b32_e32 v54, 0xffff0000, v54
	v_pk_add_f32 v[38:39], v[38:39], v[54:55] neg_lo:[0,1] neg_hi:[0,1]
	s_waitcnt lgkmcnt(0)
	global_store_dwordx4 v[42:43], v[24:27], off
	v_pk_add_f32 v[42:43], v[50:51], v[66:67] neg_lo:[0,1] neg_hi:[0,1]
	v_pk_fma_f32 v[18:19], v[18:19], v[38:39], v[54:55]
	v_pk_fma_f32 v[42:43], v[44:45], v[42:43], v[66:67]
	v_pk_mul_f32 v[22:23], v[22:23], v[18:19]
	v_pk_mul_f32 v[44:45], v[46:47], v[42:43]
	v_mov_b32_e32 v39, v22
	v_mov_b32_e32 v38, v44
	v_pk_mul_f32 v[38:39], v[38:39], v[38:39]
	v_mov_b32_e32 v46, v45
	v_mov_b32_e32 v47, v23
	v_pk_mul_f32 v[46:47], v[46:47], v[46:47]
	v_add_f32_e32 v2, v38, v39
	v_add_f32_e32 v2, v2, v46
	v_add_f32_e32 v2, v2, v47
	v_mov_b32_e32 v48, v60
	v_mov_b32_e32 v47, v42
	v_add_f32_dpp v2, v2, v2 quad_perm:[1,0,3,2] row_mask:0xf bank_mask:0xf bound_ctrl:1
	v_lshlrev_b32_e32 v32, 16, v52
	v_and_b32_e32 v28, 0xffff0000, v52
	v_add_f32_dpp v2, v2, v2 quad_perm:[2,3,0,1] row_mask:0xf bank_mask:0xf bound_ctrl:1
	v_mov_b32_e32 v52, v61
	v_mov_b32_e32 v51, v18
	v_add_f32_dpp v2, v2, v2 row_half_mirror row_mask:0xf bank_mask:0xf bound_ctrl:1
	v_mov_b32_e32 v68, v62
	v_mov_b32_e32 v70, v63
	v_add_f32_dpp v2, v2, v2 row_mirror row_mask:0xf bank_mask:0xf bound_ctrl:1
	v_add_f32_e32 v2, 0x358637bd, v2
	v_cmp_gt_f32_e32 vcc, s72, v2
	v_mul_f32_e32 v38, 0x4b800000, v2
	s_movk_i32 s0, 0x1400
	v_cndmask_b32_e32 v2, v2, v38, vcc
	v_rsq_f32_e32 v2, v2
	v_lshlrev_b32_e32 v65, 16, v57
	v_lshlrev_b32_e32 v64, 16, v56
	v_mad_i64_i32 v[40:41], s[16:17], v4, s0, v[40:41]
	v_mul_f32_e32 v38, 0x45800000, v2
	v_cndmask_b32_e32 v2, v2, v38, vcc
	v_pk_mul_f32 v[38:39], v[44:45], v[2:3] op_sel_hi:[1,0] neg_lo:[0,1] neg_hi:[0,1]
	v_pk_mul_f32 v[22:23], v[22:23], v[2:3] op_sel_hi:[1,0] neg_lo:[0,1] neg_hi:[0,1]
	v_pk_add_f32 v[44:45], v[38:39], 0 neg_lo:[1,1] neg_hi:[1,1]
	v_and_b32_e32 v57, 0xffff0000, v57
	v_mov_b32_e32 v46, v44
	v_pk_mul_f32 v[46:47], v[48:49], v[46:47]
	v_pk_add_f32 v[48:49], v[22:23], 0 neg_lo:[1,1] neg_hi:[1,1]
	v_and_b32_sdwa v42, v47, v183 dst_sel:DWORD dst_unused:UNUSED_PAD src0_sel:WORD_1 src1_sel:DWORD
	v_mov_b32_e32 v50, v48
	v_pk_mul_f32 v[50:51], v[52:53], v[50:51]
	v_add3_u32 v59, v47, v42, s37
	v_and_b32_sdwa v2, v51, v183 dst_sel:DWORD dst_unused:UNUSED_PAD src0_sel:WORD_1 src1_sel:DWORD
	v_mov_b32_e32 v42, v45
	v_and_b32_sdwa v48, v50, v183 dst_sel:DWORD dst_unused:UNUSED_PAD src0_sel:WORD_1 src1_sel:DWORD
	v_pk_mul_f32 v[42:43], v[68:69], v[42:43]
	v_mov_b32_e32 v18, v49
	v_add3_u32 v2, v51, v2, s37
	v_pk_mul_f32 v[18:19], v[70:71], v[18:19]
	v_add3_u32 v48, v50, v48, s37
	v_and_b32_e32 v49, 0xffff0000, v2
	v_and_b32_sdwa v2, v43, v183 dst_sel:DWORD dst_unused:UNUSED_PAD src0_sel:WORD_1 src1_sel:DWORD
	v_and_b32_sdwa v50, v42, v183 dst_sel:DWORD dst_unused:UNUSED_PAD src0_sel:WORD_1 src1_sel:DWORD
	v_add3_u32 v60, v43, v2, s37
	v_add3_u32 v42, v42, v50, s37
	v_and_b32_sdwa v2, v19, v183 dst_sel:DWORD dst_unused:UNUSED_PAD src0_sel:WORD_1 src1_sel:DWORD
	v_and_b32_sdwa v50, v18, v183 dst_sel:DWORD dst_unused:UNUSED_PAD src0_sel:WORD_1 src1_sel:DWORD
	v_add3_u32 v2, v19, v2, s37
	v_add3_u32 v18, v18, v50, s37
	v_and_b32_e32 v55, 0xffff0000, v2
	v_and_b32_e32 v54, 0xffff0000, v18
	v_and_b32_sdwa v2, v39, v183 dst_sel:DWORD dst_unused:UNUSED_PAD src0_sel:WORD_1 src1_sel:DWORD
	v_and_b32_sdwa v18, v38, v183 dst_sel:DWORD dst_unused:UNUSED_PAD src0_sel:WORD_1 src1_sel:DWORD
	v_add3_u32 v18, v38, v18, s37
	v_add3_u32 v2, v39, v2, s37
	v_and_b32_sdwa v38, v23, v183 dst_sel:DWORD dst_unused:UNUSED_PAD src0_sel:WORD_1 src1_sel:DWORD
	v_and_b32_sdwa v39, v22, v183 dst_sel:DWORD dst_unused:UNUSED_PAD src0_sel:WORD_1 src1_sel:DWORD
	v_add3_u32 v23, v23, v38, s37
	v_add3_u32 v22, v22, v39, s37
; __device__ __forceinline__ unsigned pack2(float a, float b) { return (unsigned)f2bf(a) | ((unsigned)f2bf(b) << 16); }
; __device__ __forceinline__ float rbf(float f) { return bf2f(f2bf(f)); }
; __device__ __forceinline__ float red16(float v) { v = red8(v); v += dppf<0x140>(v); return v; }
; __device__ __forceinline__ void prep_rwkv(const Params& p, int l, int item, char* smem) {
;     ...
;       float fA[4], fWR[4], fB[4], fK[4];
;       float br = 0.f, kr = 0.f, rks = 0.f;
; #pragma unroll
;       for (int j = 0; j < 4; ++j) {
;         const float kk = kkr[j] * rn;
;         const float kp = kx[j] * (1.f + (as4[j] - 1.f) * ka4[j]);
;         fA[j] = -kk; fWR[j] = de4[j] * r[j]; fB[j] = kk * as4[j]; fK[j] = kp;
;         br += rbf(fB[j]) * r[j];
;         kr += rbf(fK[j]) * r[j];
;         rks += r[j] * kp * rk4[j];
;       }
;       br = red16(br); kr = red16(kr); rks = red16(rks);
;       *(float4*)(RWW + (size_t)row * 512 + ch4) = dec;
;       bf16_t* d5 = RW5 + (size_t)row * 5 * 512 + ch4;
;       *(uint2*)(d5) = make_uint2(pack2(fA[0], fA[1]), pack2(fA[2], fA[3]));
;       *(uint2*)(d5 + 512) = make_uint2(pack2(fWR[0], fWR[1]), pack2(fWR[2], fWR[3]));
;       *(uint2*)(d5 + 1024) = make_uint2(pack2(fB[0], fB[1]), pack2(fB[2], fB[3]));
;       *(uint2*)(d5 + 1536) = make_uint2(pack2(fK[0], fK[1]), pack2(fK[2], fK[3]));
;       *(uint2*)(d5 + 2048) = make_uint2(pack2(v[0], v[1]), pack2(v[2], v[3]));
;       if ((chunk & 15) == 0) *(float4*)(RWSC + ((size_t)row * 8 + head) * 4) = make_float4(br, kr, rks, 0.f);
;     }
;   }
;   if (row0 >= NTP) {
	v_and_b32_e32 v23, 0xffff0000, v23
	v_and_b32_e32 v22, 0xffff0000, v22
	v_or_b32_sdwa v23, v23, v2 dst_sel:DWORD dst_unused:UNUSED_PAD src0_sel:DWORD src1_sel:WORD_1
	v_or_b32_sdwa v22, v22, v18 dst_sel:DWORD dst_unused:UNUSED_PAD src0_sel:DWORD src1_sel:WORD_1
	v_and_b32_e32 v56, 0xffff0000, v56
	global_store_dwordx2 v[40:41], v[22:23], off
	v_pk_add_f32 v[22:23], v[36:37], v[64:65] neg_lo:[0,1] neg_hi:[0,1]
	v_and_b32_sdwa v44, v46, v183 dst_sel:DWORD dst_unused:UNUSED_PAD src0_sel:WORD_1 src1_sel:DWORD
	v_pk_fma_f32 v[16:17], v[16:17], v[22:23], v[64:65]
	v_pk_add_f32 v[22:23], v[34:35], v[56:57] neg_lo:[0,1] neg_hi:[0,1]
	v_mul_f32_e32 v2, v16, v47
	v_pk_fma_f32 v[14:15], v[14:15], v[22:23], v[56:57]
	v_fma_f32 v2, v8, v2, 0
	v_mul_f32_e32 v8, v14, v51
	v_add3_u32 v46, v46, v44, s37
	v_fmac_f32_e32 v2, v9, v8
	v_mul_f32_e32 v8, v17, v43
	v_and_b32_e32 v45, 0xffff0000, v59
	v_and_b32_e32 v44, 0xffff0000, v46
	v_fmac_f32_e32 v2, v10, v8
	v_mul_f32_e32 v8, v15, v19
	v_and_b32_e32 v48, 0xffff0000, v48
	v_mov_b32_e32 v23, v26
	v_mov_b32_e32 v26, v25
	v_fmac_f32_e32 v2, v11, v8
	v_pk_fma_f32 v[8:9], v[16:17], v[44:45], 0 op_sel_hi:[0,1,0]
	v_and_b32_e32 v53, 0xffff0000, v60
	v_and_b32_e32 v52, 0xffff0000, v42
	v_mov_b32_e32 v22, v24
	v_pk_mul_f32 v[24:25], v[14:15], v[26:27]
	v_pk_fma_f32 v[8:9], v[14:15], v[48:49], v[8:9] op_sel_hi:[0,1,1]
	v_pk_mul_f32 v[22:23], v[16:17], v[22:23]
	v_pk_fma_f32 v[8:9], v[16:17], v[52:53], v[8:9] op_sel:[1,0,0]
	v_and_b32_sdwa v17, v25, v183 dst_sel:DWORD dst_unused:UNUSED_PAD src0_sel:WORD_1 src1_sel:DWORD
	v_and_b32_sdwa v18, v24, v183 dst_sel:DWORD dst_unused:UNUSED_PAD src0_sel:WORD_1 src1_sel:DWORD
	v_pk_fma_f32 v[8:9], v[14:15], v[54:55], v[8:9] op_sel:[1,0,0]
	v_and_b32_sdwa v15, v23, v183 dst_sel:DWORD dst_unused:UNUSED_PAD src0_sel:WORD_1 src1_sel:DWORD
	v_and_b32_sdwa v16, v22, v183 dst_sel:DWORD dst_unused:UNUSED_PAD src0_sel:WORD_1 src1_sel:DWORD
	v_add3_u32 v17, v25, v17, s37
	v_add3_u32 v18, v24, v18, s37
	v_add3_u32 v16, v22, v16, s37
	v_add3_u32 v15, v23, v15, s37
	v_and_b32_e32 v17, 0xffff0000, v17
	v_and_b32_e32 v18, 0xffff0000, v18
	v_or_b32_sdwa v17, v17, v15 dst_sel:DWORD dst_unused:UNUSED_PAD src0_sel:DWORD src1_sel:WORD_1
	v_or_b32_sdwa v16, v18, v16 dst_sel:DWORD dst_unused:UNUSED_PAD src0_sel:DWORD src1_sel:WORD_1
	global_store_dwordx2 v[40:41], v[16:17], off offset:1024
	v_or_b32_sdwa v17, v54, v42 dst_sel:DWORD dst_unused:UNUSED_PAD src0_sel:DWORD src1_sel:WORD_1
	v_or_b32_sdwa v16, v48, v46 dst_sel:DWORD dst_unused:UNUSED_PAD src0_sel:DWORD src1_sel:WORD_1
	global_store_dwordx2 v[40:41], v[16:17], off offset:2048
	v_or_b32_sdwa v17, v55, v60 dst_sel:DWORD dst_unused:UNUSED_PAD src0_sel:DWORD src1_sel:WORD_1
	v_or_b32_sdwa v16, v49, v59 dst_sel:DWORD dst_unused:UNUSED_PAD src0_sel:DWORD src1_sel:WORD_1
	global_store_dwordx2 v[40:41], v[16:17], off offset:3072
	v_pk_add_f32 v[16:17], v[20:21], v[32:33] neg_lo:[0,1] neg_hi:[0,1]
	v_mov_b32_dpp v10, v8 quad_perm:[1,0,3,2] row_mask:0xf bank_mask:0xf bound_ctrl:1
	v_mov_b32_dpp v11, v9 quad_perm:[1,0,3,2] row_mask:0xf bank_mask:0xf bound_ctrl:1
	v_pk_fma_f32 v[12:13], v[12:13], v[16:17], v[32:33]
	v_pk_add_f32 v[16:17], v[30:31], v[28:29] neg_lo:[0,1] neg_hi:[0,1]
	v_pk_add_f32 v[8:9], v[8:9], v[10:11]
	v_pk_fma_f32 v[6:7], v[6:7], v[16:17], v[28:29]
	v_and_b32_sdwa v16, v12, v183 dst_sel:DWORD dst_unused:UNUSED_PAD src0_sel:WORD_1 src1_sel:DWORD
	v_mov_b32_dpp v10, v8 quad_perm:[2,3,0,1] row_mask:0xf bank_mask:0xf bound_ctrl:1
	v_mov_b32_dpp v11, v9 quad_perm:[2,3,0,1] row_mask:0xf bank_mask:0xf bound_ctrl:1
	v_and_b32_sdwa v15, v13, v183 dst_sel:DWORD dst_unused:UNUSED_PAD src0_sel:WORD_1 src1_sel:DWORD
	v_add3_u32 v12, v12, v16, s37
	v_and_b32_sdwa v16, v6, v183 dst_sel:DWORD dst_unused:UNUSED_PAD src0_sel:WORD_1 src1_sel:DWORD
	v_pk_add_f32 v[8:9], v[8:9], v[10:11]
	v_add_f32_dpp v2, v2, v2 quad_perm:[1,0,3,2] row_mask:0xf bank_mask:0xf bound_ctrl:1
	v_add3_u32 v13, v13, v15, s37
	v_and_b32_sdwa v15, v7, v183 dst_sel:DWORD dst_unused:UNUSED_PAD src0_sel:WORD_1 src1_sel:DWORD
	v_add3_u32 v6, v6, v16, s37
	v_mov_b32_dpp v10, v8 row_half_mirror row_mask:0xf bank_mask:0xf bound_ctrl:1
	v_mov_b32_dpp v11, v9 row_half_mirror row_mask:0xf bank_mask:0xf bound_ctrl:1
	v_add_f32_dpp v2, v2, v2 quad_perm:[2,3,0,1] row_mask:0xf bank_mask:0xf bound_ctrl:1
	v_add3_u32 v7, v7, v15, s37
	v_and_b32_e32 v6, 0xffff0000, v6
	v_pk_add_f32 v[8:9], v[8:9], v[10:11]
	v_add_f32_dpp v2, v2, v2 row_half_mirror row_mask:0xf bank_mask:0xf bound_ctrl:1
	v_and_b32_e32 v7, 0xffff0000, v7
	v_or_b32_sdwa v6, v6, v12 dst_sel:DWORD dst_unused:UNUSED_PAD src0_sel:DWORD src1_sel:WORD_1
	v_add_co_u32_e32 v12, vcc, 0x1000, v40
	v_mov_b32_dpp v10, v8 row_mirror row_mask:0xf bank_mask:0xf bound_ctrl:1
	v_mov_b32_dpp v11, v9 row_mirror row_mask:0xf bank_mask:0xf bound_ctrl:1
	v_mov_b32_dpp v14, v2 row_mirror row_mask:0xf bank_mask:0xf bound_ctrl:1
	v_or_b32_sdwa v7, v7, v13 dst_sel:DWORD dst_unused:UNUSED_PAD src0_sel:DWORD src1_sel:WORD_1
	v_addc_co_u32_e32 v13, vcc, 0, v41, vcc
	global_store_dwordx2 v[12:13], v[6:7], off
	s_and_saveexec_b64 s[16:17], s[40:41]
	s_cbranch_execnz .LBB0_557
	s_or_b64 exec, exec, s[16:17]
	s_cmpk_lt_i32 s85, 0x408
	s_mov_b64 s[16:17], -1
	s_cbranch_scc1 .LBB0_558
